# v71 + agent-scope write-through (sc1) on all 16-byte global stores outside the scan
# baseline (speedup 1.0000x reference)
.LBB0_56:
	s_or_b64 exec, exec, s[0:1]
	s_waitcnt vmcnt(31)
	v_cndmask_b32_e64 v2, 0, v2, s[66:67]
	s_waitcnt vmcnt(30)
	v_cndmask_b32_e64 v1, 0, v1, s[66:67]
	v_add_u32_e32 v47, 0x2000, v57
	s_waitcnt vmcnt(29)
	v_cndmask_b32_e64 v32, 0, v32, s[66:67]
	s_waitcnt vmcnt(28)
	v_cndmask_b32_e64 v3, 0, v3, s[66:67]
	s_waitcnt vmcnt(27)
	v_cndmask_b32_e64 v4, 0, v4, s[66:67]
	s_waitcnt vmcnt(26)
	v_cndmask_b32_e64 v5, 0, v5, s[66:67]
	ds_write2_b32 v47, v2, v1 offset0:32 offset1:97
	ds_write2_b32 v47, v32, v3 offset0:162 offset1:227
	v_add_u32_e32 v1, 0x2400, v57
	s_waitcnt vmcnt(25)
	v_cndmask_b32_e64 v6, 0, v6, s[66:67]
	s_waitcnt vmcnt(24)
	v_cndmask_b32_e64 v7, 0, v7, s[66:67]
	s_waitcnt vmcnt(23)
	v_cndmask_b32_e64 v8, 0, v8, s[66:67]
	s_waitcnt vmcnt(22)
	v_cndmask_b32_e64 v9, 0, v9, s[66:67]
	ds_write2_b32 v1, v4, v5 offset0:36 offset1:101
	ds_write2_b32 v1, v6, v7 offset0:166 offset1:231
	v_add_u32_e32 v1, 0x2800, v57
	s_waitcnt vmcnt(21)
	v_cndmask_b32_e64 v10, 0, v10, s[66:67]
	s_waitcnt vmcnt(20)
	v_cndmask_b32_e64 v11, 0, v11, s[66:67]
	s_waitcnt vmcnt(19)
	v_cndmask_b32_e64 v12, 0, v12, s[66:67]
	s_waitcnt vmcnt(18)
	v_cndmask_b32_e64 v13, 0, v13, s[66:67]
	ds_write2_b32 v1, v8, v9 offset0:40 offset1:105
	ds_write2_b32 v1, v10, v11 offset0:170 offset1:235
	v_add_u32_e32 v1, 0x2c00, v57
	s_waitcnt vmcnt(17)
	v_cndmask_b32_e64 v14, 0, v14, s[66:67]
	s_waitcnt vmcnt(16)
	v_cndmask_b32_e64 v15, 0, v15, s[66:67]
	s_waitcnt vmcnt(15)
	v_cndmask_b32_e64 v16, 0, v16, s[66:67]
	s_waitcnt vmcnt(14)
	v_cndmask_b32_e64 v17, 0, v17, s[66:67]
	ds_write2_b32 v1, v12, v13 offset0:44 offset1:109
	ds_write2_b32 v1, v14, v15 offset0:174 offset1:239
	v_add_u32_e32 v1, 0x3000, v57
	s_waitcnt vmcnt(13)
	v_cndmask_b32_e64 v18, 0, v18, s[66:67]
	s_waitcnt vmcnt(12)
	v_cndmask_b32_e64 v19, 0, v19, s[66:67]
	s_waitcnt vmcnt(11)
	v_cndmask_b32_e64 v20, 0, v20, s[66:67]
	s_waitcnt vmcnt(10)
	v_cndmask_b32_e64 v21, 0, v21, s[66:67]
	s_waitcnt vmcnt(9)
	v_cndmask_b32_e64 v22, 0, v22, s[66:67]
	s_waitcnt vmcnt(8)
	v_cndmask_b32_e64 v23, 0, v23, s[66:67]
	ds_write2_b32 v1, v16, v17 offset0:48 offset1:113
	ds_write2_b32 v1, v18, v19 offset0:178 offset1:243
	v_add_u32_e32 v1, 0x3400, v57
	v_mad_u64_u32 v[2:3], s[0:1], s85, v49, v[44:45]
	s_waitcnt vmcnt(7)
	v_cndmask_b32_e64 v24, 0, v24, s[66:67]
	s_waitcnt vmcnt(6)
	v_cndmask_b32_e64 v25, 0, v25, s[66:67]
	ds_write2_b32 v1, v20, v21 offset0:52 offset1:117
	v_and_b32_e32 v2, 0x60, v2
	ds_write2_b32 v1, v22, v23 offset0:182 offset1:247
	v_add_u32_e32 v1, 0x3800, v57
	s_waitcnt vmcnt(5)
	v_cndmask_b32_e64 v26, 0, v26, s[66:67]
	s_waitcnt vmcnt(4)
	v_cndmask_b32_e64 v27, 0, v27, s[66:67]
	s_waitcnt vmcnt(3)
	v_cndmask_b32_e64 v28, 0, v28, s[66:67]
	v_and_or_b32 v32, v46, s76, v2
	ds_write2_b32 v1, v24, v25 offset0:56 offset1:121
	ds_write2_b32 v1, v26, v27 offset0:186 offset1:251
	s_waitcnt vmcnt(2)
	v_cndmask_b32_e64 v1, 0, v29, s[66:67]
	v_add_u32_e32 v2, 0x3c00, v57
	ds_write2_b32 v2, v28, v1 offset0:60 offset1:125
	s_waitcnt vmcnt(1)
	v_cndmask_b32_e64 v1, 0, v30, s[66:67]
	s_waitcnt vmcnt(0)
	v_cndmask_b32_e64 v3, 0, v31, s[66:67]
	ds_write2_b32 v2, v1, v3 offset0:190 offset1:255
	s_waitcnt lgkmcnt(0)
	ds_read2_b32 v[6:7], v59 offset0:65 offset1:73
	ds_read2_b32 v[8:9], v59 offset1:8
	ds_read2_b32 v[10:11], v59 offset0:130 offset1:138
	ds_read2_b32 v[12:13], v59 offset0:195 offset1:203
	v_add_u32_e32 v1, 0x400, v59
	ds_read2_b32 v[14:15], v1 offset0:4 offset1:12
	ds_read2_b32 v[16:17], v1 offset0:69 offset1:77
	ds_read2_b32 v[18:19], v1 offset0:134 offset1:142
	ds_read2_b32 v[20:21], v1 offset0:199 offset1:207
	s_waitcnt lgkmcnt(6)
	v_cvt_pk_bf16_f32 v2, v8, v6
	v_or_b32_e32 v6, v32, v58
	v_mad_u64_u32 v[24:25], s[0:1], v6, s79, 0
	v_ashrrev_i32_e32 v6, 31, v46
	v_ashrrev_i32_e32 v49, 31, v48
	v_mul_lo_u32 v26, v6, s79
	v_lshl_add_u64 v[22:23], v[48:49], 1, v[40:41]
	v_add_u32_e32 v25, v25, v26
	s_waitcnt lgkmcnt(4)
	v_cvt_pk_bf16_f32 v3, v10, v12
	s_waitcnt lgkmcnt(2)
	v_cvt_pk_bf16_f32 v4, v14, v16
	s_waitcnt lgkmcnt(0)
	v_cvt_pk_bf16_f32 v5, v18, v20
	v_lshl_add_u64 v[24:25], v[24:25], 1, v[22:23]
	v_or_b32_e32 v6, v32, v60
	global_store_dwordx4 v[24:25], v[2:5], off sc1
	v_or_b32_e32 v27, 0x80, v32
	v_add_u32_e32 v38, s90, v38
	v_cvt_pk_bf16_f32 v2, v9, v7
	v_mad_u64_u32 v[6:7], s[0:1], v6, s79, 0
	v_cvt_pk_bf16_f32 v3, v11, v13
	v_cvt_pk_bf16_f32 v4, v15, v17
	v_cvt_pk_bf16_f32 v5, v19, v21
	v_add_u32_e32 v7, v7, v26
	ds_read2_b32 v[8:9], v59 offset0:16 offset1:24
	ds_read2_b32 v[10:11], v59 offset0:81 offset1:89
	ds_read2_b32 v[12:13], v59 offset0:146 offset1:154
	ds_read2_b32 v[14:15], v59 offset0:211 offset1:219
	ds_read2_b32 v[16:17], v1 offset0:20 offset1:28
	ds_read2_b32 v[18:19], v1 offset0:85 offset1:93
	ds_read2_b32 v[20:21], v1 offset0:150 offset1:158
	ds_read2_b32 v[24:25], v1 offset0:215 offset1:223
	v_lshl_add_u64 v[6:7], v[6:7], 1, v[22:23]
	global_store_dwordx4 v[6:7], v[2:5], off sc1
	v_or_b32_e32 v6, v32, v61
	v_mad_u64_u32 v[6:7], s[0:1], v6, s79, 0
	v_add_u32_e32 v7, v7, v26
	s_waitcnt lgkmcnt(6)
	v_cvt_pk_bf16_f32 v2, v8, v10
	s_waitcnt lgkmcnt(4)
	v_cvt_pk_bf16_f32 v3, v12, v14
	s_waitcnt lgkmcnt(2)
	v_cvt_pk_bf16_f32 v4, v16, v18
	s_waitcnt lgkmcnt(0)
	v_cvt_pk_bf16_f32 v5, v20, v24
	v_lshl_add_u64 v[6:7], v[6:7], 1, v[22:23]
	global_store_dwordx4 v[6:7], v[2:5], off sc1
	v_or_b32_e32 v6, v32, v62
	v_mad_u64_u32 v[6:7], s[0:1], v6, s79, 0
	v_cvt_pk_bf16_f32 v2, v9, v11
	v_cvt_pk_bf16_f32 v3, v13, v15
	v_cvt_pk_bf16_f32 v4, v17, v19
	v_cvt_pk_bf16_f32 v5, v21, v25
	v_add_u32_e32 v7, v7, v26
	ds_read2_b32 v[8:9], v59 offset0:32 offset1:40
	ds_read2_b32 v[10:11], v59 offset0:97 offset1:105
	ds_read2_b32 v[12:13], v59 offset0:162 offset1:170
	ds_read2_b32 v[14:15], v59 offset0:227 offset1:235
	ds_read2_b32 v[16:17], v1 offset0:36 offset1:44
	ds_read2_b32 v[18:19], v1 offset0:101 offset1:109
	ds_read2_b32 v[20:21], v1 offset0:166 offset1:174
	ds_read2_b32 v[24:25], v1 offset0:231 offset1:239
	v_lshl_add_u64 v[6:7], v[6:7], 1, v[22:23]
	global_store_dwordx4 v[6:7], v[2:5], off sc1
	v_or_b32_e32 v6, v27, v58
	v_mad_u64_u32 v[6:7], s[0:1], v6, s79, 0
	v_add_u32_e32 v7, v7, v26
	s_waitcnt lgkmcnt(6)
	v_cvt_pk_bf16_f32 v2, v8, v10
	s_waitcnt lgkmcnt(4)
	v_cvt_pk_bf16_f32 v3, v12, v14
	s_waitcnt lgkmcnt(2)
	v_cvt_pk_bf16_f32 v4, v16, v18
	s_waitcnt lgkmcnt(0)
	v_cvt_pk_bf16_f32 v5, v20, v24
	v_lshl_add_u64 v[6:7], v[6:7], 1, v[22:23]
	global_store_dwordx4 v[6:7], v[2:5], off sc1
	v_or_b32_e32 v6, v27, v60
	v_mad_u64_u32 v[6:7], s[0:1], v6, s79, 0
	v_cvt_pk_bf16_f32 v2, v9, v11
	v_cvt_pk_bf16_f32 v3, v13, v15
	v_cvt_pk_bf16_f32 v4, v17, v19
	v_cvt_pk_bf16_f32 v5, v21, v25
	ds_read2_b32 v[8:9], v59 offset0:48 offset1:56
	ds_read2_b32 v[10:11], v59 offset0:113 offset1:121
	ds_read2_b32 v[12:13], v59 offset0:178 offset1:186
	ds_read2_b32 v[14:15], v59 offset0:243 offset1:251
	ds_read2_b32 v[16:17], v1 offset0:52 offset1:60
	ds_read2_b32 v[18:19], v1 offset0:117 offset1:125
	ds_read2_b32 v[20:21], v1 offset0:182 offset1:190
	ds_read2_b32 v[24:25], v1 offset0:247 offset1:255
	v_add_u32_e32 v7, v7, v26
	v_lshl_add_u64 v[6:7], v[6:7], 1, v[22:23]
	v_or_b32_e32 v1, v27, v61
	global_store_dwordx4 v[6:7], v[2:5], off sc1
	v_mad_u64_u32 v[6:7], s[0:1], v1, s79, 0
	v_add_u32_e32 v7, v7, v26
	s_waitcnt lgkmcnt(6)
	v_cvt_pk_bf16_f32 v2, v8, v10
	s_waitcnt lgkmcnt(4)
	v_cvt_pk_bf16_f32 v3, v12, v14
	s_waitcnt lgkmcnt(2)
	v_cvt_pk_bf16_f32 v4, v16, v18
	s_waitcnt lgkmcnt(0)
	v_cvt_pk_bf16_f32 v5, v20, v24
	v_lshl_add_u64 v[6:7], v[6:7], 1, v[22:23]
	v_or_b32_e32 v1, v27, v62
	global_store_dwordx4 v[6:7], v[2:5], off sc1
	v_mad_u64_u32 v[6:7], s[0:1], v1, s79, 0
	v_add_u32_e32 v7, v7, v26
	v_cvt_pk_bf16_f32 v2, v9, v11
	v_cvt_pk_bf16_f32 v3, v13, v15
	v_cvt_pk_bf16_f32 v4, v17, v19
	v_cvt_pk_bf16_f32 v5, v21, v25
	v_lshl_add_u64 v[6:7], v[6:7], 1, v[22:23]
	global_store_dwordx4 v[6:7], v[2:5], off sc1
	s_waitcnt lgkmcnt(0)
	v_cmp_le_i32_e32 vcc, s81, v38
	v_add_u32_e32 v42, s84, v42
	s_or_b64 s[64:65], vcc, s[64:65]
	v_add_u32_e32 v44, s86, v44
	s_andn2_b64 exec, exec, s[64:65]
	s_cbranch_execz .LBB0_24

.LBB0_233:
	v_ashrrev_i32_e32 v0, 13, v128
	v_ashrrev_i32_e32 v1, 31, v0
	v_lshl_add_u64 v[0:1], v[134:135], 0, v[0:1]
	v_and_b32_e32 v2, 0x1fff, v128
	v_lshlrev_b64 v[0:1], 11, v[0:1]
	v_lshl_add_u64 v[40:41], v[130:131], 0, v[0:1]
	v_add_u32_e32 v0, 1, v2
	v_min_u32_e32 v129, v137, v0
	v_cmp_eq_u32_e32 vcc, 0, v2
	v_mov_b32_e32 v0, 0xfffff800
	global_load_dwordx4 v[44:47], v[40:41], off offset:16
	global_load_dwordx4 v[48:51], v[40:41], off
	v_cndmask_b32_e64 v1, -1, 0, vcc
	v_cndmask_b32_e64 v0, v0, 0, vcc
	v_lshl_add_u64 v[4:5], v[40:41], 0, v[0:1]
	global_load_dwordx4 v[0:3], v[4:5], off offset:16
	global_load_dwordx4 v[52:55], v[4:5], off
	v_cmp_lt_u32_e64 s[2:3], 2, v129
	v_mov_b32_e32 v4, 0xfffff000
	v_cmp_lt_u32_e64 s[4:5], 3, v129
	v_cndmask_b32_e64 v5, 0, -1, s[2:3]
	v_cndmask_b32_e64 v4, 0, v4, s[2:3]
	v_lshl_add_u64 v[8:9], v[40:41], 0, v[4:5]
	global_load_dwordx4 v[4:7], v[8:9], off offset:16
	global_load_dwordx4 v[56:59], v[8:9], off
	v_mov_b32_e32 v8, 0xffffe800
	v_cndmask_b32_e64 v9, 0, -1, s[4:5]
	v_cndmask_b32_e64 v8, 0, v8, s[4:5]
	v_lshl_add_u64 v[12:13], v[40:41], 0, v[8:9]
	global_load_dwordx4 v[8:11], v[12:13], off offset:16
	global_load_dwordx4 v[60:63], v[12:13], off
	v_cmp_lt_u32_e64 s[6:7], 4, v129
	v_mov_b32_e32 v12, 0xffffe000
	v_cmp_lt_u32_e64 s[8:9], 5, v129
	v_cndmask_b32_e64 v13, 0, -1, s[6:7]
	v_cndmask_b32_e64 v12, 0, v12, s[6:7]
	v_lshl_add_u64 v[16:17], v[40:41], 0, v[12:13]
	global_load_dwordx4 v[12:15], v[16:17], off offset:16
	global_load_dwordx4 v[64:67], v[16:17], off
	v_mov_b32_e32 v16, 0xffffd800
	v_cndmask_b32_e64 v17, 0, -1, s[8:9]
	v_cndmask_b32_e64 v16, 0, v16, s[8:9]
	v_lshl_add_u64 v[20:21], v[40:41], 0, v[16:17]
	global_load_dwordx4 v[16:19], v[20:21], off offset:16
	global_load_dwordx4 v[68:71], v[20:21], off
	v_cmp_lt_u32_e64 s[10:11], 6, v129
	v_mov_b32_e32 v20, 0xffffd000
	v_cmp_lt_u32_e64 s[12:13], 7, v129
	v_cndmask_b32_e64 v21, 0, -1, s[10:11]
	v_cndmask_b32_e64 v20, 0, v20, s[10:11]
	v_lshl_add_u64 v[24:25], v[40:41], 0, v[20:21]
	global_load_dwordx4 v[20:23], v[24:25], off offset:16
	global_load_dwordx4 v[72:75], v[24:25], off
	v_mov_b32_e32 v24, 0xffffc800
	v_cndmask_b32_e64 v25, 0, -1, s[12:13]
	v_cndmask_b32_e64 v24, 0, v24, s[12:13]
	v_lshl_add_u64 v[24:25], v[40:41], 0, v[24:25]
	global_load_dwordx4 v[96:99], v[24:25], off offset:16
	global_load_dwordx4 v[100:103], v[24:25], off
	v_cmp_lt_u32_e64 s[14:15], 8, v129
	v_mov_b32_e32 v24, 0xffffc000
	v_cmp_lt_u32_e64 s[16:17], 9, v129
	v_cndmask_b32_e64 v25, 0, -1, s[14:15]
	v_cndmask_b32_e64 v24, 0, v24, s[14:15]
	v_lshl_add_u64 v[24:25], v[40:41], 0, v[24:25]
	global_load_dwordx4 v[104:107], v[24:25], off offset:16
	global_load_dwordx4 v[108:111], v[24:25], off
	v_mov_b32_e32 v24, 0xffffb800
	v_cndmask_b32_e64 v25, 0, -1, s[16:17]
	v_cndmask_b32_e64 v24, 0, v24, s[16:17]
	v_lshl_add_u64 v[24:25], v[40:41], 0, v[24:25]
	global_load_dwordx4 v[112:115], v[24:25], off offset:16
	global_load_dwordx4 v[116:119], v[24:25], off
	v_cmp_lt_u32_e64 s[18:19], 10, v129
	v_mov_b32_e32 v24, 0xffffb000
	v_cmp_lt_u32_e64 s[20:21], 11, v129
	v_cndmask_b32_e64 v25, 0, -1, s[18:19]
	v_cndmask_b32_e64 v24, 0, v24, s[18:19]
	v_lshl_add_u64 v[24:25], v[40:41], 0, v[24:25]
	global_load_dwordx4 v[120:123], v[24:25], off offset:16
	global_load_dwordx4 v[124:127], v[24:25], off
	v_mov_b32_e32 v24, 0xffffa800
	v_cndmask_b32_e64 v25, 0, -1, s[20:21]
	v_cndmask_b32_e64 v24, 0, v24, s[20:21]
	v_lshl_add_u64 v[24:25], v[40:41], 0, v[24:25]
	global_load_dwordx4 v[36:39], v[24:25], off offset:16
	global_load_dwordx4 v[76:79], v[24:25], off
	v_cmp_lt_u32_e64 s[22:23], 12, v129
	v_mov_b32_e32 v24, 0xffffa000
	v_cmp_lt_u32_e64 s[24:25], 13, v129
	v_cndmask_b32_e64 v25, 0, -1, s[22:23]
	v_cndmask_b32_e64 v24, 0, v24, s[22:23]
	v_lshl_add_u64 v[24:25], v[40:41], 0, v[24:25]
	global_load_dwordx4 v[32:35], v[24:25], off offset:16
	global_load_dwordx4 v[80:83], v[24:25], off
	v_mov_b32_e32 v24, 0xffff9800
	v_cndmask_b32_e64 v25, 0, -1, s[24:25]
	v_cndmask_b32_e64 v24, 0, v24, s[24:25]
	v_lshl_add_u64 v[24:25], v[40:41], 0, v[24:25]
	global_load_dwordx4 v[28:31], v[24:25], off offset:16
	global_load_dwordx4 v[84:87], v[24:25], off
	v_cmp_lt_u32_e64 s[26:27], 14, v129
	v_mov_b32_e32 v24, 0xffff9000
	v_cmp_lt_u32_e64 s[28:29], 15, v129
	v_cndmask_b32_e64 v25, 0, -1, s[26:27]
	v_cndmask_b32_e64 v24, 0, v24, s[26:27]
	v_lshl_add_u64 v[42:43], v[40:41], 0, v[24:25]
	global_load_dwordx4 v[24:27], v[42:43], off offset:16
	global_load_dwordx4 v[88:91], v[42:43], off
	v_mov_b32_e32 v42, 0xffff8800
	v_cndmask_b32_e64 v43, 0, -1, s[28:29]
	v_cndmask_b32_e64 v42, 0, v42, s[28:29]
	v_lshl_add_u64 v[92:93], v[40:41], 0, v[42:43]
	global_load_dwordx4 v[40:43], v[92:93], off offset:16
	s_nop 0
	global_load_dwordx4 v[92:95], v[92:93], off
	v_cndmask_b32_e64 v138, 1.0, 0, vcc
	v_cndmask_b32_e64 v140, 0, 1.0, s[2:3]
	s_waitcnt vmcnt(26)
	v_lshlrev_b32_e32 v216, 16, v56
	v_and_b32_e32 v217, 0xffff0000, v56
	v_cndmask_b32_e64 v142, 0, 1.0, s[4:5]
	v_cndmask_b32_e64 v144, 0, 1.0, s[6:7]
	v_cndmask_b32_e64 v146, 0, 1.0, s[8:9]
	s_waitcnt vmcnt(24)
	v_lshlrev_b32_e32 v218, 16, v60
	v_and_b32_e32 v219, 0xffff0000, v60
	v_cndmask_b32_e64 v148, 0, 1.0, s[10:11]
	v_cndmask_b32_e64 v136, 0, 1.0, s[12:13]
	v_cndmask_b32_e64 v152, 0, 1.0, s[14:15]
	v_lshlrev_b32_e32 v56, 16, v57
	v_and_b32_e32 v57, 0xffff0000, v57
	s_waitcnt vmcnt(22)
	v_lshlrev_b32_e32 v220, 16, v64
	v_and_b32_e32 v221, 0xffff0000, v64
	v_lshlrev_b32_e32 v60, 16, v61
	v_and_b32_e32 v61, 0xffff0000, v61
	v_lshlrev_b32_e32 v64, 16, v65
	s_waitcnt vmcnt(20)
	v_lshlrev_b32_e32 v222, 16, v68
	v_and_b32_e32 v223, 0xffff0000, v68
	v_and_b32_e32 v65, 0xffff0000, v65
	v_lshlrev_b32_e32 v68, 16, v69
	v_and_b32_e32 v69, 0xffff0000, v69
	v_add_u32_e32 v128, s86, v128
	v_lshl_add_u64 v[134:135], v[134:135], 0, s[86:87]
	s_waitcnt vmcnt(18)
	v_lshlrev_b32_e32 v238, 16, v72
	v_and_b32_e32 v239, 0xffff0000, v72
	v_lshlrev_b32_e32 v72, 16, v73
	v_and_b32_e32 v73, 0xffff0000, v73
	s_waitcnt vmcnt(17)
	v_lshlrev_b32_e32 v172, 16, v97
	v_and_b32_e32 v173, 0xffff0000, v97
	v_cvt_f32_ubyte0_e32 v97, v129
	v_lshlrev_b32_e32 v158, 16, v98
	v_and_b32_e32 v159, 0xffff0000, v98
	v_div_scale_f32 v98, s[0:1], v97, v97, 1.0
	v_lshlrev_b32_e32 v150, 16, v99
	v_and_b32_e32 v151, 0xffff0000, v99
	v_rcp_f32_e32 v99, v98
	s_waitcnt vmcnt(16)
	v_lshlrev_b32_e32 v208, 16, v100
	v_and_b32_e32 v209, 0xffff0000, v100
	s_waitcnt vmcnt(14)
	v_lshlrev_b32_e32 v210, 16, v108
	s_waitcnt vmcnt(12)
	v_lshlrev_b32_e32 v212, 16, v116
	v_and_b32_e32 v213, 0xffff0000, v116
	v_lshlrev_b32_e32 v196, 16, v117
	v_and_b32_e32 v197, 0xffff0000, v117
	v_and_b32_e32 v211, 0xffff0000, v108
	v_lshlrev_b32_e32 v192, 16, v101
	s_waitcnt vmcnt(11)
	v_lshlrev_b32_e32 v116, 16, v123
	s_waitcnt vmcnt(10)
	v_lshlrev_b32_e32 v214, 16, v124
	v_and_b32_e32 v215, 0xffff0000, v124
	v_lshlrev_b32_e32 v198, 16, v125
	v_and_b32_e32 v199, 0xffff0000, v125
	v_lshlrev_b32_e32 v124, 16, v122
	v_and_b32_e32 v125, 0xffff0000, v122
	v_and_b32_e32 v117, 0xffff0000, v123
	v_lshlrev_b32_e32 v122, 16, v48
	v_and_b32_e32 v123, 0xffff0000, v48
	v_lshlrev_b32_e32 v206, 16, v120
	v_and_b32_e32 v207, 0xffff0000, v120
	v_lshlrev_b32_e32 v190, 16, v121
	v_and_b32_e32 v191, 0xffff0000, v121
	v_lshlrev_b32_e32 v170, 16, v126
	v_and_b32_e32 v171, 0xffff0000, v126
	v_lshlrev_b32_e32 v120, 16, v127
	v_and_b32_e32 v121, 0xffff0000, v127
	v_lshlrev_b32_e32 v126, 16, v52
	v_and_b32_e32 v127, 0xffff0000, v52
	v_pk_add_f32 v[240:241], v[122:123], 0 op_sel_hi:[1,0]
	v_and_b32_e32 v193, 0xffff0000, v101
	v_pk_fma_f32 v[126:127], v[138:139], v[126:127], v[240:241] op_sel_hi:[0,1,1]
	v_pk_fma_f32 v[126:127], v[140:141], v[216:217], v[126:127] op_sel_hi:[0,1,1]
	v_pk_fma_f32 v[126:127], v[142:143], v[218:219], v[126:127] op_sel_hi:[0,1,1]
	v_pk_fma_f32 v[126:127], v[144:145], v[220:221], v[126:127] op_sel_hi:[0,1,1]
	v_pk_fma_f32 v[126:127], v[146:147], v[222:223], v[126:127] op_sel_hi:[0,1,1]
	v_pk_fma_f32 v[126:127], v[148:149], v[238:239], v[126:127] op_sel_hi:[0,1,1]
	v_pk_fma_f32 v[126:127], v[136:137], v[208:209], v[126:127] op_sel_hi:[0,1,1]
	v_lshlrev_b32_e32 v166, 16, v110
	v_and_b32_e32 v167, 0xffff0000, v110
	v_cndmask_b32_e64 v110, 0, 1.0, s[16:17]
	v_fma_f32 v101, -v98, v99, 1.0
	v_pk_fma_f32 v[126:127], v[152:153], v[210:211], v[126:127] op_sel_hi:[0,1,1]
	v_lshlrev_b32_e32 v162, 16, v114
	v_and_b32_e32 v163, 0xffff0000, v114
	v_cndmask_b32_e64 v114, 0, 1.0, s[18:19]
	v_fmac_f32_e32 v99, v101, v99
	v_div_scale_f32 v101, vcc, 1.0, v97, 1.0
	v_pk_fma_f32 v[126:127], v[110:111], v[212:213], v[126:127] op_sel_hi:[0,1,1]
	v_lshlrev_b32_e32 v154, 16, v103
	v_and_b32_e32 v155, 0xffff0000, v103
	v_lshlrev_b32_e32 v160, 16, v106
	v_and_b32_e32 v161, 0xffff0000, v106
	v_cndmask_b32_e64 v106, 0, 1.0, s[20:21]
	v_mul_f32_e32 v103, v101, v99
	v_pk_fma_f32 v[126:127], v[114:115], v[214:215], v[126:127] op_sel_hi:[0,1,1]
	s_waitcnt vmcnt(8)
	v_lshlrev_b32_e32 v208, 16, v76
	v_and_b32_e32 v209, 0xffff0000, v76
	v_lshlrev_b32_e32 v202, 16, v104
	v_and_b32_e32 v203, 0xffff0000, v104
	v_lshlrev_b32_e32 v174, 16, v105
	v_and_b32_e32 v175, 0xffff0000, v105
	v_cndmask_b32_e64 v104, 0, 1.0, s[22:23]
	v_fma_f32 v105, -v98, v103, v101
	v_pk_fma_f32 v[126:127], v[106:107], v[208:209], v[126:127] op_sel_hi:[0,1,1]
	s_waitcnt vmcnt(6)
	v_lshlrev_b32_e32 v208, 16, v80
	v_and_b32_e32 v209, 0xffff0000, v80
	v_lshlrev_b32_e32 v164, 16, v102
	v_and_b32_e32 v165, 0xffff0000, v102
	v_cndmask_b32_e64 v102, 0, 1.0, s[24:25]
	v_fmac_f32_e32 v103, v105, v99
	v_pk_fma_f32 v[126:127], v[104:105], v[208:209], v[126:127] op_sel_hi:[0,1,1]
	s_waitcnt vmcnt(4)
	v_lshlrev_b32_e32 v208, 16, v84
	v_and_b32_e32 v209, 0xffff0000, v84
	v_cndmask_b32_e64 v100, 0, 1.0, s[26:27]
	v_fma_f32 v98, -v98, v103, v101
	v_pk_fma_f32 v[126:127], v[102:103], v[208:209], v[126:127] op_sel_hi:[0,1,1]
	s_waitcnt vmcnt(2)
	v_lshlrev_b32_e32 v208, 16, v88
	v_and_b32_e32 v209, 0xffff0000, v88
	v_lshlrev_b32_e32 v200, 16, v96
	v_and_b32_e32 v201, 0xffff0000, v96
	v_cndmask_b32_e64 v96, 0, 1.0, s[28:29]
	v_div_fmas_f32 v98, v98, v99, v103
	v_pk_fma_f32 v[126:127], v[100:101], v[208:209], v[126:127] op_sel_hi:[0,1,1]
	s_waitcnt vmcnt(0)
	v_lshlrev_b32_e32 v208, 16, v92
	v_and_b32_e32 v209, 0xffff0000, v92
	v_div_fixup_f32 v98, v98, v97, 1.0
	v_pk_fma_f32 v[126:127], v[96:97], v[208:209], v[126:127] op_sel_hi:[0,1,1]
	v_pk_fma_f32 v[122:123], v[98:99], v[126:127], v[122:123] op_sel_hi:[0,1,1] neg_lo:[0,0,1] neg_hi:[0,0,1]
	v_cvt_pk_bf16_f32 v48, v122, v123
	v_lshlrev_b32_e32 v122, 16, v44
	v_and_b32_e32 v123, 0xffff0000, v44
	v_lshlrev_b32_e32 v126, 16, v0
	v_and_b32_e32 v127, 0xffff0000, v0
	v_pk_add_f32 v[218:219], v[122:123], 0 op_sel_hi:[1,0]
	v_lshlrev_b32_e32 v208, 16, v4
	v_and_b32_e32 v209, 0xffff0000, v4
	v_pk_fma_f32 v[126:127], v[138:139], v[126:127], v[218:219] op_sel_hi:[0,1,1]
	v_lshlrev_b32_e32 v210, 16, v8
	v_and_b32_e32 v211, 0xffff0000, v8
	v_pk_fma_f32 v[126:127], v[140:141], v[208:209], v[126:127] op_sel_hi:[0,1,1]
	v_lshlrev_b32_e32 v212, 16, v12
	v_and_b32_e32 v213, 0xffff0000, v12
	v_pk_fma_f32 v[126:127], v[142:143], v[210:211], v[126:127] op_sel_hi:[0,1,1]
	v_lshlrev_b32_e32 v214, 16, v16
	v_and_b32_e32 v215, 0xffff0000, v16
	v_pk_fma_f32 v[126:127], v[144:145], v[212:213], v[126:127] op_sel_hi:[0,1,1]
	v_lshlrev_b32_e32 v216, 16, v20
	v_and_b32_e32 v217, 0xffff0000, v20
	v_pk_fma_f32 v[126:127], v[146:147], v[214:215], v[126:127] op_sel_hi:[0,1,1]
	v_pk_fma_f32 v[126:127], v[148:149], v[216:217], v[126:127] op_sel_hi:[0,1,1]
	v_pk_fma_f32 v[126:127], v[136:137], v[200:201], v[126:127] op_sel_hi:[0,1,1]
	v_lshlrev_b32_e32 v204, 16, v112
	v_and_b32_e32 v205, 0xffff0000, v112
	v_pk_fma_f32 v[126:127], v[152:153], v[202:203], v[126:127] op_sel_hi:[0,1,1]
	v_pk_fma_f32 v[126:127], v[110:111], v[204:205], v[126:127] op_sel_hi:[0,1,1]
	v_pk_fma_f32 v[126:127], v[114:115], v[206:207], v[126:127] op_sel_hi:[0,1,1]
	v_lshlrev_b32_e32 v200, 16, v36
	v_and_b32_e32 v201, 0xffff0000, v36
	v_pk_fma_f32 v[126:127], v[106:107], v[200:201], v[126:127] op_sel_hi:[0,1,1]
	v_lshlrev_b32_e32 v200, 16, v32
	v_and_b32_e32 v201, 0xffff0000, v32
	v_pk_fma_f32 v[126:127], v[104:105], v[200:201], v[126:127] op_sel_hi:[0,1,1]
	v_lshlrev_b32_e32 v200, 16, v28
	v_and_b32_e32 v201, 0xffff0000, v28
	v_pk_fma_f32 v[126:127], v[102:103], v[200:201], v[126:127] op_sel_hi:[0,1,1]
	v_lshlrev_b32_e32 v200, 16, v24
	v_and_b32_e32 v201, 0xffff0000, v24
	v_pk_fma_f32 v[126:127], v[100:101], v[200:201], v[126:127] op_sel_hi:[0,1,1]
	v_lshlrev_b32_e32 v200, 16, v40
	v_and_b32_e32 v201, 0xffff0000, v40
	v_pk_fma_f32 v[126:127], v[96:97], v[200:201], v[126:127] op_sel_hi:[0,1,1]
	v_pk_fma_f32 v[122:123], v[98:99], v[126:127], v[122:123] op_sel_hi:[0,1,1] neg_lo:[0,0,1] neg_hi:[0,0,1]
	v_cvt_pk_bf16_f32 v0, v122, v123
	v_lshlrev_b32_e32 v122, 16, v49
	v_and_b32_e32 v123, 0xffff0000, v49
	v_lshlrev_b32_e32 v52, 16, v53
	v_and_b32_e32 v53, 0xffff0000, v53
	v_pk_add_f32 v[126:127], v[122:123], 0 op_sel_hi:[1,0]
	v_lshlrev_b32_e32 v194, 16, v109
	v_pk_fma_f32 v[52:53], v[138:139], v[52:53], v[126:127] op_sel_hi:[0,1,1]
	v_pk_fma_f32 v[52:53], v[140:141], v[56:57], v[52:53] op_sel_hi:[0,1,1]
	v_pk_fma_f32 v[52:53], v[142:143], v[60:61], v[52:53] op_sel_hi:[0,1,1]
	v_pk_fma_f32 v[52:53], v[144:145], v[64:65], v[52:53] op_sel_hi:[0,1,1]
	v_pk_fma_f32 v[52:53], v[146:147], v[68:69], v[52:53] op_sel_hi:[0,1,1]
	v_pk_fma_f32 v[52:53], v[148:149], v[72:73], v[52:53] op_sel_hi:[0,1,1]
	v_and_b32_e32 v195, 0xffff0000, v109
	v_pk_fma_f32 v[52:53], v[136:137], v[192:193], v[52:53] op_sel_hi:[0,1,1]
	v_pk_fma_f32 v[52:53], v[152:153], v[194:195], v[52:53] op_sel_hi:[0,1,1]
	v_pk_fma_f32 v[52:53], v[110:111], v[196:197], v[52:53] op_sel_hi:[0,1,1]
	v_pk_fma_f32 v[52:53], v[114:115], v[198:199], v[52:53] op_sel_hi:[0,1,1]
	v_lshlrev_b32_e32 v56, 16, v77
	v_and_b32_e32 v57, 0xffff0000, v77
	v_pk_fma_f32 v[52:53], v[106:107], v[56:57], v[52:53] op_sel_hi:[0,1,1]
	v_lshlrev_b32_e32 v56, 16, v81
	v_and_b32_e32 v57, 0xffff0000, v81
	v_pk_fma_f32 v[52:53], v[104:105], v[56:57], v[52:53] op_sel_hi:[0,1,1]
	v_lshlrev_b32_e32 v56, 16, v85
	v_and_b32_e32 v57, 0xffff0000, v85
	v_pk_fma_f32 v[52:53], v[102:103], v[56:57], v[52:53] op_sel_hi:[0,1,1]
	v_lshlrev_b32_e32 v56, 16, v89
	v_and_b32_e32 v57, 0xffff0000, v89
	v_pk_fma_f32 v[52:53], v[100:101], v[56:57], v[52:53] op_sel_hi:[0,1,1]
	v_lshlrev_b32_e32 v56, 16, v93
	v_and_b32_e32 v57, 0xffff0000, v93
	v_pk_fma_f32 v[52:53], v[96:97], v[56:57], v[52:53] op_sel_hi:[0,1,1]
	v_pk_fma_f32 v[52:53], v[98:99], v[52:53], v[122:123] op_sel_hi:[0,1,1] neg_lo:[0,0,1] neg_hi:[0,0,1]
	v_lshlrev_b32_e32 v44, 16, v45
	v_and_b32_e32 v45, 0xffff0000, v45
	v_cvt_pk_bf16_f32 v49, v52, v53
	v_lshlrev_b32_e32 v52, 16, v1
	v_and_b32_e32 v53, 0xffff0000, v1
	v_pk_add_f32 v[56:57], v[44:45], 0 op_sel_hi:[1,0]
	v_lshlrev_b32_e32 v4, 16, v5
	v_and_b32_e32 v5, 0xffff0000, v5
	v_pk_fma_f32 v[52:53], v[138:139], v[52:53], v[56:57] op_sel_hi:[0,1,1]
	v_lshlrev_b32_e32 v8, 16, v9
	v_and_b32_e32 v9, 0xffff0000, v9
	v_pk_fma_f32 v[4:5], v[140:141], v[4:5], v[52:53] op_sel_hi:[0,1,1]
	v_lshlrev_b32_e32 v12, 16, v13
	v_and_b32_e32 v13, 0xffff0000, v13
	v_pk_fma_f32 v[4:5], v[142:143], v[8:9], v[4:5] op_sel_hi:[0,1,1]
	v_lshlrev_b32_e32 v16, 16, v17
	v_and_b32_e32 v17, 0xffff0000, v17
	v_pk_fma_f32 v[4:5], v[144:145], v[12:13], v[4:5] op_sel_hi:[0,1,1]
	v_lshlrev_b32_e32 v20, 16, v21
	v_and_b32_e32 v21, 0xffff0000, v21
	v_pk_fma_f32 v[4:5], v[146:147], v[16:17], v[4:5] op_sel_hi:[0,1,1]
	v_pk_fma_f32 v[4:5], v[148:149], v[20:21], v[4:5] op_sel_hi:[0,1,1]
	v_pk_fma_f32 v[4:5], v[136:137], v[172:173], v[4:5] op_sel_hi:[0,1,1]
	v_lshlrev_b32_e32 v188, 16, v113
	v_and_b32_e32 v189, 0xffff0000, v113
	v_pk_fma_f32 v[4:5], v[152:153], v[174:175], v[4:5] op_sel_hi:[0,1,1]
	v_pk_fma_f32 v[4:5], v[110:111], v[188:189], v[4:5] op_sel_hi:[0,1,1]
	v_pk_fma_f32 v[4:5], v[114:115], v[190:191], v[4:5] op_sel_hi:[0,1,1]
	v_lshlrev_b32_e32 v8, 16, v37
	v_and_b32_e32 v9, 0xffff0000, v37
	v_pk_fma_f32 v[4:5], v[106:107], v[8:9], v[4:5] op_sel_hi:[0,1,1]
	v_lshlrev_b32_e32 v8, 16, v33
	v_and_b32_e32 v9, 0xffff0000, v33
	v_pk_fma_f32 v[4:5], v[104:105], v[8:9], v[4:5] op_sel_hi:[0,1,1]
	v_lshlrev_b32_e32 v8, 16, v29
	v_and_b32_e32 v9, 0xffff0000, v29
	v_pk_fma_f32 v[4:5], v[102:103], v[8:9], v[4:5] op_sel_hi:[0,1,1]
	v_lshlrev_b32_e32 v8, 16, v25
	v_and_b32_e32 v9, 0xffff0000, v25
	v_pk_fma_f32 v[4:5], v[100:101], v[8:9], v[4:5] op_sel_hi:[0,1,1]
	v_lshlrev_b32_e32 v8, 16, v41
	v_and_b32_e32 v9, 0xffff0000, v41
	v_pk_fma_f32 v[4:5], v[96:97], v[8:9], v[4:5] op_sel_hi:[0,1,1]
	v_pk_fma_f32 v[4:5], v[98:99], v[4:5], v[44:45] op_sel_hi:[0,1,1] neg_lo:[0,0,1] neg_hi:[0,0,1]
	v_cvt_pk_bf16_f32 v1, v4, v5
	v_lshlrev_b32_e32 v4, 16, v50
	v_and_b32_e32 v5, 0xffff0000, v50
	v_lshlrev_b32_e32 v8, 16, v54
	v_and_b32_e32 v9, 0xffff0000, v54
	v_pk_add_f32 v[32:33], v[4:5], 0 op_sel_hi:[1,0]
	v_lshlrev_b32_e32 v12, 16, v58
	v_and_b32_e32 v13, 0xffff0000, v58
	v_pk_fma_f32 v[8:9], v[138:139], v[8:9], v[32:33] op_sel_hi:[0,1,1]
	v_lshlrev_b32_e32 v16, 16, v62
	v_and_b32_e32 v17, 0xffff0000, v62
	v_pk_fma_f32 v[8:9], v[140:141], v[12:13], v[8:9] op_sel_hi:[0,1,1]
	v_lshlrev_b32_e32 v20, 16, v66
	v_and_b32_e32 v21, 0xffff0000, v66
	v_pk_fma_f32 v[8:9], v[142:143], v[16:17], v[8:9] op_sel_hi:[0,1,1]
	v_lshlrev_b32_e32 v24, 16, v70
	v_and_b32_e32 v25, 0xffff0000, v70
	v_pk_fma_f32 v[8:9], v[144:145], v[20:21], v[8:9] op_sel_hi:[0,1,1]
	v_lshlrev_b32_e32 v28, 16, v74
	v_and_b32_e32 v29, 0xffff0000, v74
	v_pk_fma_f32 v[8:9], v[146:147], v[24:25], v[8:9] op_sel_hi:[0,1,1]
	v_pk_fma_f32 v[8:9], v[148:149], v[28:29], v[8:9] op_sel_hi:[0,1,1]
	v_pk_fma_f32 v[8:9], v[136:137], v[164:165], v[8:9] op_sel_hi:[0,1,1]
	v_lshlrev_b32_e32 v168, 16, v118
	v_and_b32_e32 v169, 0xffff0000, v118
	v_pk_fma_f32 v[8:9], v[152:153], v[166:167], v[8:9] op_sel_hi:[0,1,1]
	v_pk_fma_f32 v[8:9], v[110:111], v[168:169], v[8:9] op_sel_hi:[0,1,1]
	v_pk_fma_f32 v[8:9], v[114:115], v[170:171], v[8:9] op_sel_hi:[0,1,1]
	v_lshlrev_b32_e32 v12, 16, v78
	v_and_b32_e32 v13, 0xffff0000, v78
	v_pk_fma_f32 v[8:9], v[106:107], v[12:13], v[8:9] op_sel_hi:[0,1,1]
	v_lshlrev_b32_e32 v12, 16, v82
	v_and_b32_e32 v13, 0xffff0000, v82
	v_pk_fma_f32 v[8:9], v[104:105], v[12:13], v[8:9] op_sel_hi:[0,1,1]
	v_lshlrev_b32_e32 v12, 16, v86
	v_and_b32_e32 v13, 0xffff0000, v86
	v_pk_fma_f32 v[8:9], v[102:103], v[12:13], v[8:9] op_sel_hi:[0,1,1]
	v_lshlrev_b32_e32 v12, 16, v90
	v_and_b32_e32 v13, 0xffff0000, v90
	v_pk_fma_f32 v[8:9], v[100:101], v[12:13], v[8:9] op_sel_hi:[0,1,1]
	v_lshlrev_b32_e32 v12, 16, v94
	v_and_b32_e32 v13, 0xffff0000, v94
	v_pk_fma_f32 v[8:9], v[96:97], v[12:13], v[8:9] op_sel_hi:[0,1,1]
	v_pk_fma_f32 v[4:5], v[98:99], v[8:9], v[4:5] op_sel_hi:[0,1,1] neg_lo:[0,0,1] neg_hi:[0,0,1]
	v_cvt_pk_bf16_f32 v50, v4, v5
	v_lshlrev_b32_e32 v4, 16, v46
	v_and_b32_e32 v5, 0xffff0000, v46
	v_lshlrev_b32_e32 v8, 16, v2
	v_and_b32_e32 v9, 0xffff0000, v2
	v_pk_add_f32 v[32:33], v[4:5], 0 op_sel_hi:[1,0]
	v_lshlrev_b32_e32 v12, 16, v6
	v_and_b32_e32 v13, 0xffff0000, v6
	v_pk_fma_f32 v[8:9], v[138:139], v[8:9], v[32:33] op_sel_hi:[0,1,1]
	v_lshlrev_b32_e32 v16, 16, v10
	v_and_b32_e32 v17, 0xffff0000, v10
	v_pk_fma_f32 v[8:9], v[140:141], v[12:13], v[8:9] op_sel_hi:[0,1,1]
	v_lshlrev_b32_e32 v20, 16, v14
	v_and_b32_e32 v21, 0xffff0000, v14
	v_pk_fma_f32 v[8:9], v[142:143], v[16:17], v[8:9] op_sel_hi:[0,1,1]
	v_lshlrev_b32_e32 v24, 16, v18
	v_and_b32_e32 v25, 0xffff0000, v18
	v_pk_fma_f32 v[8:9], v[144:145], v[20:21], v[8:9] op_sel_hi:[0,1,1]
	v_lshlrev_b32_e32 v28, 16, v22
	v_and_b32_e32 v29, 0xffff0000, v22
	v_pk_fma_f32 v[8:9], v[146:147], v[24:25], v[8:9] op_sel_hi:[0,1,1]
	v_pk_fma_f32 v[8:9], v[148:149], v[28:29], v[8:9] op_sel_hi:[0,1,1]
	v_pk_fma_f32 v[8:9], v[136:137], v[158:159], v[8:9] op_sel_hi:[0,1,1]
	v_pk_fma_f32 v[8:9], v[152:153], v[160:161], v[8:9] op_sel_hi:[0,1,1]
	v_pk_fma_f32 v[8:9], v[110:111], v[162:163], v[8:9] op_sel_hi:[0,1,1]
	v_pk_fma_f32 v[8:9], v[114:115], v[124:125], v[8:9] op_sel_hi:[0,1,1]
	v_lshlrev_b32_e32 v12, 16, v38
	v_and_b32_e32 v13, 0xffff0000, v38
	v_pk_fma_f32 v[8:9], v[106:107], v[12:13], v[8:9] op_sel_hi:[0,1,1]
	v_lshlrev_b32_e32 v12, 16, v34
	v_and_b32_e32 v13, 0xffff0000, v34
	v_pk_fma_f32 v[8:9], v[104:105], v[12:13], v[8:9] op_sel_hi:[0,1,1]
	v_lshlrev_b32_e32 v12, 16, v30
	v_and_b32_e32 v13, 0xffff0000, v30
	v_pk_fma_f32 v[8:9], v[102:103], v[12:13], v[8:9] op_sel_hi:[0,1,1]
	v_lshlrev_b32_e32 v12, 16, v26
	v_and_b32_e32 v13, 0xffff0000, v26
	v_pk_fma_f32 v[8:9], v[100:101], v[12:13], v[8:9] op_sel_hi:[0,1,1]
	v_lshlrev_b32_e32 v12, 16, v42
	v_and_b32_e32 v13, 0xffff0000, v42
	v_pk_fma_f32 v[8:9], v[96:97], v[12:13], v[8:9] op_sel_hi:[0,1,1]
	v_pk_fma_f32 v[4:5], v[98:99], v[8:9], v[4:5] op_sel_hi:[0,1,1] neg_lo:[0,0,1] neg_hi:[0,0,1]
	v_cvt_pk_bf16_f32 v2, v4, v5
	v_lshlrev_b32_e32 v4, 16, v51
	v_and_b32_e32 v5, 0xffff0000, v51
	v_lshlrev_b32_e32 v8, 16, v55
	v_and_b32_e32 v9, 0xffff0000, v55
	v_pk_add_f32 v[32:33], v[4:5], 0 op_sel_hi:[1,0]
	v_lshlrev_b32_e32 v12, 16, v59
	v_and_b32_e32 v13, 0xffff0000, v59
	v_pk_fma_f32 v[8:9], v[138:139], v[8:9], v[32:33] op_sel_hi:[0,1,1]
	v_lshlrev_b32_e32 v16, 16, v63
	v_and_b32_e32 v17, 0xffff0000, v63
	v_pk_fma_f32 v[8:9], v[140:141], v[12:13], v[8:9] op_sel_hi:[0,1,1]
	v_lshlrev_b32_e32 v20, 16, v67
	v_and_b32_e32 v21, 0xffff0000, v67
	v_pk_fma_f32 v[8:9], v[142:143], v[16:17], v[8:9] op_sel_hi:[0,1,1]
	v_lshlrev_b32_e32 v24, 16, v71
	v_and_b32_e32 v25, 0xffff0000, v71
	v_pk_fma_f32 v[8:9], v[144:145], v[20:21], v[8:9] op_sel_hi:[0,1,1]
	v_lshlrev_b32_e32 v28, 16, v75
	v_and_b32_e32 v29, 0xffff0000, v75
	v_pk_fma_f32 v[8:9], v[146:147], v[24:25], v[8:9] op_sel_hi:[0,1,1]
	v_pk_fma_f32 v[8:9], v[148:149], v[28:29], v[8:9] op_sel_hi:[0,1,1]
	v_lshlrev_b32_e32 v156, 16, v111
	v_and_b32_e32 v157, 0xffff0000, v111
	v_pk_fma_f32 v[8:9], v[136:137], v[154:155], v[8:9] op_sel_hi:[0,1,1]
	v_lshlrev_b32_e32 v118, 16, v119
	v_and_b32_e32 v119, 0xffff0000, v119
	v_pk_fma_f32 v[8:9], v[152:153], v[156:157], v[8:9] op_sel_hi:[0,1,1]
	v_pk_fma_f32 v[8:9], v[110:111], v[118:119], v[8:9] op_sel_hi:[0,1,1]
	v_pk_fma_f32 v[8:9], v[114:115], v[120:121], v[8:9] op_sel_hi:[0,1,1]
	v_lshlrev_b32_e32 v12, 16, v79
	v_and_b32_e32 v13, 0xffff0000, v79
	v_pk_fma_f32 v[8:9], v[106:107], v[12:13], v[8:9] op_sel_hi:[0,1,1]
	v_lshlrev_b32_e32 v12, 16, v83
	v_and_b32_e32 v13, 0xffff0000, v83
	v_pk_fma_f32 v[8:9], v[104:105], v[12:13], v[8:9] op_sel_hi:[0,1,1]
	v_lshlrev_b32_e32 v12, 16, v87
	v_and_b32_e32 v13, 0xffff0000, v87
	v_pk_fma_f32 v[8:9], v[102:103], v[12:13], v[8:9] op_sel_hi:[0,1,1]
	v_lshlrev_b32_e32 v12, 16, v91
	v_and_b32_e32 v13, 0xffff0000, v91
	v_pk_fma_f32 v[8:9], v[100:101], v[12:13], v[8:9] op_sel_hi:[0,1,1]
	v_lshlrev_b32_e32 v12, 16, v95
	v_and_b32_e32 v13, 0xffff0000, v95
	v_pk_fma_f32 v[8:9], v[96:97], v[12:13], v[8:9] op_sel_hi:[0,1,1]
	v_pk_fma_f32 v[4:5], v[98:99], v[8:9], v[4:5] op_sel_hi:[0,1,1] neg_lo:[0,0,1] neg_hi:[0,0,1]
	v_cvt_pk_bf16_f32 v51, v4, v5
	v_lshlrev_b32_e32 v4, 16, v47
	v_and_b32_e32 v5, 0xffff0000, v47
	v_lshlrev_b32_e32 v8, 16, v3
	v_and_b32_e32 v9, 0xffff0000, v3
	v_lshlrev_b32_e32 v12, 16, v15
	v_and_b32_e32 v13, 0xffff0000, v15
	v_lshlrev_b32_e32 v14, 16, v19
	v_and_b32_e32 v15, 0xffff0000, v19
	v_pk_add_f32 v[18:19], v[4:5], 0 op_sel_hi:[1,0]
	v_lshlrev_b32_e32 v6, 16, v7
	v_and_b32_e32 v7, 0xffff0000, v7
	v_pk_fma_f32 v[8:9], v[138:139], v[8:9], v[18:19] op_sel_hi:[0,1,1]
	v_lshlrev_b32_e32 v10, 16, v11
	v_and_b32_e32 v11, 0xffff0000, v11
	v_pk_fma_f32 v[6:7], v[140:141], v[6:7], v[8:9] op_sel_hi:[0,1,1]
	v_pk_fma_f32 v[6:7], v[142:143], v[10:11], v[6:7] op_sel_hi:[0,1,1]
	v_pk_fma_f32 v[6:7], v[144:145], v[12:13], v[6:7] op_sel_hi:[0,1,1]
	v_lshlrev_b32_e32 v16, 16, v23
	v_and_b32_e32 v17, 0xffff0000, v23
	v_pk_fma_f32 v[6:7], v[146:147], v[14:15], v[6:7] op_sel_hi:[0,1,1]
	v_pk_fma_f32 v[6:7], v[148:149], v[16:17], v[6:7] op_sel_hi:[0,1,1]
	v_lshlrev_b32_e32 v108, 16, v107
	v_and_b32_e32 v109, 0xffff0000, v107
	v_pk_fma_f32 v[6:7], v[136:137], v[150:151], v[6:7] op_sel_hi:[0,1,1]
	v_lshlrev_b32_e32 v112, 16, v115
	v_and_b32_e32 v113, 0xffff0000, v115
	v_pk_fma_f32 v[6:7], v[152:153], v[108:109], v[6:7] op_sel_hi:[0,1,1]
	v_pk_fma_f32 v[6:7], v[110:111], v[112:113], v[6:7] op_sel_hi:[0,1,1]
	v_pk_fma_f32 v[6:7], v[114:115], v[116:117], v[6:7] op_sel_hi:[0,1,1]
	v_lshlrev_b32_e32 v8, 16, v39
	v_and_b32_e32 v9, 0xffff0000, v39
	v_pk_fma_f32 v[6:7], v[106:107], v[8:9], v[6:7] op_sel_hi:[0,1,1]
	v_lshlrev_b32_e32 v8, 16, v35
	v_and_b32_e32 v9, 0xffff0000, v35
	v_pk_fma_f32 v[6:7], v[104:105], v[8:9], v[6:7] op_sel_hi:[0,1,1]
	v_lshlrev_b32_e32 v8, 16, v31
	v_and_b32_e32 v9, 0xffff0000, v31
	v_pk_fma_f32 v[6:7], v[102:103], v[8:9], v[6:7] op_sel_hi:[0,1,1]
	v_lshlrev_b32_e32 v8, 16, v27
	v_and_b32_e32 v9, 0xffff0000, v27
	v_pk_fma_f32 v[6:7], v[100:101], v[8:9], v[6:7] op_sel_hi:[0,1,1]
	v_lshlrev_b32_e32 v8, 16, v43
	v_and_b32_e32 v9, 0xffff0000, v43
	s_movk_i32 s22, 0x3fff
	v_pk_fma_f32 v[6:7], v[96:97], v[8:9], v[6:7] op_sel_hi:[0,1,1]
	v_pk_fma_f32 v[4:5], v[98:99], v[6:7], v[4:5] op_sel_hi:[0,1,1] neg_lo:[0,0,1] neg_hi:[0,0,1]
	v_cmp_lt_i32_e32 vcc, s22, v128
	v_cvt_pk_bf16_f32 v3, v4, v5
	global_store_dwordx4 v[132:133], v[48:51], off offset:-16 sc1
	global_store_dwordx4 v[132:133], v[0:3], off sc1
	v_lshl_add_u64 v[132:133], v[132:133], 0, s[30:31]
	s_or_b64 s[50:51], vcc, s[50:51]
	s_andn2_b64 exec, exec, s[50:51]
	s_cbranch_execnz .LBB0_233

.LBB0_514:
	v_and_b32_e32 v0, 0x1fff, v64
	v_cmp_ne_u32_e32 vcc, s18, v0
	v_lshl_add_u64 v[20:21], s[66:67], 0, v[76:77]
	v_mov_b32_e32 v1, s49
	v_cndmask_b32_e64 v0, 0, 1, vcc
	global_load_dwordx4 v[44:47], v[20:21], off
	global_load_dwordx4 v[40:43], v[20:21], off offset:16
	v_lshl_add_u64 v[0:1], v[64:65], 0, v[0:1]
	s_mov_b64 s[8:9], 0x2000000
	v_lshlrev_b64 v[0:1], 11, v[0:1]
	v_lshl_add_u64 v[2:3], v[20:21], 0, s[8:9]
	v_lshl_add_u64 v[0:1], v[72:73], 0, v[0:1]
	global_load_dwordx4 v[12:15], v[2:3], off offset:16
	global_load_dwordx4 v[52:55], v[0:1], off
	global_load_dwordx4 v[48:51], v[0:1], off offset:16
	global_load_dwordx4 v[16:19], v[66:67], off
	global_load_dwordx4 v[8:11], v[66:67], off offset:16
	global_load_dwordx4 v[4:7], v[66:67], off offset:32
	s_nop 0
	global_load_dwordx4 v[0:3], v[66:67], off offset:48
	s_brev_b32 s0, 64
	v_add_co_u32_e32 v20, vcc, s0, v20
	v_lshl_add_u64 v[24:25], s[66:67], 0, v[78:79]
	s_nop 0
	v_addc_co_u32_e32 v21, vcc, 0, v21, vcc
	global_load_dwordx4 v[20:23], v[20:21], off
	v_lshl_add_u64 v[26:27], v[24:25], 0, s[8:9]
	v_add_co_u32_e32 v24, vcc, s0, v24
	global_load_dwordx4 v[28:31], v[26:27], off offset:16
	s_nop 0
	v_addc_co_u32_e32 v25, vcc, 0, v25, vcc
	global_load_dwordx4 v[24:27], v[24:25], off
	s_nop 0
	global_load_dwordx4 v[36:39], v[68:69], off
	global_load_dwordx4 v[32:35], v[68:69], off offset:16
	global_load_dwordx4 v[56:59], v[68:69], off offset:32
	global_load_dwordx4 v[60:63], v[68:69], off offset:48
	s_waitcnt vmcnt(15)
	v_lshlrev_b32_e32 v121, 16, v47
	v_and_b32_e32 v146, 0xffff0000, v47
	v_lshlrev_b32_e32 v125, 16, v46
	s_waitcnt vmcnt(12)
	v_and_b32_e32 v47, 0xffff0000, v52
	v_and_b32_e32 v123, 0xffff0000, v46
	v_lshlrev_b32_e32 v46, 16, v52
	s_waitcnt vmcnt(10)
	v_mul_f32_e32 v92, v17, v47
	v_lshlrev_b32_e32 v52, 16, v53
	v_mul_f32_e32 v46, v16, v46
	v_mul_f32_e32 v47, v92, v92
	v_and_b32_e32 v53, 0xffff0000, v53
	v_mul_f32_e32 v93, v18, v52
	v_fmac_f32_e32 v47, v46, v46
	v_lshlrev_b32_e32 v80, 16, v54
	v_mul_f32_e32 v94, v19, v53
	v_fmac_f32_e32 v47, v93, v93
	v_and_b32_e32 v54, 0xffff0000, v54
	s_waitcnt vmcnt(9)
	v_mul_f32_e32 v95, v8, v80
	v_fmac_f32_e32 v47, v94, v94
	v_lshlrev_b32_e32 v82, 16, v55
	v_mul_f32_e32 v96, v9, v54
	v_fmac_f32_e32 v47, v95, v95
	v_and_b32_e32 v55, 0xffff0000, v55
	v_mul_f32_e32 v97, v10, v82
	v_fmac_f32_e32 v47, v96, v96
	v_lshlrev_b32_e32 v83, 16, v48
	v_mul_f32_e32 v98, v11, v55
	v_fmac_f32_e32 v47, v97, v97
	v_lshlrev_b32_e32 v119, 16, v40
	v_and_b32_e32 v117, 0xffff0000, v40
	v_lshlrev_b32_e32 v115, 16, v41
	v_and_b32_e32 v111, 0xffff0000, v41
	v_and_b32_e32 v48, 0xffff0000, v48
	v_lshlrev_b32_e32 v40, 16, v49
	v_and_b32_e32 v41, 0xffff0000, v49
	s_waitcnt vmcnt(8)
	v_mul_f32_e32 v100, v4, v83
	v_fmac_f32_e32 v47, v98, v98
	v_mul_f32_e32 v101, v5, v48
	v_pk_mul_f32 v[90:91], v[6:7], v[40:41]
	v_fmac_f32_e32 v47, v100, v100
	v_lshlrev_b32_e32 v109, 16, v42
	v_and_b32_e32 v105, 0xffff0000, v42
	v_lshlrev_b32_e32 v99, 16, v43
	v_and_b32_e32 v85, 0xffff0000, v43
	v_lshlrev_b32_e32 v42, 16, v50
	v_and_b32_e32 v43, 0xffff0000, v50
	v_pk_mul_f32 v[40:41], v[90:91], v[90:91]
	v_fmac_f32_e32 v47, v101, v101
	s_waitcnt vmcnt(7)
	v_pk_mul_f32 v[88:89], v[0:1], v[42:43]
	v_add_f32_e32 v40, v47, v40
	v_lshlrev_b32_e32 v145, 16, v44
	v_and_b32_e32 v144, 0xffff0000, v44
	v_lshlrev_b32_e32 v143, 16, v45
	v_and_b32_e32 v142, 0xffff0000, v45
	v_lshlrev_b32_e32 v44, 16, v51
	v_and_b32_e32 v45, 0xffff0000, v51
	v_pk_mul_f32 v[42:43], v[88:89], v[88:89]
	v_add_f32_e32 v40, v40, v41
	v_pk_mul_f32 v[86:87], v[2:3], v[44:45]
	v_add_f32_e32 v40, v40, v42
	v_pk_mul_f32 v[44:45], v[86:87], v[86:87]
	v_add_f32_e32 v40, v40, v43
	v_add_f32_e32 v40, v40, v44
	v_add_f32_e32 v40, v40, v45
	s_waitcnt vmcnt(4)
	v_lshlrev_b32_e32 v162, 16, v24
	v_lshlrev_b32_e32 v163, 16, v20
	v_add_f32_dpp v40, v40, v40 quad_perm:[1,0,3,2] row_mask:0xf bank_mask:0xf bound_ctrl:1
	v_and_b32_e32 v165, 0xffff0000, v20
	v_and_b32_e32 v164, 0xffff0000, v24
	v_add_f32_dpp v40, v40, v40 quad_perm:[2,3,0,1] row_mask:0xf bank_mask:0xf bound_ctrl:1
	v_max_f32_e32 v40, 0x179abe15, v40
	v_rsq_f32_e32 v147, v40
	v_lshlrev_b32_e32 v166, 16, v25
	v_mov_b32_e32 v190, v17
	v_mov_b32_e32 v212, v163
	v_mul_f32_e32 v84, v46, v147
	global_load_dwordx4 v[40:43], v[70:71], off offset:48
	global_load_dwordx4 v[44:47], v[70:71], off offset:32
	global_load_dwordx4 v[48:51], v[70:71], off offset:16
	global_load_dwordx4 v[52:55], v[70:71], off
	v_mul_f32_e32 v110, v98, v147
	v_mul_f32_e32 v98, v90, v147
	v_mul_f32_e32 v90, v91, v147
	v_add_f32_e32 v91, -1.0, v162
	v_mov_b32_e32 v17, v91
	s_waitcnt vmcnt(7)
	v_mov_b32_e32 v213, v36
	v_mul_f32_e32 v114, v92, v147
	v_mul_f32_e32 v116, v93, v147
	v_mul_f32_e32 v124, v97, v147
	v_lshlrev_b32_e32 v103, 16, v14
	v_and_b32_e32 v97, 0xffff0000, v14
	v_lshlrev_b32_e32 v93, 16, v15
	v_lshlrev_b32_e32 v92, 16, v31
	v_and_b32_e32 v15, 0xffff0000, v15
	v_and_b32_e32 v14, 0xffff0000, v31
	v_lshlrev_b32_e32 v167, 16, v21
	v_add_f32_e32 v191, -1.0, v164
	v_add_f32_e32 v176, -1.0, v166
	v_mov_b32_e32 v208, v165
	v_mov_b32_e32 v209, v37
	v_pk_mul_f32 v[36:37], v[16:17], v[212:213]
	v_mul_f32_e32 v118, v94, v147
	v_mul_f32_e32 v120, v95, v147
	v_mul_f32_e32 v122, v96, v147
	v_lshlrev_b32_e32 v102, 16, v30
	v_and_b32_e32 v96, 0xffff0000, v30
	v_add_f32_e32 v31, -1.0, v14
	v_mov_b32_e32 v30, v3
	v_mov_b32_e32 v94, v15
	s_waitcnt vmcnt(4)
	v_mov_b32_e32 v95, v63
	v_add_f32_e32 v3, -1.0, v92
	v_mov_b32_e32 v126, v93
	v_mov_b32_e32 v127, v62
	v_and_b32_e32 v21, 0xffff0000, v21
	v_and_b32_e32 v20, 0xffff0000, v25
	v_lshlrev_b32_e32 v24, 16, v26
	v_mov_b32_e32 v192, v19
	v_mov_b32_e32 v19, v176
	v_mov_b32_e32 v206, v167
	v_mov_b32_e32 v207, v38
	v_pk_mul_f32 v[210:211], v[190:191], v[208:209]
	v_mul_f32_e32 v91, v36, v36
	v_lshlrev_b32_e32 v80, 16, v29
	v_mul_f32_e32 v108, v100, v147
	v_mul_f32_e32 v104, v101, v147
	v_pk_mul_f32 v[100:101], v[30:31], v[94:95]
	v_pk_mul_f32 v[62:63], v[2:3], v[126:127]
	v_lshlrev_b32_e32 v25, 16, v22
	v_add_f32_e32 v193, -1.0, v20
	v_add_f32_e32 v178, -1.0, v24
	v_mov_b32_e32 v202, v21
	v_mov_b32_e32 v203, v39
	v_pk_mul_f32 v[38:39], v[18:19], v[206:207]
	v_fmac_f32_e32 v91, v210, v210
	v_lshlrev_b32_e32 v81, 16, v13
	v_and_b32_e32 v107, 0xffff0000, v13
	v_and_b32_e32 v106, 0xffff0000, v29
	v_add_f32_e32 v13, -1.0, v80
	v_add_f32_e32 v29, -1.0, v102
	v_mov_b32_e32 v132, v62
	v_mov_b32_e32 v133, v100
	v_and_b32_e32 v169, 0xffff0000, v22
	v_and_b32_e32 v168, 0xffff0000, v26
	v_mov_b32_e32 v194, v9
	v_mov_b32_e32 v9, v178
	v_mov_b32_e32 v200, v25
	v_mov_b32_e32 v201, v32
	v_pk_mul_f32 v[204:205], v[192:193], v[202:203]
	v_fmac_f32_e32 v91, v38, v38
	v_and_b32_e32 v83, 0xffff0000, v12
	v_and_b32_e32 v82, 0xffff0000, v28
	v_add_f32_e32 v129, -1.0, v96
	v_pk_mul_f32 v[148:149], v[132:133], v[132:133]
	v_mov_b32_e32 v128, v1
	v_mov_b32_e32 v132, v97
	v_mov_b32_e32 v133, v61
	v_mov_b32_e32 v1, v29
	v_mov_b32_e32 v136, v103
	v_mov_b32_e32 v137, v60
	v_mov_b32_e32 v130, v7
	v_mov_b32_e32 v7, v13
	v_lshlrev_b32_e32 v13, 16, v12
	v_lshlrev_b32_e32 v12, 16, v28
	v_lshlrev_b32_e32 v171, 16, v23
	v_lshlrev_b32_e32 v170, 16, v27
	v_add_f32_e32 v195, -1.0, v168
	v_mov_b32_e32 v196, v169
	v_mov_b32_e32 v197, v33
	v_pk_mul_f32 v[32:33], v[8:9], v[200:201]
	v_fmac_f32_e32 v91, v204, v204
	v_add_f32_e32 v113, -1.0, v82
	v_pk_mul_f32 v[134:135], v[128:129], v[132:133]
	v_pk_mul_f32 v[60:61], v[0:1], v[136:137]
	v_mov_b32_e32 v112, v5
	v_mov_b32_e32 v156, v83
	v_mov_b32_e32 v157, v57
	v_add_f32_e32 v5, -1.0, v12
	v_mov_b32_e32 v28, v13
	v_mov_b32_e32 v29, v56
	v_add_f32_e32 v173, -1.0, v170
	v_mov_b32_e32 v172, v10
	v_mov_b32_e32 v174, v171
	v_mov_b32_e32 v175, v34
	v_and_b32_e32 v23, 0xffff0000, v23
	v_and_b32_e32 v22, 0xffff0000, v27
	v_pk_mul_f32 v[198:199], v[194:195], v[196:197]
	v_fmac_f32_e32 v91, v32, v32
	v_mov_b32_e32 v138, v60
	v_mov_b32_e32 v139, v134
	v_pk_mul_f32 v[158:159], v[112:113], v[156:157]
	v_pk_mul_f32 v[56:57], v[4:5], v[28:29]
	v_pk_mul_f32 v[188:189], v[172:173], v[174:175]
	v_add_f32_e32 v27, -1.0, v22
	v_mov_b32_e32 v26, v11
	v_mov_b32_e32 v34, v23
	v_fmac_f32_e32 v91, v198, v198
	v_add_f32_e32 v131, -1.0, v106
	v_pk_mul_f32 v[150:151], v[138:139], v[138:139]
	v_mov_b32_e32 v138, v107
	v_mov_b32_e32 v139, v59
	v_mov_b32_e32 v152, v81
	v_mov_b32_e32 v153, v58
	v_mov_b32_e32 v160, v56
	v_mov_b32_e32 v161, v158
	v_pk_mul_f32 v[10:11], v[26:27], v[34:35]
	v_fmac_f32_e32 v91, v188, v188
	v_pk_mul_f32 v[140:141], v[130:131], v[138:139]
	v_pk_mul_f32 v[58:59], v[6:7], v[152:153]
	v_pk_mul_f32 v[160:161], v[160:161], v[160:161]
	v_fmac_f32_e32 v91, v10, v10
	v_mov_b32_e32 v154, v58
	v_mov_b32_e32 v155, v140
	v_add_f32_e32 v91, v91, v160
	v_pk_mul_f32 v[154:155], v[154:155], v[154:155]
	v_add_f32_e32 v91, v91, v161
	v_add_f32_e32 v91, v91, v154
	v_add_f32_e32 v91, v91, v155
	v_add_f32_e32 v91, v91, v150
	v_add_f32_e32 v91, v91, v151
	v_add_f32_e32 v91, v91, v148
	v_add_f32_e32 v91, v91, v149
	v_pk_fma_f32 v[26:27], v[26:27], v[34:35], s[26:27]
	v_pk_fma_f32 v[16:17], v[16:17], v[212:213], s[26:27]
	v_add_f32_dpp v91, v91, v91 quad_perm:[1,0,3,2] row_mask:0xf bank_mask:0xf bound_ctrl:1
	v_pk_fma_f32 v[18:19], v[18:19], v[206:207], s[26:27]
	v_pk_fma_f32 v[34:35], v[192:193], v[202:203], s[26:27]
	v_add_f32_dpp v91, v91, v91 quad_perm:[2,3,0,1] row_mask:0xf bank_mask:0xf bound_ctrl:1
	v_max_f32_e32 v91, 0x179abe15, v91
	v_rsq_f32_e32 v178, v91
	v_pk_fma_f32 v[8:9], v[8:9], v[200:201], s[26:27]
	v_pk_fma_f32 v[4:5], v[4:5], v[28:29], s[26:27]
	v_mul_f32_e32 v150, v87, v147
	v_pk_mul_f32 v[10:11], v[10:11], v[178:179]
	v_pk_fma_f32 v[6:7], v[6:7], v[152:153], s[26:27]
	v_mov_b32_e32 v11, v27
	v_pk_mul_f32 v[10:11], v[10:11], v[22:23]
	v_pk_mul_f32 v[22:23], v[36:37], v[178:179]
	v_pk_fma_f32 v[26:27], v[190:191], v[208:209], s[26:27]
	v_mov_b32_e32 v23, v17
	v_pk_mul_f32 v[16:17], v[22:23], v[162:163]
	v_mul_f32_e32 v87, v11, v146
	v_mul_f32_e32 v22, v17, v145
	s_waitcnt vmcnt(0)
	v_fma_f32 v36, v52, v22, 0
	v_pk_mul_f32 v[22:23], v[210:211], v[178:179]
	v_pk_fma_f32 v[0:1], v[0:1], v[136:137], s[26:27]
	v_mov_b32_e32 v23, v27
	v_pk_mul_f32 v[22:23], v[22:23], v[164:165]
	v_mul_f32_e32 v88, v88, v147
	v_mul_f32_e32 v26, v23, v144
	v_fmac_f32_e32 v36, v53, v26
	v_pk_mul_f32 v[26:27], v[38:39], v[178:179]
	v_mul_f32_e32 v148, v89, v147
	v_mov_b32_e32 v27, v19
	v_pk_mul_f32 v[18:19], v[26:27], v[166:167]
	v_pk_fma_f32 v[2:3], v[2:3], v[126:127], s[26:27]
	v_mul_f32_e32 v26, v19, v143
	v_fmac_f32_e32 v36, v54, v26
	v_pk_mul_f32 v[26:27], v[204:205], v[178:179]
	v_mul_f32_e32 v86, v86, v147
	v_mov_b32_e32 v27, v35
	v_pk_mul_f32 v[20:21], v[26:27], v[20:21]
	s_nop 0
	v_mul_f32_e32 v26, v21, v142
	v_fmac_f32_e32 v36, v55, v26
	v_pk_mul_f32 v[26:27], v[32:33], v[178:179]
	v_pk_fma_f32 v[32:33], v[172:173], v[174:175], s[26:27]
	v_mov_b32_e32 v27, v9
	v_pk_mul_f32 v[8:9], v[26:27], v[24:25]
	v_pk_fma_f32 v[26:27], v[194:195], v[196:197], s[26:27]
	v_mul_f32_e32 v24, v9, v125
	v_fmac_f32_e32 v36, v48, v24
	v_pk_mul_f32 v[24:25], v[198:199], v[178:179]
	s_nop 0
	v_mov_b32_e32 v25, v27
	v_pk_mul_f32 v[24:25], v[24:25], v[168:169]
	s_nop 0
	v_mul_f32_e32 v26, v25, v123
	v_fmac_f32_e32 v36, v49, v26
	v_pk_mul_f32 v[26:27], v[188:189], v[178:179]
	s_nop 0
	v_mov_b32_e32 v27, v33
	v_pk_mul_f32 v[26:27], v[26:27], v[170:171]
	s_nop 0
	v_mul_f32_e32 v32, v27, v121
	v_fmac_f32_e32 v36, v50, v32
	v_pk_mul_f32 v[32:33], v[56:57], v[178:179]
	v_fmac_f32_e32 v36, v51, v87
	v_mov_b32_e32 v33, v5
	v_pk_mul_f32 v[4:5], v[32:33], v[12:13]
	s_nop 0
	v_mul_f32_e32 v12, v5, v119
	v_fmac_f32_e32 v36, v44, v12
	v_pk_fma_f32 v[12:13], v[16:17], v[84:85], 0 op_sel_hi:[1,0,0]
	s_nop 0
	v_pk_fma_f32 v[12:13], v[114:115], v[22:23], v[12:13] op_sel_hi:[0,1,1]
	v_pk_fma_f32 v[12:13], v[116:117], v[18:19], v[12:13] op_sel_hi:[0,1,1]
	v_pk_fma_f32 v[12:13], v[118:119], v[20:21], v[12:13] op_sel_hi:[0,1,1]
	v_pk_fma_f32 v[8:9], v[120:121], v[8:9], v[12:13] op_sel_hi:[0,1,1]
	v_pk_fma_f32 v[8:9], v[122:123], v[24:25], v[8:9] op_sel_hi:[0,1,1]
	v_pk_fma_f32 v[8:9], v[124:125], v[26:27], v[8:9] op_sel_hi:[0,1,1]
	v_pk_fma_f32 v[8:9], v[110:111], v[10:11], v[8:9] op_sel_hi:[0,1,1]
	v_pk_fma_f32 v[4:5], v[108:109], v[4:5], v[8:9] op_sel_hi:[0,1,1]
	v_pk_mul_f32 v[8:9], v[158:159], v[178:179]
	v_pk_fma_f32 v[10:11], v[112:113], v[156:157], s[26:27]
	s_nop 0
	v_mov_b32_e32 v9, v11
	v_pk_mul_f32 v[8:9], v[8:9], v[82:83]
	s_nop 0
	v_pk_fma_f32 v[4:5], v[104:105], v[8:9], v[4:5] op_sel_hi:[0,1,1]
	v_mul_f32_e32 v8, v9, v117
	v_fmac_f32_e32 v36, v45, v8
	v_pk_mul_f32 v[8:9], v[58:59], v[178:179]
	s_nop 0
	v_mov_b32_e32 v9, v7
	v_pk_mul_f32 v[6:7], v[8:9], v[80:81]
	v_pk_fma_f32 v[8:9], v[130:131], v[138:139], s[26:27]
	v_pk_fma_f32 v[4:5], v[98:99], v[6:7], v[4:5] op_sel_hi:[0,1,1]
	v_mul_f32_e32 v6, v7, v115
	v_fmac_f32_e32 v36, v46, v6
	v_pk_mul_f32 v[6:7], v[140:141], v[178:179]
	s_nop 0
	v_mov_b32_e32 v7, v9
	v_pk_mul_f32 v[6:7], v[6:7], v[106:107]
	s_nop 0
	v_pk_fma_f32 v[4:5], v[90:91], v[6:7], v[4:5] op_sel_hi:[0,1,1]
	v_mul_f32_e32 v6, v7, v111
	v_fmac_f32_e32 v36, v47, v6
	v_pk_mul_f32 v[6:7], v[60:61], v[178:179]
	s_nop 0
	v_mov_b32_e32 v7, v1
	v_pk_mul_f32 v[0:1], v[6:7], v[102:103]
	v_pk_fma_f32 v[6:7], v[128:129], v[132:133], s[26:27]
	v_pk_fma_f32 v[4:5], v[88:89], v[0:1], v[4:5] op_sel_hi:[0,1,1]
	v_mul_f32_e32 v0, v1, v109
	v_fmac_f32_e32 v36, v40, v0
	v_pk_mul_f32 v[0:1], v[134:135], v[178:179]
	s_nop 0
	v_mov_b32_e32 v1, v7
	v_pk_mul_f32 v[0:1], v[0:1], v[96:97]
	s_nop 0
	v_pk_fma_f32 v[4:5], v[148:149], v[0:1], v[4:5] op_sel_hi:[0,1,1]
	v_mul_f32_e32 v0, v1, v105
	v_fmac_f32_e32 v36, v41, v0
	v_pk_mul_f32 v[0:1], v[62:63], v[178:179]
	s_nop 0
	v_mov_b32_e32 v1, v3
	v_pk_mul_f32 v[0:1], v[0:1], v[92:93]
	s_nop 0
	v_pk_fma_f32 v[2:3], v[86:87], v[0:1], v[4:5] op_sel_hi:[0,1,1]
	v_mul_f32_e32 v0, v1, v99
	v_fmac_f32_e32 v36, v42, v0
	v_pk_mul_f32 v[0:1], v[100:101], v[178:179]
	v_pk_fma_f32 v[4:5], v[30:31], v[94:95], s[26:27]
	s_nop 0
	v_mov_b32_e32 v1, v5
	v_pk_mul_f32 v[0:1], v[0:1], v[14:15]
	v_mov_b32_e32 v5, 0
	v_pk_fma_f32 v[2:3], v[150:151], v[0:1], v[2:3] op_sel_hi:[0,1,1]
	v_mul_f32_e32 v0, v1, v85
	v_fmac_f32_e32 v36, v43, v0
	v_mov_b32_e32 v0, v177
	v_mov_b32_e32 v1, v177
	v_add_f32_dpp v4, v36, v36 quad_perm:[1,0,3,2] row_mask:0xf bank_mask:0xf bound_ctrl:1
	v_mov_b32_dpp v0, v2 quad_perm:[1,0,3,2] row_mask:0xf bank_mask:0xf
	v_mov_b32_dpp v1, v3 quad_perm:[1,0,3,2] row_mask:0xf bank_mask:0xf
	v_pk_add_f32 v[0:1], v[2:3], v[0:1]
	v_mov_b32_e32 v2, 0
	v_mov_b32_e32 v3, 0
	v_mov_b32_dpp v5, v4 quad_perm:[2,3,0,1] row_mask:0xf bank_mask:0xf
	v_mov_b32_dpp v2, v0 quad_perm:[2,3,0,1] row_mask:0xf bank_mask:0xf
	v_mov_b32_dpp v3, v1 quad_perm:[2,3,0,1] row_mask:0xf bank_mask:0xf
	s_and_saveexec_b64 s[0:1], s[2:3]
	s_cbranch_execz .LBB0_513
	v_pk_add_f32 v[8:9], v[0:1], v[2:3]
	v_lshl_add_u64 v[6:7], s[66:67], 0, v[74:75]
	v_add_f32_e32 v3, v4, v5
	v_mov_b32_e32 v0, v178
	v_mov_b32_e32 v1, v8
	v_mov_b32_e32 v2, v9
	global_store_dwordx4 v[6:7], v[0:3], off sc1
	s_branch .LBB0_513

.LBB0_800:
	v_lshl_add_u64 v[24:25], s[66:67], 0, v[22:23]
	v_lshl_add_u64 v[26:27], v[24:25], 0, s[28:29]
	v_add_co_u32_e32 v24, vcc, s26, v24
	v_lshl_add_u64 v[4:5], s[66:67], 0, v[20:21]
	s_nop 0
	v_addc_co_u32_e32 v25, vcc, 0, v25, vcc
	global_load_dwordx4 v[0:3], v[4:5], off offset:-16
	s_nop 0
	global_load_dwordx4 v[4:7], v[4:5], off
	s_nop 0
	global_load_dwordx4 v[32:35], v[24:25], off
	global_load_dwordx4 v[36:39], v[26:27], off offset:16
	v_lshl_add_u64 v[24:25], s[66:67], 0, v[18:19]
	v_lshl_add_u64 v[26:27], v[24:25], 0, s[28:29]
	v_add_co_u32_e32 v24, vcc, s26, v24
	v_lshl_add_u64 v[80:81], s[66:67], 0, v[16:17]
	s_nop 0
	v_addc_co_u32_e32 v25, vcc, 0, v25, vcc
	global_load_dwordx4 v[40:43], v[24:25], off
	global_load_dwordx4 v[44:47], v[26:27], off offset:16
	global_load_dwordx4 v[48:51], v[10:11], off offset:48
	global_load_dwordx4 v[52:55], v[10:11], off offset:32
	global_load_dwordx4 v[56:59], v[10:11], off offset:16
	global_load_dwordx4 v[60:63], v[10:11], off
	global_load_dwordx4 v[64:67], v[12:13], off offset:48
	global_load_dwordx4 v[68:71], v[12:13], off offset:32
	global_load_dwordx4 v[72:75], v[12:13], off offset:16
	global_load_dwordx4 v[76:79], v[12:13], off
	s_nop 0
	global_load_dwordx2 v[80:81], v[80:81], off offset:8
	v_lshl_add_u64 v[16:17], v[16:17], 0, s[20:21]
	v_lshl_add_u64 v[18:19], v[18:19], 0, s[18:19]
	v_lshl_add_u64 v[20:21], v[20:21], 0, s[18:19]
	v_lshl_add_u64 v[22:23], v[22:23], 0, s[18:19]
	s_waitcnt vmcnt(14)
	v_lshlrev_b32_e32 v84, 16, v3
	s_waitcnt vmcnt(13)
	v_lshlrev_b32_e32 v82, 16, v7
	v_and_b32_e32 v83, 0xffff0000, v7
	s_waitcnt vmcnt(11)
	v_lshlrev_b32_e32 v24, 16, v39
	v_and_b32_e32 v25, 0xffff0000, v39
	v_and_b32_e32 v85, 0xffff0000, v3
	v_lshlrev_b32_e32 v28, 16, v35
	v_and_b32_e32 v29, 0xffff0000, v35
	v_lshlrev_b32_e32 v86, 16, v6
	s_waitcnt vmcnt(10)
	v_lshlrev_b32_e32 v30, 16, v43
	s_waitcnt vmcnt(9)
	v_lshlrev_b32_e32 v26, 16, v47
	v_and_b32_e32 v27, 0xffff0000, v47
	v_and_b32_e32 v31, 0xffff0000, v43
	v_and_b32_e32 v87, 0xffff0000, v6
	v_lshlrev_b32_e32 v6, 16, v38
	v_and_b32_e32 v7, 0xffff0000, v38
	v_lshlrev_b32_e32 v38, 16, v46
	v_and_b32_e32 v39, 0xffff0000, v46
	v_lshlrev_b32_e32 v46, 16, v2
	v_and_b32_e32 v47, 0xffff0000, v2
	v_lshlrev_b32_e32 v2, 16, v34
	v_and_b32_e32 v3, 0xffff0000, v34
	v_lshlrev_b32_e32 v34, 16, v42
	v_and_b32_e32 v35, 0xffff0000, v42
	v_lshlrev_b32_e32 v42, 16, v5
	v_and_b32_e32 v43, 0xffff0000, v5
	v_lshlrev_b32_e32 v88, 16, v37
	v_and_b32_e32 v89, 0xffff0000, v37
	v_lshlrev_b32_e32 v98, 16, v4
	v_and_b32_e32 v99, 0xffff0000, v4
	v_lshlrev_b32_e32 v4, 16, v36
	v_and_b32_e32 v5, 0xffff0000, v36
	v_lshlrev_b32_e32 v36, 16, v44
	v_and_b32_e32 v37, 0xffff0000, v44
	v_lshlrev_b32_e32 v44, 16, v0
	v_lshlrev_b32_e32 v90, 16, v45
	v_and_b32_e32 v91, 0xffff0000, v45
	v_and_b32_e32 v45, 0xffff0000, v0
	v_add_f32_e32 v9, 0, v44
	v_lshlrev_b32_e32 v92, 16, v1
	v_add_f32_e32 v9, v9, v45
	v_and_b32_e32 v93, 0xffff0000, v1
	v_add_f32_e32 v9, v9, v92
	v_add_f32_e32 v9, v9, v93
	v_add_f32_e32 v9, v9, v46
	v_add_f32_e32 v9, v9, v47
	v_add_f32_e32 v9, v9, v84
	v_add_f32_e32 v9, v9, v85
	v_add_f32_e32 v9, v9, v98
	v_add_f32_e32 v9, v9, v99
	v_add_f32_e32 v9, v9, v42
	v_add_f32_e32 v9, v9, v43
	v_add_f32_e32 v9, v9, v86
	v_add_f32_e32 v9, v9, v87
	v_add_f32_e32 v9, v9, v82
	v_add_f32_e32 v9, v9, v83
	v_lshlrev_b32_e32 v94, 16, v33
	v_and_b32_e32 v95, 0xffff0000, v33
	v_add_f32_dpp v9, v9, v9 quad_perm:[1,0,3,2] row_mask:0xf bank_mask:0xf bound_ctrl:1
	v_lshlrev_b32_e32 v0, 16, v32
	v_and_b32_e32 v1, 0xffff0000, v32
	v_add_f32_dpp v9, v9, v9 quad_perm:[2,3,0,1] row_mask:0xf bank_mask:0xf bound_ctrl:1
	v_lshlrev_b32_e32 v32, 16, v40
	v_and_b32_e32 v33, 0xffff0000, v40
	v_mul_f32_e32 v40, 0x3c800000, v9
	v_pk_add_f32 v[44:45], v[44:45], v[40:41] op_sel_hi:[1,0] neg_lo:[0,1] neg_hi:[0,1]
	v_pk_add_f32 v[92:93], v[92:93], v[40:41] op_sel_hi:[1,0] neg_lo:[0,1] neg_hi:[0,1]
	v_pk_mul_f32 v[100:101], v[44:45], v[44:45]
	v_pk_mul_f32 v[102:103], v[92:93], v[92:93]
	v_add_f32_e32 v9, v100, v101
	v_pk_add_f32 v[46:47], v[46:47], v[40:41] op_sel_hi:[1,0] neg_lo:[0,1] neg_hi:[0,1]
	v_add_f32_e32 v9, v102, v9
	v_pk_mul_f32 v[104:105], v[46:47], v[46:47]
	v_add_f32_e32 v9, v103, v9
	v_pk_add_f32 v[84:85], v[84:85], v[40:41] op_sel_hi:[1,0] neg_lo:[0,1] neg_hi:[0,1]
	v_add_f32_e32 v9, v104, v9
	v_pk_mul_f32 v[106:107], v[84:85], v[84:85]
	v_add_f32_e32 v9, v105, v9
	v_pk_add_f32 v[98:99], v[98:99], v[40:41] op_sel_hi:[1,0] neg_lo:[0,1] neg_hi:[0,1]
	v_add_f32_e32 v9, v106, v9
	v_pk_mul_f32 v[108:109], v[98:99], v[98:99]
	v_add_f32_e32 v9, v107, v9
	v_pk_add_f32 v[42:43], v[42:43], v[40:41] op_sel_hi:[1,0] neg_lo:[0,1] neg_hi:[0,1]
	v_add_f32_e32 v9, v108, v9
	v_pk_mul_f32 v[110:111], v[42:43], v[42:43]
	v_add_f32_e32 v9, v109, v9
	v_pk_add_f32 v[86:87], v[86:87], v[40:41] op_sel_hi:[1,0] neg_lo:[0,1] neg_hi:[0,1]
	v_add_f32_e32 v9, v110, v9
	v_pk_mul_f32 v[112:113], v[86:87], v[86:87]
	v_add_f32_e32 v9, v111, v9
	v_lshlrev_b32_e32 v96, 16, v41
	v_and_b32_e32 v97, 0xffff0000, v41
	v_pk_add_f32 v[40:41], v[82:83], v[40:41] op_sel_hi:[1,0] neg_lo:[0,1] neg_hi:[0,1]
	v_add_f32_e32 v9, v112, v9
	v_pk_mul_f32 v[82:83], v[40:41], v[40:41]
	v_add_f32_e32 v9, v113, v9
	v_add_f32_e32 v9, v82, v9
	v_add_f32_e32 v9, v83, v9
	v_mov_b32_e32 v82, 0x3a27c5ac
	s_nop 0
	v_add_f32_dpp v9, v9, v9 quad_perm:[1,0,3,2] row_mask:0xf bank_mask:0xf bound_ctrl:1
	s_nop 1
	v_add_f32_dpp v9, v9, v9 quad_perm:[2,3,0,1] row_mask:0xf bank_mask:0xf bound_ctrl:1
	v_fmamk_f32 v9, v9, 0x3c800000, v82
	v_cmp_gt_f32_e32 vcc, s22, v9
	v_mul_f32_e32 v82, 0x4b800000, v9
	s_nop 0
	v_cndmask_b32_e32 v9, v9, v82, vcc
	v_rsq_f32_e32 v9, v9
	s_nop 0
	v_mul_f32_e32 v82, 0x45800000, v9
	v_cndmask_b32_e32 v82, v9, v82, vcc
	v_pk_mul_f32 v[44:45], v[44:45], v[82:83] op_sel_hi:[1,0]
	v_ashrrev_i32_e32 v9, 13, v8
	s_waitcnt vmcnt(1)
	v_pk_fma_f32 v[44:45], v[60:61], v[44:45], v[76:77]
	s_waitcnt vmcnt(0)
	v_pk_fma_f32 v[0:1], v[80:81], v[0:1], v[44:45] op_sel:[1,0,0]
	s_nop 0
	v_pk_mul_f32 v[0:1], v[0:1], v[32:33]
	v_pk_mul_f32 v[32:33], v[98:99], v[82:83] op_sel_hi:[1,0]
	s_nop 0
	v_pk_fma_f32 v[32:33], v[52:53], v[32:33], v[68:69]
	s_nop 0
	v_pk_fma_f32 v[4:5], v[80:81], v[4:5], v[32:33] op_sel:[1,0,0]
	s_nop 0
	v_pk_mul_f32 v[32:33], v[4:5], v[36:37]
	v_cvt_pk_bf16_f32 v4, v0, v1
	v_cvt_pk_bf16_f32 v0, v32, v33
	v_pk_mul_f32 v[32:33], v[92:93], v[82:83] op_sel_hi:[1,0]
	v_pk_mul_f32 v[36:37], v[42:43], v[82:83] op_sel_hi:[1,0]
	v_pk_fma_f32 v[32:33], v[62:63], v[32:33], v[78:79]
	v_pk_fma_f32 v[36:37], v[54:55], v[36:37], v[70:71]
	v_pk_fma_f32 v[32:33], v[80:81], v[94:95], v[32:33] op_sel:[1,0,0]
	v_pk_fma_f32 v[36:37], v[80:81], v[88:89], v[36:37] op_sel:[1,0,0]
	v_pk_mul_f32 v[32:33], v[32:33], v[96:97]
	v_pk_mul_f32 v[36:37], v[36:37], v[90:91]
	v_cvt_pk_bf16_f32 v5, v32, v33
	v_pk_mul_f32 v[32:33], v[46:47], v[82:83] op_sel_hi:[1,0]
	v_cvt_pk_bf16_f32 v1, v36, v37
	v_pk_fma_f32 v[32:33], v[56:57], v[32:33], v[72:73]
	s_nop 0
	v_pk_fma_f32 v[2:3], v[80:81], v[2:3], v[32:33] op_sel:[1,0,0]
	v_pk_mul_f32 v[32:33], v[86:87], v[82:83] op_sel_hi:[1,0]
	v_pk_mul_f32 v[2:3], v[2:3], v[34:35]
	v_pk_fma_f32 v[32:33], v[48:49], v[32:33], v[64:65]
	s_nop 0
	v_pk_fma_f32 v[6:7], v[80:81], v[6:7], v[32:33] op_sel:[1,0,0]
	s_nop 0
	v_pk_mul_f32 v[32:33], v[6:7], v[38:39]
	v_cvt_pk_bf16_f32 v6, v2, v3
	v_cvt_pk_bf16_f32 v2, v32, v33
	v_pk_mul_f32 v[32:33], v[84:85], v[82:83] op_sel_hi:[1,0]
	s_nop 0
	v_pk_fma_f32 v[32:33], v[58:59], v[32:33], v[74:75]
	s_nop 0
	v_pk_fma_f32 v[28:29], v[80:81], v[28:29], v[32:33] op_sel:[1,0,0]
	s_nop 0
	v_pk_mul_f32 v[28:29], v[28:29], v[30:31]
	v_pk_mul_f32 v[30:31], v[40:41], v[82:83] op_sel_hi:[1,0]
	v_cvt_pk_bf16_f32 v7, v28, v29
	v_pk_fma_f32 v[30:31], v[50:51], v[30:31], v[66:67]
	s_nop 0
	v_pk_fma_f32 v[24:25], v[80:81], v[24:25], v[30:31] op_sel:[1,0,0]
	s_nop 0
	v_pk_mul_f32 v[24:25], v[24:25], v[26:27]
	s_nop 0
	v_cvt_pk_bf16_f32 v3, v24, v25
	v_add3_u32 v24, v8, v9, 1
	v_ashrrev_i32_e32 v25, 31, v24
	v_add_u32_e32 v8, s86, v8
	v_lshlrev_b64 v[24:25], 11, v[24:25]
	v_cmp_lt_i32_e32 vcc, s23, v8
	v_lshl_add_u64 v[24:25], v[14:15], 0, v[24:25]
	s_or_b64 s[4:5], vcc, s[4:5]
	global_store_dwordx4 v[24:25], v[4:7], off sc1
	global_store_dwordx4 v[24:25], v[0:3], off offset:16 sc1
	s_andn2_b64 exec, exec, s[4:5]
	s_cbranch_execnz .LBB0_800

.LBB0_973:
	s_cmp_lg_u32 s31, 10
	s_cselect_b64 s[0:1], -1, 0
	s_or_b64 s[0:1], s[18:19], s[0:1]
	s_and_b64 vcc, exec, s[0:1]
	s_cbranch_vccnz .LBB0_975
	v_mul_f32_e32 v94, 0xbfb8aa3b, v94
	v_mul_f32_e32 v95, 0xbfb8aa3b, v95
	v_exp_f32_e32 v94, v94
	v_exp_f32_e32 v95, v95
	v_mul_f32_e32 v92, 0xbfb8aa3b, v92
	v_mul_f32_e32 v93, 0xbfb8aa3b, v93
	v_exp_f32_e32 v92, v92
	v_pk_add_f32 v[94:95], v[94:95], 1.0 op_sel_hi:[1,0]
	v_exp_f32_e32 v93, v93
	v_div_scale_f32 v97, s[0:1], v95, v95, 1.0
	v_rcp_f32_e32 v98, v97
	v_pk_add_f32 v[92:93], v[92:93], 1.0 op_sel_hi:[1,0]
	v_mul_f32_e32 v90, 0xbfb8aa3b, v90
	v_mul_f32_e32 v91, 0xbfb8aa3b, v91
	v_fma_f32 v99, -v97, v98, 1.0
	v_fmac_f32_e32 v98, v99, v98
	v_div_scale_f32 v99, vcc, 1.0, v95, 1.0
	v_mul_f32_e32 v100, v99, v98
	v_fma_f32 v101, -v97, v100, v99
	v_fmac_f32_e32 v100, v101, v98
	v_fma_f32 v97, -v97, v100, v99
	v_div_fmas_f32 v97, v97, v98, v100
	v_div_fixup_f32 v101, v97, v95, 1.0
	v_div_scale_f32 v95, s[0:1], v94, v94, 1.0
	v_rcp_f32_e32 v97, v95
	v_exp_f32_e32 v90, v90
	v_exp_f32_e32 v91, v91
	v_lshl_add_u32 v96, s30, 8, v153
	v_fma_f32 v98, -v95, v97, 1.0
	v_fmac_f32_e32 v97, v98, v97
	v_div_scale_f32 v98, vcc, 1.0, v94, 1.0
	v_mul_f32_e32 v99, v98, v97
	v_fma_f32 v100, -v95, v99, v98
	v_fmac_f32_e32 v99, v100, v97
	v_fma_f32 v95, -v95, v99, v98
	v_div_fmas_f32 v95, v95, v97, v99
	v_div_fixup_f32 v100, v95, v94, 1.0
	v_div_scale_f32 v94, s[0:1], v93, v93, 1.0
	v_rcp_f32_e32 v95, v94
	v_pk_add_f32 v[90:91], v[90:91], 1.0 op_sel_hi:[1,0]
	s_movk_i32 s4, 0xc0
	v_mul_f32_e32 v88, 0xbfb8aa3b, v88
	v_fma_f32 v97, -v94, v95, 1.0
	v_fmac_f32_e32 v95, v97, v95
	v_div_scale_f32 v97, vcc, 1.0, v93, 1.0
	v_mul_f32_e32 v98, v97, v95
	v_fma_f32 v99, -v94, v98, v97
	v_fmac_f32_e32 v98, v99, v95
	v_fma_f32 v94, -v94, v98, v97
	v_div_fmas_f32 v94, v94, v95, v98
	v_div_fixup_f32 v99, v94, v93, 1.0
	v_div_scale_f32 v93, s[0:1], v92, v92, 1.0
	v_rcp_f32_e32 v94, v93
	v_mul_f32_e32 v89, 0xbfb8aa3b, v89
	v_exp_f32_e32 v88, v88
	v_exp_f32_e32 v89, v89
	v_fma_f32 v95, -v93, v94, 1.0
	v_fmac_f32_e32 v94, v95, v94
	v_div_scale_f32 v95, vcc, 1.0, v92, 1.0
	v_mul_f32_e32 v97, v95, v94
	v_fma_f32 v98, -v93, v97, v95
	v_fmac_f32_e32 v97, v98, v94
	v_fma_f32 v93, -v93, v97, v95
	v_div_fmas_f32 v93, v93, v94, v97
	v_div_scale_f32 v94, s[0:1], v91, v91, 1.0
	v_rcp_f32_e32 v95, v94
	v_div_fixup_f32 v98, v93, v92, 1.0
	v_mad_i64_i32 v[92:93], s[0:1], v96, s4, v[156:157]
	v_fma_f32 v97, -v94, v95, 1.0
	v_fmac_f32_e32 v95, v97, v95
	v_div_scale_f32 v97, vcc, 1.0, v91, 1.0
	global_store_dwordx4 v[92:93], v[98:101], off sc1
	v_pk_add_f32 v[88:89], v[88:89], 1.0 op_sel_hi:[1,0]
	v_mul_f32_e32 v86, 0xbfb8aa3b, v86
	v_mul_f32_e32 v98, v97, v95
	v_fma_f32 v99, -v94, v98, v97
	v_fmac_f32_e32 v98, v99, v95
	v_fma_f32 v94, -v94, v98, v97
	v_div_fmas_f32 v94, v94, v95, v98
	v_div_fixup_f32 v91, v94, v91, 1.0
	v_div_scale_f32 v94, s[0:1], v90, v90, 1.0
	v_rcp_f32_e32 v95, v94
	v_mul_f32_e32 v87, 0xbfb8aa3b, v87
	v_exp_f32_e32 v86, v86
	v_exp_f32_e32 v87, v87
	v_fma_f32 v97, -v94, v95, 1.0
	v_fmac_f32_e32 v95, v97, v95
	v_div_scale_f32 v97, vcc, 1.0, v90, 1.0
	v_mul_f32_e32 v98, v97, v95
	v_fma_f32 v99, -v94, v98, v97
	v_fmac_f32_e32 v98, v99, v95
	v_fma_f32 v94, -v94, v98, v97
	v_div_fmas_f32 v94, v94, v95, v98
	v_div_fixup_f32 v90, v94, v90, 1.0
	v_div_scale_f32 v94, s[0:1], v89, v89, 1.0
	v_rcp_f32_e32 v95, v94
	v_pk_add_f32 v[86:87], v[86:87], 1.0 op_sel_hi:[1,0]
	v_mul_f32_e32 v84, 0xbfb8aa3b, v84
	v_mul_f32_e32 v85, 0xbfb8aa3b, v85
	v_fma_f32 v97, -v94, v95, 1.0
	v_fmac_f32_e32 v95, v97, v95
	v_div_scale_f32 v97, vcc, 1.0, v89, 1.0
	v_mul_f32_e32 v98, v97, v95
	v_fma_f32 v99, -v94, v98, v97
	v_fmac_f32_e32 v98, v99, v95
	v_fma_f32 v94, -v94, v98, v97
	v_div_fmas_f32 v94, v94, v95, v98
	v_div_fixup_f32 v89, v94, v89, 1.0
	v_div_scale_f32 v94, s[0:1], v88, v88, 1.0
	v_rcp_f32_e32 v95, v94
	v_exp_f32_e32 v84, v84
	v_exp_f32_e32 v85, v85
	v_mul_f32_e32 v82, 0xbfb8aa3b, v82
	v_fma_f32 v97, -v94, v95, 1.0
	v_fmac_f32_e32 v95, v97, v95
	v_div_scale_f32 v97, vcc, 1.0, v88, 1.0
	v_mul_f32_e32 v98, v97, v95
	v_fma_f32 v99, -v94, v98, v97
	v_fmac_f32_e32 v98, v99, v95
	v_fma_f32 v94, -v94, v98, v97
	v_div_fmas_f32 v94, v94, v95, v98
	v_div_fixup_f32 v88, v94, v88, 1.0
	global_store_dwordx4 v[92:93], v[88:91], off offset:64 sc1
	v_pk_add_f32 v[84:85], v[84:85], 1.0 op_sel_hi:[1,0]
	v_mul_f32_e32 v83, 0xbfb8aa3b, v83
	v_div_scale_f32 v88, s[0:1], v87, v87, 1.0
	v_rcp_f32_e32 v89, v88
	v_exp_f32_e32 v82, v82
	v_exp_f32_e32 v83, v83
	v_mul_f32_e32 v80, 0xbfb8aa3b, v80
	v_fma_f32 v90, -v88, v89, 1.0
	v_fmac_f32_e32 v89, v90, v89
	v_div_scale_f32 v90, vcc, 1.0, v87, 1.0
	v_mul_f32_e32 v91, v90, v89
	v_fma_f32 v94, -v88, v91, v90
	v_fmac_f32_e32 v91, v94, v89
	v_fma_f32 v88, -v88, v91, v90
	v_div_fmas_f32 v88, v88, v89, v91
	v_div_fixup_f32 v87, v88, v87, 1.0
	v_div_scale_f32 v88, s[0:1], v86, v86, 1.0
	v_rcp_f32_e32 v89, v88
	v_pk_add_f32 v[82:83], v[82:83], 1.0 op_sel_hi:[1,0]
	v_mul_f32_e32 v81, 0xbfb8aa3b, v81
	v_exp_f32_e32 v80, v80
	v_fma_f32 v90, -v88, v89, 1.0
	v_fmac_f32_e32 v89, v90, v89
	v_div_scale_f32 v90, vcc, 1.0, v86, 1.0
	v_mul_f32_e32 v91, v90, v89
	v_fma_f32 v94, -v88, v91, v90
	v_fmac_f32_e32 v91, v94, v89
	v_fma_f32 v88, -v88, v91, v90
	v_div_fmas_f32 v88, v88, v89, v91
	v_div_fixup_f32 v86, v88, v86, 1.0
	v_div_scale_f32 v88, s[0:1], v85, v85, 1.0
	v_rcp_f32_e32 v89, v88
	v_exp_f32_e32 v81, v81
	v_mul_f32_e32 v78, 0xbfb8aa3b, v78
	v_mul_f32_e32 v79, 0xbfb8aa3b, v79
	v_fma_f32 v90, -v88, v89, 1.0
	v_fmac_f32_e32 v89, v90, v89
	v_div_scale_f32 v90, vcc, 1.0, v85, 1.0
	v_mul_f32_e32 v91, v90, v89
	v_fma_f32 v94, -v88, v91, v90
	v_fmac_f32_e32 v91, v94, v89
	v_fma_f32 v88, -v88, v91, v90
	v_div_fmas_f32 v88, v88, v89, v91
	v_div_fixup_f32 v85, v88, v85, 1.0
	v_div_scale_f32 v88, s[0:1], v84, v84, 1.0
	v_rcp_f32_e32 v89, v88
	v_pk_add_f32 v[80:81], v[80:81], 1.0 op_sel_hi:[1,0]
	v_exp_f32_e32 v78, v78
	v_exp_f32_e32 v79, v79
	v_fma_f32 v90, -v88, v89, 1.0
	v_fmac_f32_e32 v89, v90, v89
	v_div_scale_f32 v90, vcc, 1.0, v84, 1.0
	v_mul_f32_e32 v91, v90, v89
	v_fma_f32 v94, -v88, v91, v90
	v_fmac_f32_e32 v91, v94, v89
	v_fma_f32 v88, -v88, v91, v90
	v_div_fmas_f32 v88, v88, v89, v91
	v_div_fixup_f32 v84, v88, v84, 1.0
	global_store_dwordx4 v[92:93], v[84:87], off offset:128 sc1
	v_pk_add_f32 v[78:79], v[78:79], 1.0 op_sel_hi:[1,0]
	v_mul_f32_e32 v76, 0xbfb8aa3b, v76
	v_div_scale_f32 v84, s[0:1], v83, v83, 1.0
	v_rcp_f32_e32 v85, v84
	v_or_b32_e32 v86, 16, v96
	v_mul_f32_e32 v77, 0xbfb8aa3b, v77
	v_exp_f32_e32 v76, v76
	v_fma_f32 v87, -v84, v85, 1.0
	v_fmac_f32_e32 v85, v87, v85
	v_div_scale_f32 v87, vcc, 1.0, v83, 1.0
	v_mul_f32_e32 v88, v87, v85
	v_fma_f32 v89, -v84, v88, v87
	v_fmac_f32_e32 v88, v89, v85
	v_fma_f32 v84, -v84, v88, v87
	v_div_fmas_f32 v84, v84, v85, v88
	v_div_fixup_f32 v85, v84, v83, 1.0
	v_div_scale_f32 v83, s[0:1], v82, v82, 1.0
	v_rcp_f32_e32 v84, v83
	v_exp_f32_e32 v77, v77
	v_mul_f32_e32 v74, 0xbfb8aa3b, v74
	v_mul_f32_e32 v75, 0xbfb8aa3b, v75
	v_fma_f32 v87, -v83, v84, 1.0
	v_fmac_f32_e32 v84, v87, v84
	v_div_scale_f32 v87, vcc, 1.0, v82, 1.0
	v_mul_f32_e32 v88, v87, v84
	v_fma_f32 v89, -v83, v88, v87
	v_fmac_f32_e32 v88, v89, v84
	v_fma_f32 v83, -v83, v88, v87
	v_div_fmas_f32 v83, v83, v84, v88
	v_div_fixup_f32 v84, v83, v82, 1.0
	v_div_scale_f32 v82, s[0:1], v81, v81, 1.0
	v_rcp_f32_e32 v83, v82
	v_pk_add_f32 v[76:77], v[76:77], 1.0 op_sel_hi:[1,0]
	v_exp_f32_e32 v74, v74
	v_exp_f32_e32 v75, v75
	v_fma_f32 v87, -v82, v83, 1.0
	v_fmac_f32_e32 v83, v87, v83
	v_div_scale_f32 v87, vcc, 1.0, v81, 1.0
	v_mul_f32_e32 v88, v87, v83
	v_fma_f32 v89, -v82, v88, v87
	v_fmac_f32_e32 v88, v89, v83
	v_fma_f32 v82, -v82, v88, v87
	v_div_fmas_f32 v82, v82, v83, v88
	v_div_fixup_f32 v83, v82, v81, 1.0
	v_div_scale_f32 v81, s[0:1], v80, v80, 1.0
	v_rcp_f32_e32 v82, v81
	v_pk_add_f32 v[74:75], v[74:75], 1.0 op_sel_hi:[1,0]
	v_mul_f32_e32 v72, 0xbfb8aa3b, v72
	v_mul_f32_e32 v73, 0xbfb8aa3b, v73
	v_fma_f32 v87, -v81, v82, 1.0
	v_fmac_f32_e32 v82, v87, v82
	v_div_scale_f32 v87, vcc, 1.0, v80, 1.0
	v_mul_f32_e32 v88, v87, v82
	v_fma_f32 v89, -v81, v88, v87
	v_fmac_f32_e32 v88, v89, v82
	v_fma_f32 v81, -v81, v88, v87
	v_div_fmas_f32 v81, v81, v82, v88
	v_div_fixup_f32 v82, v81, v80, 1.0
	v_mad_i64_i32 v[80:81], s[0:1], v86, s4, v[156:157]
	global_store_dwordx4 v[80:81], v[82:85], off sc1
	v_exp_f32_e32 v72, v72
	v_exp_f32_e32 v73, v73
	v_div_scale_f32 v82, s[0:1], v79, v79, 1.0
	v_rcp_f32_e32 v83, v82
	v_pk_add_f32 v[72:73], v[72:73], 1.0 op_sel_hi:[1,0]
	v_mul_f32_e32 v70, 0xbfb8aa3b, v70
	v_mul_f32_e32 v71, 0xbfb8aa3b, v71
	v_fma_f32 v84, -v82, v83, 1.0
	v_fmac_f32_e32 v83, v84, v83
	v_div_scale_f32 v84, vcc, 1.0, v79, 1.0
	v_mul_f32_e32 v85, v84, v83
	v_fma_f32 v86, -v82, v85, v84
	v_fmac_f32_e32 v85, v86, v83
	v_fma_f32 v82, -v82, v85, v84
	v_div_fmas_f32 v82, v82, v83, v85
	v_div_fixup_f32 v79, v82, v79, 1.0
	v_div_scale_f32 v82, s[0:1], v78, v78, 1.0
	v_rcp_f32_e32 v83, v82
	v_exp_f32_e32 v70, v70
	v_exp_f32_e32 v71, v71
	v_mul_f32_e32 v68, 0xbfb8aa3b, v68
	v_fma_f32 v84, -v82, v83, 1.0
	v_fmac_f32_e32 v83, v84, v83
	v_div_scale_f32 v84, vcc, 1.0, v78, 1.0
	v_mul_f32_e32 v85, v84, v83
	v_fma_f32 v86, -v82, v85, v84
	v_fmac_f32_e32 v85, v86, v83
	v_fma_f32 v82, -v82, v85, v84
	v_div_fmas_f32 v82, v82, v83, v85
	v_div_fixup_f32 v78, v82, v78, 1.0
	v_div_scale_f32 v82, s[0:1], v77, v77, 1.0
	v_rcp_f32_e32 v83, v82
	v_pk_add_f32 v[70:71], v[70:71], 1.0 op_sel_hi:[1,0]
	v_mul_f32_e32 v69, 0xbfb8aa3b, v69
	v_exp_f32_e32 v68, v68
	v_fma_f32 v84, -v82, v83, 1.0
	v_fmac_f32_e32 v83, v84, v83
	v_div_scale_f32 v84, vcc, 1.0, v77, 1.0
	v_mul_f32_e32 v85, v84, v83
	v_fma_f32 v86, -v82, v85, v84
	v_fmac_f32_e32 v85, v86, v83
	v_fma_f32 v82, -v82, v85, v84
	v_div_fmas_f32 v82, v82, v83, v85
	v_div_fixup_f32 v77, v82, v77, 1.0
	v_div_scale_f32 v82, s[0:1], v76, v76, 1.0
	v_rcp_f32_e32 v83, v82
	v_exp_f32_e32 v69, v69
	v_mul_f32_e32 v66, 0xbfb8aa3b, v66
	v_mul_f32_e32 v67, 0xbfb8aa3b, v67
	v_fma_f32 v84, -v82, v83, 1.0
	v_fmac_f32_e32 v83, v84, v83
	v_div_scale_f32 v84, vcc, 1.0, v76, 1.0
	v_mul_f32_e32 v85, v84, v83
	v_fma_f32 v86, -v82, v85, v84
	v_fmac_f32_e32 v85, v86, v83
	v_fma_f32 v82, -v82, v85, v84
	v_div_fmas_f32 v82, v82, v83, v85
	v_div_fixup_f32 v76, v82, v76, 1.0
	global_store_dwordx4 v[80:81], v[76:79], off offset:64 sc1
	v_pk_add_f32 v[68:69], v[68:69], 1.0 op_sel_hi:[1,0]
	v_exp_f32_e32 v66, v66
	v_div_scale_f32 v76, s[0:1], v75, v75, 1.0
	v_rcp_f32_e32 v77, v76
	v_exp_f32_e32 v67, v67
	v_mul_f32_e32 v64, 0xbfb8aa3b, v64
	v_mul_f32_e32 v65, 0xbfb8aa3b, v65
	v_fma_f32 v78, -v76, v77, 1.0
	v_fmac_f32_e32 v77, v78, v77
	v_div_scale_f32 v78, vcc, 1.0, v75, 1.0
	v_mul_f32_e32 v79, v78, v77
	v_fma_f32 v82, -v76, v79, v78
	v_fmac_f32_e32 v79, v82, v77
	v_fma_f32 v76, -v76, v79, v78
	v_div_fmas_f32 v76, v76, v77, v79
	v_div_fixup_f32 v75, v76, v75, 1.0
	v_div_scale_f32 v76, s[0:1], v74, v74, 1.0
	v_rcp_f32_e32 v77, v76
	v_pk_add_f32 v[66:67], v[66:67], 1.0 op_sel_hi:[1,0]
	v_exp_f32_e32 v64, v64
	v_exp_f32_e32 v65, v65
	v_fma_f32 v78, -v76, v77, 1.0
	v_fmac_f32_e32 v77, v78, v77
	v_div_scale_f32 v78, vcc, 1.0, v74, 1.0
	v_mul_f32_e32 v79, v78, v77
	v_fma_f32 v82, -v76, v79, v78
	v_fmac_f32_e32 v79, v82, v77
	v_fma_f32 v76, -v76, v79, v78
	v_div_fmas_f32 v76, v76, v77, v79
	v_div_fixup_f32 v74, v76, v74, 1.0
	v_div_scale_f32 v76, s[0:1], v73, v73, 1.0
	v_rcp_f32_e32 v77, v76
	v_pk_add_f32 v[64:65], v[64:65], 1.0 op_sel_hi:[1,0]
	v_mul_f32_e32 v62, 0xbfb8aa3b, v62
	v_mul_f32_e32 v63, 0xbfb8aa3b, v63
	v_fma_f32 v78, -v76, v77, 1.0
	v_fmac_f32_e32 v77, v78, v77
	v_div_scale_f32 v78, vcc, 1.0, v73, 1.0
	v_mul_f32_e32 v79, v78, v77
	v_fma_f32 v82, -v76, v79, v78
	v_fmac_f32_e32 v79, v82, v77
	v_fma_f32 v76, -v76, v79, v78
	v_div_fmas_f32 v76, v76, v77, v79
	v_div_fixup_f32 v73, v76, v73, 1.0
	v_div_scale_f32 v76, s[0:1], v72, v72, 1.0
	v_rcp_f32_e32 v77, v76
	v_exp_f32_e32 v62, v62
	v_exp_f32_e32 v63, v63
	v_mul_f32_e32 v60, 0xbfb8aa3b, v60
	v_fma_f32 v78, -v76, v77, 1.0
	v_fmac_f32_e32 v77, v78, v77
	v_div_scale_f32 v78, vcc, 1.0, v72, 1.0
	v_mul_f32_e32 v79, v78, v77
	v_fma_f32 v82, -v76, v79, v78
	v_fmac_f32_e32 v79, v82, v77
	v_fma_f32 v76, -v76, v79, v78
	v_div_fmas_f32 v76, v76, v77, v79
	v_div_fixup_f32 v72, v76, v72, 1.0
	global_store_dwordx4 v[80:81], v[72:75], off offset:128 sc1
	v_pk_add_f32 v[62:63], v[62:63], 1.0 op_sel_hi:[1,0]
	v_mul_f32_e32 v61, 0xbfb8aa3b, v61
	v_div_scale_f32 v72, s[0:1], v71, v71, 1.0
	v_rcp_f32_e32 v73, v72
	v_or_b32_e32 v74, 32, v96
	v_exp_f32_e32 v60, v60
	v_exp_f32_e32 v61, v61
	v_fma_f32 v75, -v72, v73, 1.0
	v_fmac_f32_e32 v73, v75, v73
	v_div_scale_f32 v75, vcc, 1.0, v71, 1.0
	v_mul_f32_e32 v76, v75, v73
	v_fma_f32 v77, -v72, v76, v75
	v_fmac_f32_e32 v76, v77, v73
	v_fma_f32 v72, -v72, v76, v75
	v_div_fmas_f32 v72, v72, v73, v76
	v_div_fixup_f32 v73, v72, v71, 1.0
	v_div_scale_f32 v71, s[0:1], v70, v70, 1.0
	v_rcp_f32_e32 v72, v71
	v_pk_add_f32 v[60:61], v[60:61], 1.0 op_sel_hi:[1,0]
	v_mul_f32_e32 v58, 0xbfb8aa3b, v58
	v_mul_f32_e32 v59, 0xbfb8aa3b, v59
	v_fma_f32 v75, -v71, v72, 1.0
	v_fmac_f32_e32 v72, v75, v72
	v_div_scale_f32 v75, vcc, 1.0, v70, 1.0
	v_mul_f32_e32 v76, v75, v72
	v_fma_f32 v77, -v71, v76, v75
	v_fmac_f32_e32 v76, v77, v72
	v_fma_f32 v71, -v71, v76, v75
	v_div_fmas_f32 v71, v71, v72, v76
	v_div_fixup_f32 v72, v71, v70, 1.0
	v_div_scale_f32 v70, s[0:1], v69, v69, 1.0
	v_rcp_f32_e32 v71, v70
	v_exp_f32_e32 v58, v58
	v_exp_f32_e32 v59, v59
	v_mul_f32_e32 v56, 0xbfb8aa3b, v56
	v_fma_f32 v75, -v70, v71, 1.0
	v_fmac_f32_e32 v71, v75, v71
	v_div_scale_f32 v75, vcc, 1.0, v69, 1.0
	v_mul_f32_e32 v76, v75, v71
	v_fma_f32 v77, -v70, v76, v75
	v_fmac_f32_e32 v76, v77, v71
	v_fma_f32 v70, -v70, v76, v75
	v_div_fmas_f32 v70, v70, v71, v76
	v_div_fixup_f32 v71, v70, v69, 1.0
	v_div_scale_f32 v69, s[0:1], v68, v68, 1.0
	v_rcp_f32_e32 v70, v69
	v_pk_add_f32 v[58:59], v[58:59], 1.0 op_sel_hi:[1,0]
	v_mul_f32_e32 v57, 0xbfb8aa3b, v57
	v_exp_f32_e32 v56, v56
	v_fma_f32 v75, -v69, v70, 1.0
	v_fmac_f32_e32 v70, v75, v70
	v_div_scale_f32 v75, vcc, 1.0, v68, 1.0
	v_mul_f32_e32 v76, v75, v70
	v_fma_f32 v77, -v69, v76, v75
	v_fmac_f32_e32 v76, v77, v70
	v_fma_f32 v69, -v69, v76, v75
	v_div_fmas_f32 v69, v69, v70, v76
	v_div_fixup_f32 v70, v69, v68, 1.0
	v_mad_i64_i32 v[68:69], s[0:1], v74, s4, v[156:157]
	global_store_dwordx4 v[68:69], v[70:73], off sc1
	v_exp_f32_e32 v57, v57
	v_mul_f32_e32 v54, 0xbfb8aa3b, v54
	v_div_scale_f32 v70, s[0:1], v67, v67, 1.0
	v_rcp_f32_e32 v71, v70
	v_pk_add_f32 v[56:57], v[56:57], 1.0 op_sel_hi:[1,0]
	v_mul_f32_e32 v55, 0xbfb8aa3b, v55
	v_exp_f32_e32 v54, v54
	v_fma_f32 v72, -v70, v71, 1.0
	v_fmac_f32_e32 v71, v72, v71
	v_div_scale_f32 v72, vcc, 1.0, v67, 1.0
	v_mul_f32_e32 v73, v72, v71
	v_fma_f32 v74, -v70, v73, v72
	v_fmac_f32_e32 v73, v74, v71
	v_fma_f32 v70, -v70, v73, v72
	v_div_fmas_f32 v70, v70, v71, v73
	v_div_fixup_f32 v67, v70, v67, 1.0
	v_div_scale_f32 v70, s[0:1], v66, v66, 1.0
	v_rcp_f32_e32 v71, v70
	v_exp_f32_e32 v55, v55
	v_mul_f32_e32 v52, 0xbfb8aa3b, v52
	v_mul_f32_e32 v53, 0xbfb8aa3b, v53
	v_fma_f32 v72, -v70, v71, 1.0
	v_fmac_f32_e32 v71, v72, v71
	v_div_scale_f32 v72, vcc, 1.0, v66, 1.0
	v_mul_f32_e32 v73, v72, v71
	v_fma_f32 v74, -v70, v73, v72
	v_fmac_f32_e32 v73, v74, v71
	v_fma_f32 v70, -v70, v73, v72
	v_div_fmas_f32 v70, v70, v71, v73
	v_div_fixup_f32 v66, v70, v66, 1.0
	v_div_scale_f32 v70, s[0:1], v65, v65, 1.0
	v_rcp_f32_e32 v71, v70
	v_pk_add_f32 v[54:55], v[54:55], 1.0 op_sel_hi:[1,0]
	v_exp_f32_e32 v52, v52
	v_exp_f32_e32 v53, v53
	v_fma_f32 v72, -v70, v71, 1.0
	v_fmac_f32_e32 v71, v72, v71
	v_div_scale_f32 v72, vcc, 1.0, v65, 1.0
	v_mul_f32_e32 v73, v72, v71
	v_fma_f32 v74, -v70, v73, v72
	v_fmac_f32_e32 v73, v74, v71
	v_fma_f32 v70, -v70, v73, v72
	v_div_fmas_f32 v70, v70, v71, v73
	v_div_fixup_f32 v65, v70, v65, 1.0
	v_div_scale_f32 v70, s[0:1], v64, v64, 1.0
	v_rcp_f32_e32 v71, v70
	v_pk_add_f32 v[52:53], v[52:53], 1.0 op_sel_hi:[1,0]
	v_mul_f32_e32 v50, 0xbfb8aa3b, v50
	v_mul_f32_e32 v51, 0xbfb8aa3b, v51
	v_fma_f32 v72, -v70, v71, 1.0
	v_fmac_f32_e32 v71, v72, v71
	v_div_scale_f32 v72, vcc, 1.0, v64, 1.0
	v_mul_f32_e32 v73, v72, v71
	v_fma_f32 v74, -v70, v73, v72
	v_fmac_f32_e32 v73, v74, v71
	v_fma_f32 v70, -v70, v73, v72
	v_div_fmas_f32 v70, v70, v71, v73
	v_div_fixup_f32 v64, v70, v64, 1.0
	global_store_dwordx4 v[68:69], v[64:67], off offset:64 sc1
	v_exp_f32_e32 v50, v50
	v_exp_f32_e32 v51, v51
	v_div_scale_f32 v64, s[0:1], v63, v63, 1.0
	v_rcp_f32_e32 v65, v64
	v_pk_add_f32 v[50:51], v[50:51], 1.0 op_sel_hi:[1,0]
	v_mul_f32_e32 v48, 0xbfb8aa3b, v48
	v_mul_f32_e32 v49, 0xbfb8aa3b, v49
	v_fma_f32 v66, -v64, v65, 1.0
	v_fmac_f32_e32 v65, v66, v65
	v_div_scale_f32 v66, vcc, 1.0, v63, 1.0
	v_mul_f32_e32 v67, v66, v65
	v_fma_f32 v70, -v64, v67, v66
	v_fmac_f32_e32 v67, v70, v65
	v_fma_f32 v64, -v64, v67, v66
	v_div_fmas_f32 v64, v64, v65, v67
	v_div_fixup_f32 v63, v64, v63, 1.0
	v_div_scale_f32 v64, s[0:1], v62, v62, 1.0
	v_rcp_f32_e32 v65, v64
	v_exp_f32_e32 v48, v48
	v_exp_f32_e32 v49, v49
	v_mul_f32_e32 v46, 0xbfb8aa3b, v46
	v_fma_f32 v66, -v64, v65, 1.0
	v_fmac_f32_e32 v65, v66, v65
	v_div_scale_f32 v66, vcc, 1.0, v62, 1.0
	v_mul_f32_e32 v67, v66, v65
	v_fma_f32 v70, -v64, v67, v66
	v_fmac_f32_e32 v67, v70, v65
	v_fma_f32 v64, -v64, v67, v66
	v_div_fmas_f32 v64, v64, v65, v67
	v_div_fixup_f32 v62, v64, v62, 1.0
	v_div_scale_f32 v64, s[0:1], v61, v61, 1.0
	v_rcp_f32_e32 v65, v64
	v_pk_add_f32 v[48:49], v[48:49], 1.0 op_sel_hi:[1,0]
	v_mul_f32_e32 v47, 0xbfb8aa3b, v47
	v_exp_f32_e32 v46, v46
	v_fma_f32 v66, -v64, v65, 1.0
	v_fmac_f32_e32 v65, v66, v65
	v_div_scale_f32 v66, vcc, 1.0, v61, 1.0
	v_mul_f32_e32 v67, v66, v65
	v_fma_f32 v70, -v64, v67, v66
	v_fmac_f32_e32 v67, v70, v65
	v_fma_f32 v64, -v64, v67, v66
	v_div_fmas_f32 v64, v64, v65, v67
	v_div_fixup_f32 v61, v64, v61, 1.0
	v_div_scale_f32 v64, s[0:1], v60, v60, 1.0
	v_rcp_f32_e32 v65, v64
	v_exp_f32_e32 v47, v47
	v_mul_f32_e32 v44, 0xbfb8aa3b, v44
	v_mul_f32_e32 v45, 0xbfb8aa3b, v45
	v_fma_f32 v66, -v64, v65, 1.0
	v_fmac_f32_e32 v65, v66, v65
	v_div_scale_f32 v66, vcc, 1.0, v60, 1.0
	v_mul_f32_e32 v67, v66, v65
	v_fma_f32 v70, -v64, v67, v66
	v_fmac_f32_e32 v67, v70, v65
	v_fma_f32 v64, -v64, v67, v66
	v_div_fmas_f32 v64, v64, v65, v67
	v_div_fixup_f32 v60, v64, v60, 1.0
	global_store_dwordx4 v[68:69], v[60:63], off offset:128 sc1
	v_pk_add_f32 v[46:47], v[46:47], 1.0 op_sel_hi:[1,0]
	v_exp_f32_e32 v44, v44
	v_div_scale_f32 v60, s[0:1], v59, v59, 1.0
	v_rcp_f32_e32 v61, v60
	v_or_b32_e32 v62, 48, v96
	v_exp_f32_e32 v45, v45
	v_mul_f32_e32 v42, 0xbfb8aa3b, v42
	v_fma_f32 v63, -v60, v61, 1.0
	v_fmac_f32_e32 v61, v63, v61
	v_div_scale_f32 v63, vcc, 1.0, v59, 1.0
	v_mul_f32_e32 v64, v63, v61
	v_fma_f32 v65, -v60, v64, v63
	v_fmac_f32_e32 v64, v65, v61
	v_fma_f32 v60, -v60, v64, v63
	v_div_fmas_f32 v60, v60, v61, v64
	v_div_fixup_f32 v61, v60, v59, 1.0
	v_div_scale_f32 v59, s[0:1], v58, v58, 1.0
	v_rcp_f32_e32 v60, v59
	v_pk_add_f32 v[44:45], v[44:45], 1.0 op_sel_hi:[1,0]
	v_mul_f32_e32 v43, 0xbfb8aa3b, v43
	v_exp_f32_e32 v42, v42
	v_fma_f32 v63, -v59, v60, 1.0
	v_fmac_f32_e32 v60, v63, v60
	v_div_scale_f32 v63, vcc, 1.0, v58, 1.0
	v_mul_f32_e32 v64, v63, v60
	v_fma_f32 v65, -v59, v64, v63
	v_fmac_f32_e32 v64, v65, v60
	v_fma_f32 v59, -v59, v64, v63
	v_div_fmas_f32 v59, v59, v60, v64
	v_div_fixup_f32 v60, v59, v58, 1.0
	v_div_scale_f32 v58, s[0:1], v57, v57, 1.0
	v_rcp_f32_e32 v59, v58
	v_exp_f32_e32 v43, v43
	v_mul_f32_e32 v40, 0xbfb8aa3b, v40
	v_mul_f32_e32 v41, 0xbfb8aa3b, v41
	v_fma_f32 v63, -v58, v59, 1.0
	v_fmac_f32_e32 v59, v63, v59
	v_div_scale_f32 v63, vcc, 1.0, v57, 1.0
	v_mul_f32_e32 v64, v63, v59
	v_fma_f32 v65, -v58, v64, v63
	v_fmac_f32_e32 v64, v65, v59
	v_fma_f32 v58, -v58, v64, v63
	v_div_fmas_f32 v58, v58, v59, v64
	v_div_fixup_f32 v59, v58, v57, 1.0
	v_div_scale_f32 v57, s[0:1], v56, v56, 1.0
	v_rcp_f32_e32 v58, v57
	v_pk_add_f32 v[42:43], v[42:43], 1.0 op_sel_hi:[1,0]
	v_exp_f32_e32 v40, v40
	v_exp_f32_e32 v41, v41
	v_fma_f32 v63, -v57, v58, 1.0
	v_fmac_f32_e32 v58, v63, v58
	v_div_scale_f32 v63, vcc, 1.0, v56, 1.0
	v_mul_f32_e32 v64, v63, v58
	v_fma_f32 v65, -v57, v64, v63
	v_fmac_f32_e32 v64, v65, v58
	v_fma_f32 v57, -v57, v64, v63
	v_div_fmas_f32 v57, v57, v58, v64
	v_div_fixup_f32 v58, v57, v56, 1.0
	v_mad_i64_i32 v[56:57], s[0:1], v62, s4, v[156:157]
	global_store_dwordx4 v[56:57], v[58:61], off sc1
	v_pk_add_f32 v[40:41], v[40:41], 1.0 op_sel_hi:[1,0]
	v_mul_f32_e32 v38, 0xbfb8aa3b, v38
	v_div_scale_f32 v58, s[0:1], v55, v55, 1.0
	v_rcp_f32_e32 v59, v58
	v_mul_f32_e32 v39, 0xbfb8aa3b, v39
	v_exp_f32_e32 v38, v38
	v_exp_f32_e32 v39, v39
	v_fma_f32 v60, -v58, v59, 1.0
	v_fmac_f32_e32 v59, v60, v59
	v_div_scale_f32 v60, vcc, 1.0, v55, 1.0
	v_mul_f32_e32 v61, v60, v59
	v_fma_f32 v62, -v58, v61, v60
	v_fmac_f32_e32 v61, v62, v59
	v_fma_f32 v58, -v58, v61, v60
	v_div_fmas_f32 v58, v58, v59, v61
	v_div_fixup_f32 v55, v58, v55, 1.0
	v_div_scale_f32 v58, s[0:1], v54, v54, 1.0
	v_rcp_f32_e32 v59, v58
	v_pk_add_f32 v[38:39], v[38:39], 1.0 op_sel_hi:[1,0]
	v_mul_f32_e32 v36, 0xbfb8aa3b, v36
	v_mul_f32_e32 v37, 0xbfb8aa3b, v37
	v_fma_f32 v60, -v58, v59, 1.0
	v_fmac_f32_e32 v59, v60, v59
	v_div_scale_f32 v60, vcc, 1.0, v54, 1.0
	v_mul_f32_e32 v61, v60, v59
	v_fma_f32 v62, -v58, v61, v60
	v_fmac_f32_e32 v61, v62, v59
	v_fma_f32 v58, -v58, v61, v60
	v_div_fmas_f32 v58, v58, v59, v61
	v_div_fixup_f32 v54, v58, v54, 1.0
	v_div_scale_f32 v58, s[0:1], v53, v53, 1.0
	v_rcp_f32_e32 v59, v58
	v_exp_f32_e32 v36, v36
	v_exp_f32_e32 v37, v37
	v_mul_f32_e32 v34, 0xbfb8aa3b, v34
	v_fma_f32 v60, -v58, v59, 1.0
	v_fmac_f32_e32 v59, v60, v59
	v_div_scale_f32 v60, vcc, 1.0, v53, 1.0
	v_mul_f32_e32 v61, v60, v59
	v_fma_f32 v62, -v58, v61, v60
	v_fmac_f32_e32 v61, v62, v59
	v_fma_f32 v58, -v58, v61, v60
	v_div_fmas_f32 v58, v58, v59, v61
	v_div_fixup_f32 v53, v58, v53, 1.0
	v_div_scale_f32 v58, s[0:1], v52, v52, 1.0
	v_rcp_f32_e32 v59, v58
	v_pk_add_f32 v[36:37], v[36:37], 1.0 op_sel_hi:[1,0]
	v_mul_f32_e32 v35, 0xbfb8aa3b, v35
	v_exp_f32_e32 v34, v34
	v_fma_f32 v60, -v58, v59, 1.0
	v_fmac_f32_e32 v59, v60, v59
	v_div_scale_f32 v60, vcc, 1.0, v52, 1.0
	v_mul_f32_e32 v61, v60, v59
	v_fma_f32 v62, -v58, v61, v60
	v_fmac_f32_e32 v61, v62, v59
	v_fma_f32 v58, -v58, v61, v60
	v_div_fmas_f32 v58, v58, v59, v61
	v_div_fixup_f32 v52, v58, v52, 1.0
	global_store_dwordx4 v[56:57], v[52:55], off offset:64 sc1
	v_exp_f32_e32 v35, v35
	v_mul_f32_e32 v32, 0xbfb8aa3b, v32
	v_div_scale_f32 v52, s[0:1], v51, v51, 1.0
	v_rcp_f32_e32 v53, v52
	v_pk_add_f32 v[34:35], v[34:35], 1.0 op_sel_hi:[1,0]
	v_mul_f32_e32 v33, 0xbfb8aa3b, v33
	v_exp_f32_e32 v32, v32
	v_fma_f32 v54, -v52, v53, 1.0
	v_fmac_f32_e32 v53, v54, v53
	v_div_scale_f32 v54, vcc, 1.0, v51, 1.0
	v_mul_f32_e32 v55, v54, v53
	v_fma_f32 v58, -v52, v55, v54
	v_fmac_f32_e32 v55, v58, v53
	v_fma_f32 v52, -v52, v55, v54
	v_div_fmas_f32 v52, v52, v53, v55
	v_div_fixup_f32 v51, v52, v51, 1.0
	v_div_scale_f32 v52, s[0:1], v50, v50, 1.0
	v_rcp_f32_e32 v53, v52
	v_exp_f32_e32 v33, v33
	v_mul_f32_e32 v30, 0xbfb8aa3b, v30
	v_mul_f32_e32 v31, 0xbfb8aa3b, v31
	v_fma_f32 v54, -v52, v53, 1.0
	v_fmac_f32_e32 v53, v54, v53
	v_div_scale_f32 v54, vcc, 1.0, v50, 1.0
	v_mul_f32_e32 v55, v54, v53
	v_fma_f32 v58, -v52, v55, v54
	v_fmac_f32_e32 v55, v58, v53
	v_fma_f32 v52, -v52, v55, v54
	v_div_fmas_f32 v52, v52, v53, v55
	v_div_fixup_f32 v50, v52, v50, 1.0
	v_div_scale_f32 v52, s[0:1], v49, v49, 1.0
	v_rcp_f32_e32 v53, v52
	v_pk_add_f32 v[32:33], v[32:33], 1.0 op_sel_hi:[1,0]
	v_exp_f32_e32 v30, v30
	v_exp_f32_e32 v31, v31
	v_fma_f32 v54, -v52, v53, 1.0
	v_fmac_f32_e32 v53, v54, v53
	v_div_scale_f32 v54, vcc, 1.0, v49, 1.0
	v_mul_f32_e32 v55, v54, v53
	v_fma_f32 v58, -v52, v55, v54
	v_fmac_f32_e32 v55, v58, v53
	v_fma_f32 v52, -v52, v55, v54
	v_div_fmas_f32 v52, v52, v53, v55
	v_div_fixup_f32 v49, v52, v49, 1.0
	v_div_scale_f32 v52, s[0:1], v48, v48, 1.0
	v_rcp_f32_e32 v53, v52
	v_pk_add_f32 v[30:31], v[30:31], 1.0 op_sel_hi:[1,0]
	v_mul_f32_e32 v28, 0xbfb8aa3b, v28
	v_mul_f32_e32 v29, 0xbfb8aa3b, v29
	v_fma_f32 v54, -v52, v53, 1.0
	v_fmac_f32_e32 v53, v54, v53
	v_div_scale_f32 v54, vcc, 1.0, v48, 1.0
	v_mul_f32_e32 v55, v54, v53
	v_fma_f32 v58, -v52, v55, v54
	v_fmac_f32_e32 v55, v58, v53
	v_fma_f32 v52, -v52, v55, v54
	v_div_fmas_f32 v52, v52, v53, v55
	v_div_fixup_f32 v48, v52, v48, 1.0
	global_store_dwordx4 v[56:57], v[48:51], off offset:128 sc1
	v_exp_f32_e32 v28, v28
	v_exp_f32_e32 v29, v29
	v_div_scale_f32 v48, s[0:1], v47, v47, 1.0
	v_rcp_f32_e32 v49, v48
	v_add_u32_e32 v50, 0x80, v96
	v_pk_add_f32 v[28:29], v[28:29], 1.0 op_sel_hi:[1,0]
	v_mul_f32_e32 v26, 0xbfb8aa3b, v26
	v_fma_f32 v51, -v48, v49, 1.0
	v_fmac_f32_e32 v49, v51, v49
	v_div_scale_f32 v51, vcc, 1.0, v47, 1.0
	v_mul_f32_e32 v52, v51, v49
	v_fma_f32 v53, -v48, v52, v51
	v_fmac_f32_e32 v52, v53, v49
	v_fma_f32 v48, -v48, v52, v51
	v_div_fmas_f32 v48, v48, v49, v52
	v_div_fixup_f32 v49, v48, v47, 1.0
	v_div_scale_f32 v47, s[0:1], v46, v46, 1.0
	v_rcp_f32_e32 v48, v47
	v_mul_f32_e32 v27, 0xbfb8aa3b, v27
	v_exp_f32_e32 v26, v26
	v_exp_f32_e32 v27, v27
	v_fma_f32 v51, -v47, v48, 1.0
	v_fmac_f32_e32 v48, v51, v48
	v_div_scale_f32 v51, vcc, 1.0, v46, 1.0
	v_mul_f32_e32 v52, v51, v48
	v_fma_f32 v53, -v47, v52, v51
	v_fmac_f32_e32 v52, v53, v48
	v_fma_f32 v47, -v47, v52, v51
	v_div_fmas_f32 v47, v47, v48, v52
	v_div_fixup_f32 v48, v47, v46, 1.0
	v_div_scale_f32 v46, s[0:1], v45, v45, 1.0
	v_rcp_f32_e32 v47, v46
	v_pk_add_f32 v[26:27], v[26:27], 1.0 op_sel_hi:[1,0]
	v_mul_f32_e32 v24, 0xbfb8aa3b, v24
	v_mul_f32_e32 v25, 0xbfb8aa3b, v25
	v_fma_f32 v51, -v46, v47, 1.0
	v_fmac_f32_e32 v47, v51, v47
	v_div_scale_f32 v51, vcc, 1.0, v45, 1.0
	v_mul_f32_e32 v52, v51, v47
	v_fma_f32 v53, -v46, v52, v51
	v_fmac_f32_e32 v52, v53, v47
	v_fma_f32 v46, -v46, v52, v51
	v_div_fmas_f32 v46, v46, v47, v52
	v_div_fixup_f32 v47, v46, v45, 1.0
	v_div_scale_f32 v45, s[0:1], v44, v44, 1.0
	v_rcp_f32_e32 v46, v45
	v_exp_f32_e32 v24, v24
	v_exp_f32_e32 v25, v25
	v_mul_f32_e32 v22, 0xbfb8aa3b, v22
	v_fma_f32 v51, -v45, v46, 1.0
	v_fmac_f32_e32 v46, v51, v46
	v_div_scale_f32 v51, vcc, 1.0, v44, 1.0
	v_mul_f32_e32 v52, v51, v46
	v_fma_f32 v53, -v45, v52, v51
	v_fmac_f32_e32 v52, v53, v46
	v_fma_f32 v45, -v45, v52, v51
	v_div_fmas_f32 v45, v45, v46, v52
	v_div_fixup_f32 v46, v45, v44, 1.0
	v_mad_i64_i32 v[44:45], s[0:1], v50, s4, v[156:157]
	global_store_dwordx4 v[44:45], v[46:49], off sc1
	v_pk_add_f32 v[24:25], v[24:25], 1.0 op_sel_hi:[1,0]
	v_mul_f32_e32 v23, 0xbfb8aa3b, v23
	v_div_scale_f32 v46, s[0:1], v43, v43, 1.0
	v_rcp_f32_e32 v47, v46
	v_exp_f32_e32 v22, v22
	v_exp_f32_e32 v23, v23
	v_mul_f32_e32 v20, 0xbfb8aa3b, v20
	v_fma_f32 v48, -v46, v47, 1.0
	v_fmac_f32_e32 v47, v48, v47
	v_div_scale_f32 v48, vcc, 1.0, v43, 1.0
	v_mul_f32_e32 v49, v48, v47
	v_fma_f32 v50, -v46, v49, v48
	v_fmac_f32_e32 v49, v50, v47
	v_fma_f32 v46, -v46, v49, v48
	v_div_fmas_f32 v46, v46, v47, v49
	v_div_fixup_f32 v43, v46, v43, 1.0
	v_div_scale_f32 v46, s[0:1], v42, v42, 1.0
	v_rcp_f32_e32 v47, v46
	v_pk_add_f32 v[22:23], v[22:23], 1.0 op_sel_hi:[1,0]
	v_mul_f32_e32 v21, 0xbfb8aa3b, v21
	v_exp_f32_e32 v20, v20
	v_fma_f32 v48, -v46, v47, 1.0
	v_fmac_f32_e32 v47, v48, v47
	v_div_scale_f32 v48, vcc, 1.0, v42, 1.0
	v_mul_f32_e32 v49, v48, v47
	v_fma_f32 v50, -v46, v49, v48
	v_fmac_f32_e32 v49, v50, v47
	v_fma_f32 v46, -v46, v49, v48
	v_div_fmas_f32 v46, v46, v47, v49
	v_div_fixup_f32 v42, v46, v42, 1.0
	v_div_scale_f32 v46, s[0:1], v41, v41, 1.0
	v_rcp_f32_e32 v47, v46
	v_exp_f32_e32 v21, v21
	v_mul_f32_e32 v18, 0xbfb8aa3b, v18
	v_mul_f32_e32 v19, 0xbfb8aa3b, v19
	v_fma_f32 v48, -v46, v47, 1.0
	v_fmac_f32_e32 v47, v48, v47
	v_div_scale_f32 v48, vcc, 1.0, v41, 1.0
	v_mul_f32_e32 v49, v48, v47
	v_fma_f32 v50, -v46, v49, v48
	v_fmac_f32_e32 v49, v50, v47
	v_fma_f32 v46, -v46, v49, v48
	v_div_fmas_f32 v46, v46, v47, v49
	v_div_fixup_f32 v41, v46, v41, 1.0
	v_div_scale_f32 v46, s[0:1], v40, v40, 1.0
	v_rcp_f32_e32 v47, v46
	v_pk_add_f32 v[20:21], v[20:21], 1.0 op_sel_hi:[1,0]
	v_exp_f32_e32 v18, v18
	v_exp_f32_e32 v19, v19
	v_fma_f32 v48, -v46, v47, 1.0
	v_fmac_f32_e32 v47, v48, v47
	v_div_scale_f32 v48, vcc, 1.0, v40, 1.0
	v_mul_f32_e32 v49, v48, v47
	v_fma_f32 v50, -v46, v49, v48
	v_fmac_f32_e32 v49, v50, v47
	v_fma_f32 v46, -v46, v49, v48
	v_div_fmas_f32 v46, v46, v47, v49
	v_div_fixup_f32 v40, v46, v40, 1.0
	global_store_dwordx4 v[44:45], v[40:43], off offset:64 sc1
	v_pk_add_f32 v[18:19], v[18:19], 1.0 op_sel_hi:[1,0]
	v_mul_f32_e32 v16, 0xbfb8aa3b, v16
	v_div_scale_f32 v40, s[0:1], v39, v39, 1.0
	v_rcp_f32_e32 v41, v40
	v_mul_f32_e32 v17, 0xbfb8aa3b, v17
	v_exp_f32_e32 v16, v16
	v_exp_f32_e32 v17, v17
	v_fma_f32 v42, -v40, v41, 1.0
	v_fmac_f32_e32 v41, v42, v41
	v_div_scale_f32 v42, vcc, 1.0, v39, 1.0
	v_mul_f32_e32 v43, v42, v41
	v_fma_f32 v46, -v40, v43, v42
	v_fmac_f32_e32 v43, v46, v41
	v_fma_f32 v40, -v40, v43, v42
	v_div_fmas_f32 v40, v40, v41, v43
	v_div_fixup_f32 v39, v40, v39, 1.0
	v_div_scale_f32 v40, s[0:1], v38, v38, 1.0
	v_rcp_f32_e32 v41, v40
	v_pk_add_f32 v[16:17], v[16:17], 1.0 op_sel_hi:[1,0]
	v_mul_f32_e32 v14, 0xbfb8aa3b, v14
	v_mul_f32_e32 v15, 0xbfb8aa3b, v15
	v_fma_f32 v42, -v40, v41, 1.0
	v_fmac_f32_e32 v41, v42, v41
	v_div_scale_f32 v42, vcc, 1.0, v38, 1.0
	v_mul_f32_e32 v43, v42, v41
	v_fma_f32 v46, -v40, v43, v42
	v_fmac_f32_e32 v43, v46, v41
	v_fma_f32 v40, -v40, v43, v42
	v_div_fmas_f32 v40, v40, v41, v43
	v_div_fixup_f32 v38, v40, v38, 1.0
	v_div_scale_f32 v40, s[0:1], v37, v37, 1.0
	v_rcp_f32_e32 v41, v40
	v_exp_f32_e32 v14, v14
	v_exp_f32_e32 v15, v15
	v_mul_f32_e32 v12, 0xbfb8aa3b, v12
	v_fma_f32 v42, -v40, v41, 1.0
	v_fmac_f32_e32 v41, v42, v41
	v_div_scale_f32 v42, vcc, 1.0, v37, 1.0
	v_mul_f32_e32 v43, v42, v41
	v_fma_f32 v46, -v40, v43, v42
	v_fmac_f32_e32 v43, v46, v41
	v_fma_f32 v40, -v40, v43, v42
	v_div_fmas_f32 v40, v40, v41, v43
	v_div_fixup_f32 v37, v40, v37, 1.0
	v_div_scale_f32 v40, s[0:1], v36, v36, 1.0
	v_rcp_f32_e32 v41, v40
	v_pk_add_f32 v[14:15], v[14:15], 1.0 op_sel_hi:[1,0]
	v_mul_f32_e32 v13, 0xbfb8aa3b, v13
	v_exp_f32_e32 v12, v12
	v_fma_f32 v42, -v40, v41, 1.0
	v_fmac_f32_e32 v41, v42, v41
	v_div_scale_f32 v42, vcc, 1.0, v36, 1.0
	v_mul_f32_e32 v43, v42, v41
	v_fma_f32 v46, -v40, v43, v42
	v_fmac_f32_e32 v43, v46, v41
	v_fma_f32 v40, -v40, v43, v42
	v_div_fmas_f32 v40, v40, v41, v43
	v_div_fixup_f32 v36, v40, v36, 1.0
	global_store_dwordx4 v[44:45], v[36:39], off offset:128 sc1
	v_exp_f32_e32 v13, v13
	v_mul_f32_e32 v10, 0xbfb8aa3b, v10
	v_div_scale_f32 v36, s[0:1], v35, v35, 1.0
	v_rcp_f32_e32 v37, v36
	v_add_u32_e32 v38, 0x90, v96
	v_pk_add_f32 v[12:13], v[12:13], 1.0 op_sel_hi:[1,0]
	v_mul_f32_e32 v11, 0xbfb8aa3b, v11
	v_fma_f32 v39, -v36, v37, 1.0
	v_fmac_f32_e32 v37, v39, v37
	v_div_scale_f32 v39, vcc, 1.0, v35, 1.0
	v_mul_f32_e32 v40, v39, v37
	v_fma_f32 v41, -v36, v40, v39
	v_fmac_f32_e32 v40, v41, v37
	v_fma_f32 v36, -v36, v40, v39
	v_div_fmas_f32 v36, v36, v37, v40
	v_div_fixup_f32 v37, v36, v35, 1.0
	v_div_scale_f32 v35, s[0:1], v34, v34, 1.0
	v_rcp_f32_e32 v36, v35
	v_exp_f32_e32 v10, v10
	v_exp_f32_e32 v11, v11
	v_mul_f32_e32 v8, 0xbfb8aa3b, v8
	v_fma_f32 v39, -v35, v36, 1.0
	v_fmac_f32_e32 v36, v39, v36
	v_div_scale_f32 v39, vcc, 1.0, v34, 1.0
	v_mul_f32_e32 v40, v39, v36
	v_fma_f32 v41, -v35, v40, v39
	v_fmac_f32_e32 v40, v41, v36
	v_fma_f32 v35, -v35, v40, v39
	v_div_fmas_f32 v35, v35, v36, v40
	v_div_fixup_f32 v36, v35, v34, 1.0
	v_div_scale_f32 v34, s[0:1], v33, v33, 1.0
	v_rcp_f32_e32 v35, v34
	v_pk_add_f32 v[10:11], v[10:11], 1.0 op_sel_hi:[1,0]
	v_mul_f32_e32 v9, 0xbfb8aa3b, v9
	v_exp_f32_e32 v8, v8
	v_fma_f32 v39, -v34, v35, 1.0
	v_fmac_f32_e32 v35, v39, v35
	v_div_scale_f32 v39, vcc, 1.0, v33, 1.0
	v_mul_f32_e32 v40, v39, v35
	v_fma_f32 v41, -v34, v40, v39
	v_fmac_f32_e32 v40, v41, v35
	v_fma_f32 v34, -v34, v40, v39
	v_div_fmas_f32 v34, v34, v35, v40
	v_div_fixup_f32 v35, v34, v33, 1.0
	v_div_scale_f32 v33, s[0:1], v32, v32, 1.0
	v_rcp_f32_e32 v34, v33
	v_exp_f32_e32 v9, v9
	v_mul_f32_e32 v6, 0xbfb8aa3b, v6
	v_mul_f32_e32 v7, 0xbfb8aa3b, v7
	v_fma_f32 v39, -v33, v34, 1.0
	v_fmac_f32_e32 v34, v39, v34
	v_div_scale_f32 v39, vcc, 1.0, v32, 1.0
	v_mul_f32_e32 v40, v39, v34
	v_fma_f32 v41, -v33, v40, v39
	v_fmac_f32_e32 v40, v41, v34
	v_fma_f32 v33, -v33, v40, v39
	v_div_fmas_f32 v33, v33, v34, v40
	v_div_fixup_f32 v34, v33, v32, 1.0
	v_mad_i64_i32 v[32:33], s[0:1], v38, s4, v[156:157]
	global_store_dwordx4 v[32:33], v[34:37], off sc1
	v_pk_add_f32 v[8:9], v[8:9], 1.0 op_sel_hi:[1,0]
	v_exp_f32_e32 v6, v6
	v_div_scale_f32 v34, s[0:1], v31, v31, 1.0
	v_rcp_f32_e32 v35, v34
	v_exp_f32_e32 v7, v7
	v_mul_f32_e32 v4, 0xbfb8aa3b, v4
	v_mul_f32_e32 v5, 0xbfb8aa3b, v5
	v_fma_f32 v36, -v34, v35, 1.0
	v_fmac_f32_e32 v35, v36, v35
	v_div_scale_f32 v36, vcc, 1.0, v31, 1.0
	v_mul_f32_e32 v37, v36, v35
	v_fma_f32 v38, -v34, v37, v36
	v_fmac_f32_e32 v37, v38, v35
	v_fma_f32 v34, -v34, v37, v36
	v_div_fmas_f32 v34, v34, v35, v37
	v_div_fixup_f32 v31, v34, v31, 1.0
	v_div_scale_f32 v34, s[0:1], v30, v30, 1.0
	v_rcp_f32_e32 v35, v34
	v_pk_add_f32 v[6:7], v[6:7], 1.0 op_sel_hi:[1,0]
	v_exp_f32_e32 v4, v4
	v_exp_f32_e32 v5, v5
	v_fma_f32 v36, -v34, v35, 1.0
	v_fmac_f32_e32 v35, v36, v35
	v_div_scale_f32 v36, vcc, 1.0, v30, 1.0
	v_mul_f32_e32 v37, v36, v35
	v_fma_f32 v38, -v34, v37, v36
	v_fmac_f32_e32 v37, v38, v35
	v_fma_f32 v34, -v34, v37, v36
	v_div_fmas_f32 v34, v34, v35, v37
	v_div_fixup_f32 v30, v34, v30, 1.0
	v_div_scale_f32 v34, s[0:1], v29, v29, 1.0
	v_rcp_f32_e32 v35, v34
	v_pk_add_f32 v[4:5], v[4:5], 1.0 op_sel_hi:[1,0]
	v_mul_f32_e32 v2, 0xbfb8aa3b, v2
	v_mul_f32_e32 v3, 0xbfb8aa3b, v3
	v_fma_f32 v36, -v34, v35, 1.0
	v_fmac_f32_e32 v35, v36, v35
	v_div_scale_f32 v36, vcc, 1.0, v29, 1.0
	v_mul_f32_e32 v37, v36, v35
	v_fma_f32 v38, -v34, v37, v36
	v_fmac_f32_e32 v37, v38, v35
	v_fma_f32 v34, -v34, v37, v36
	v_div_fmas_f32 v34, v34, v35, v37
	v_div_fixup_f32 v29, v34, v29, 1.0
	v_div_scale_f32 v34, s[0:1], v28, v28, 1.0
	v_rcp_f32_e32 v35, v34
	v_exp_f32_e32 v2, v2
	v_exp_f32_e32 v3, v3
	v_mul_f32_e32 v0, 0xbfb8aa3b, v0
	v_fma_f32 v36, -v34, v35, 1.0
	v_fmac_f32_e32 v35, v36, v35
	v_div_scale_f32 v36, vcc, 1.0, v28, 1.0
	v_mul_f32_e32 v37, v36, v35
	v_fma_f32 v38, -v34, v37, v36
	v_fmac_f32_e32 v37, v38, v35
	v_fma_f32 v34, -v34, v37, v36
	v_div_fmas_f32 v34, v34, v35, v37
	v_div_fixup_f32 v28, v34, v28, 1.0
	global_store_dwordx4 v[32:33], v[28:31], off offset:64 sc1
	v_pk_add_f32 v[2:3], v[2:3], 1.0 op_sel_hi:[1,0]
	v_mul_f32_e32 v1, 0xbfb8aa3b, v1
	v_div_scale_f32 v28, s[0:1], v27, v27, 1.0
	v_rcp_f32_e32 v29, v28
	v_exp_f32_e32 v0, v0
	v_exp_f32_e32 v1, v1
	v_fma_f32 v30, -v28, v29, 1.0
	v_fmac_f32_e32 v29, v30, v29
	v_div_scale_f32 v30, vcc, 1.0, v27, 1.0
	v_mul_f32_e32 v31, v30, v29
	v_fma_f32 v34, -v28, v31, v30
	v_fmac_f32_e32 v31, v34, v29
	v_fma_f32 v28, -v28, v31, v30
	v_div_fmas_f32 v28, v28, v29, v31
	v_div_fixup_f32 v27, v28, v27, 1.0
	v_div_scale_f32 v28, s[0:1], v26, v26, 1.0
	v_rcp_f32_e32 v29, v28
	v_pk_add_f32 v[0:1], v[0:1], 1.0 op_sel_hi:[1,0]
	v_fma_f32 v30, -v28, v29, 1.0
	v_fmac_f32_e32 v29, v30, v29
	v_div_scale_f32 v30, vcc, 1.0, v26, 1.0
	v_mul_f32_e32 v31, v30, v29
	v_fma_f32 v34, -v28, v31, v30
	v_fmac_f32_e32 v31, v34, v29
	v_fma_f32 v28, -v28, v31, v30
	v_div_fmas_f32 v28, v28, v29, v31
	v_div_fixup_f32 v26, v28, v26, 1.0
	v_div_scale_f32 v28, s[0:1], v25, v25, 1.0
	v_rcp_f32_e32 v29, v28
	s_nop 0
	v_fma_f32 v30, -v28, v29, 1.0
	v_fmac_f32_e32 v29, v30, v29
	v_div_scale_f32 v30, vcc, 1.0, v25, 1.0
	v_mul_f32_e32 v31, v30, v29
	v_fma_f32 v34, -v28, v31, v30
	v_fmac_f32_e32 v31, v34, v29
	v_fma_f32 v28, -v28, v31, v30
	v_div_fmas_f32 v28, v28, v29, v31
	v_div_fixup_f32 v25, v28, v25, 1.0
	v_div_scale_f32 v28, s[0:1], v24, v24, 1.0
	v_rcp_f32_e32 v29, v28
	s_nop 0
	v_fma_f32 v30, -v28, v29, 1.0
	v_fmac_f32_e32 v29, v30, v29
	v_div_scale_f32 v30, vcc, 1.0, v24, 1.0
	v_mul_f32_e32 v31, v30, v29
	v_fma_f32 v34, -v28, v31, v30
	v_fmac_f32_e32 v31, v34, v29
	v_fma_f32 v28, -v28, v31, v30
	v_div_fmas_f32 v28, v28, v29, v31
	v_div_fixup_f32 v24, v28, v24, 1.0
	global_store_dwordx4 v[32:33], v[24:27], off offset:128 sc1
	s_nop 1
	v_div_scale_f32 v24, s[0:1], v23, v23, 1.0
	v_rcp_f32_e32 v25, v24
	v_add_u32_e32 v26, 0xa0, v96
	v_fma_f32 v27, -v24, v25, 1.0
	v_fmac_f32_e32 v25, v27, v25
	v_div_scale_f32 v27, vcc, 1.0, v23, 1.0
	v_mul_f32_e32 v28, v27, v25
	v_fma_f32 v29, -v24, v28, v27
	v_fmac_f32_e32 v28, v29, v25
	v_fma_f32 v24, -v24, v28, v27
	v_div_fmas_f32 v24, v24, v25, v28
	v_div_fixup_f32 v25, v24, v23, 1.0
	v_div_scale_f32 v23, s[0:1], v22, v22, 1.0
	v_rcp_f32_e32 v24, v23
	s_nop 0
	v_fma_f32 v27, -v23, v24, 1.0
	v_fmac_f32_e32 v24, v27, v24
	v_div_scale_f32 v27, vcc, 1.0, v22, 1.0
	v_mul_f32_e32 v28, v27, v24
	v_fma_f32 v29, -v23, v28, v27
	v_fmac_f32_e32 v28, v29, v24
	v_fma_f32 v23, -v23, v28, v27
	v_div_fmas_f32 v23, v23, v24, v28
	v_div_fixup_f32 v24, v23, v22, 1.0
	v_div_scale_f32 v22, s[0:1], v21, v21, 1.0
	v_rcp_f32_e32 v23, v22
	s_nop 0
	v_fma_f32 v27, -v22, v23, 1.0
	v_fmac_f32_e32 v23, v27, v23
	v_div_scale_f32 v27, vcc, 1.0, v21, 1.0
	v_mul_f32_e32 v28, v27, v23
	v_fma_f32 v29, -v22, v28, v27
	v_fmac_f32_e32 v28, v29, v23
	v_fma_f32 v22, -v22, v28, v27
	v_div_fmas_f32 v22, v22, v23, v28
	v_div_fixup_f32 v23, v22, v21, 1.0
	v_div_scale_f32 v21, s[0:1], v20, v20, 1.0
	v_rcp_f32_e32 v22, v21
	s_nop 0
	v_fma_f32 v27, -v21, v22, 1.0
	v_fmac_f32_e32 v22, v27, v22
	v_div_scale_f32 v27, vcc, 1.0, v20, 1.0
	v_mul_f32_e32 v28, v27, v22
	v_fma_f32 v29, -v21, v28, v27
	v_fmac_f32_e32 v28, v29, v22
	v_fma_f32 v21, -v21, v28, v27
	v_div_fmas_f32 v21, v21, v22, v28
	v_div_fixup_f32 v22, v21, v20, 1.0
	v_mad_i64_i32 v[20:21], s[0:1], v26, s4, v[156:157]
	global_store_dwordx4 v[20:21], v[22:25], off sc1
	s_nop 1
	v_div_scale_f32 v22, s[0:1], v19, v19, 1.0
	v_rcp_f32_e32 v23, v22
	s_nop 0
	v_fma_f32 v24, -v22, v23, 1.0
	v_fmac_f32_e32 v23, v24, v23
	v_div_scale_f32 v24, vcc, 1.0, v19, 1.0
	v_mul_f32_e32 v25, v24, v23
	v_fma_f32 v26, -v22, v25, v24
	v_fmac_f32_e32 v25, v26, v23
	v_fma_f32 v22, -v22, v25, v24
	v_div_fmas_f32 v22, v22, v23, v25
	v_div_fixup_f32 v19, v22, v19, 1.0
	v_div_scale_f32 v22, s[0:1], v18, v18, 1.0
	v_rcp_f32_e32 v23, v22
	s_nop 0
	v_fma_f32 v24, -v22, v23, 1.0
	v_fmac_f32_e32 v23, v24, v23
	v_div_scale_f32 v24, vcc, 1.0, v18, 1.0
	v_mul_f32_e32 v25, v24, v23
	v_fma_f32 v26, -v22, v25, v24
	v_fmac_f32_e32 v25, v26, v23
	v_fma_f32 v22, -v22, v25, v24
	v_div_fmas_f32 v22, v22, v23, v25
	v_div_fixup_f32 v18, v22, v18, 1.0
	v_div_scale_f32 v22, s[0:1], v17, v17, 1.0
	v_rcp_f32_e32 v23, v22
	s_nop 0
	v_fma_f32 v24, -v22, v23, 1.0
	v_fmac_f32_e32 v23, v24, v23
	v_div_scale_f32 v24, vcc, 1.0, v17, 1.0
	v_mul_f32_e32 v25, v24, v23
	v_fma_f32 v26, -v22, v25, v24
	v_fmac_f32_e32 v25, v26, v23
	v_fma_f32 v22, -v22, v25, v24
	v_div_fmas_f32 v22, v22, v23, v25
	v_div_fixup_f32 v17, v22, v17, 1.0
	v_div_scale_f32 v22, s[0:1], v16, v16, 1.0
	v_rcp_f32_e32 v23, v22
	s_nop 0
	v_fma_f32 v24, -v22, v23, 1.0
	v_fmac_f32_e32 v23, v24, v23
	v_div_scale_f32 v24, vcc, 1.0, v16, 1.0
	v_mul_f32_e32 v25, v24, v23
	v_fma_f32 v26, -v22, v25, v24
	v_fmac_f32_e32 v25, v26, v23
	v_fma_f32 v22, -v22, v25, v24
	v_div_fmas_f32 v22, v22, v23, v25
	v_div_fixup_f32 v16, v22, v16, 1.0
	global_store_dwordx4 v[20:21], v[16:19], off offset:64 sc1
	s_nop 1
	v_div_scale_f32 v16, s[0:1], v15, v15, 1.0
	v_rcp_f32_e32 v17, v16
	s_nop 0
	v_fma_f32 v18, -v16, v17, 1.0
	v_fmac_f32_e32 v17, v18, v17
	v_div_scale_f32 v18, vcc, 1.0, v15, 1.0
	v_mul_f32_e32 v19, v18, v17
	v_fma_f32 v22, -v16, v19, v18
	v_fmac_f32_e32 v19, v22, v17
	v_fma_f32 v16, -v16, v19, v18
	v_div_fmas_f32 v16, v16, v17, v19
	v_div_fixup_f32 v15, v16, v15, 1.0
	v_div_scale_f32 v16, s[0:1], v14, v14, 1.0
	v_rcp_f32_e32 v17, v16
	s_nop 0
	v_fma_f32 v18, -v16, v17, 1.0
	v_fmac_f32_e32 v17, v18, v17
	v_div_scale_f32 v18, vcc, 1.0, v14, 1.0
	v_mul_f32_e32 v19, v18, v17
	v_fma_f32 v22, -v16, v19, v18
	v_fmac_f32_e32 v19, v22, v17
	v_fma_f32 v16, -v16, v19, v18
	v_div_fmas_f32 v16, v16, v17, v19
	v_div_fixup_f32 v14, v16, v14, 1.0
	v_div_scale_f32 v16, s[0:1], v13, v13, 1.0
	v_rcp_f32_e32 v17, v16
	s_nop 0
	v_fma_f32 v18, -v16, v17, 1.0
	v_fmac_f32_e32 v17, v18, v17
	v_div_scale_f32 v18, vcc, 1.0, v13, 1.0
	v_mul_f32_e32 v19, v18, v17
	v_fma_f32 v22, -v16, v19, v18
	v_fmac_f32_e32 v19, v22, v17
	v_fma_f32 v16, -v16, v19, v18
	v_div_fmas_f32 v16, v16, v17, v19
	v_div_fixup_f32 v13, v16, v13, 1.0
	v_div_scale_f32 v16, s[0:1], v12, v12, 1.0
	v_rcp_f32_e32 v17, v16
	s_nop 0
	v_fma_f32 v18, -v16, v17, 1.0
	v_fmac_f32_e32 v17, v18, v17
	v_div_scale_f32 v18, vcc, 1.0, v12, 1.0
	v_mul_f32_e32 v19, v18, v17
	v_fma_f32 v22, -v16, v19, v18
	v_fmac_f32_e32 v19, v22, v17
	v_fma_f32 v16, -v16, v19, v18
	v_div_fmas_f32 v16, v16, v17, v19
	v_div_fixup_f32 v12, v16, v12, 1.0
	global_store_dwordx4 v[20:21], v[12:15], off offset:128 sc1
	s_nop 1
	v_div_scale_f32 v12, s[0:1], v11, v11, 1.0
	v_rcp_f32_e32 v13, v12
	v_add_u32_e32 v14, 0xb0, v96
	v_fma_f32 v15, -v12, v13, 1.0
	v_fmac_f32_e32 v13, v15, v13
	v_div_scale_f32 v15, vcc, 1.0, v11, 1.0
	v_mul_f32_e32 v16, v15, v13
	v_fma_f32 v17, -v12, v16, v15
	v_fmac_f32_e32 v16, v17, v13
	v_fma_f32 v12, -v12, v16, v15
	v_div_fmas_f32 v12, v12, v13, v16
	v_div_fixup_f32 v13, v12, v11, 1.0
	v_div_scale_f32 v11, s[0:1], v10, v10, 1.0
	v_rcp_f32_e32 v12, v11
	s_nop 0
	v_fma_f32 v15, -v11, v12, 1.0
	v_fmac_f32_e32 v12, v15, v12
	v_div_scale_f32 v15, vcc, 1.0, v10, 1.0
	v_mul_f32_e32 v16, v15, v12
	v_fma_f32 v17, -v11, v16, v15
	v_fmac_f32_e32 v16, v17, v12
	v_fma_f32 v11, -v11, v16, v15
	v_div_fmas_f32 v11, v11, v12, v16
	v_div_fixup_f32 v12, v11, v10, 1.0
	v_div_scale_f32 v10, s[0:1], v9, v9, 1.0
	v_rcp_f32_e32 v11, v10
	s_nop 0
	v_fma_f32 v15, -v10, v11, 1.0
	v_fmac_f32_e32 v11, v15, v11
	v_div_scale_f32 v15, vcc, 1.0, v9, 1.0
	v_mul_f32_e32 v16, v15, v11
	v_fma_f32 v17, -v10, v16, v15
	v_fmac_f32_e32 v16, v17, v11
	v_fma_f32 v10, -v10, v16, v15
	v_div_fmas_f32 v10, v10, v11, v16
	v_div_fixup_f32 v11, v10, v9, 1.0
	v_div_scale_f32 v9, s[0:1], v8, v8, 1.0
	v_rcp_f32_e32 v10, v9
	s_nop 0
	v_fma_f32 v15, -v9, v10, 1.0
	v_fmac_f32_e32 v10, v15, v10
	v_div_scale_f32 v15, vcc, 1.0, v8, 1.0
	v_mul_f32_e32 v16, v15, v10
	v_fma_f32 v17, -v9, v16, v15
	v_fmac_f32_e32 v16, v17, v10
	v_fma_f32 v9, -v9, v16, v15
	v_div_fmas_f32 v9, v9, v10, v16
	v_div_fixup_f32 v10, v9, v8, 1.0
	v_mad_i64_i32 v[8:9], s[0:1], v14, s4, v[156:157]
	global_store_dwordx4 v[8:9], v[10:13], off sc1
	s_nop 1
	v_div_scale_f32 v10, s[0:1], v7, v7, 1.0
	v_rcp_f32_e32 v11, v10
	s_nop 0
	v_fma_f32 v12, -v10, v11, 1.0
	v_fmac_f32_e32 v11, v12, v11
	v_div_scale_f32 v12, vcc, 1.0, v7, 1.0
	v_mul_f32_e32 v13, v12, v11
	v_fma_f32 v14, -v10, v13, v12
	v_fmac_f32_e32 v13, v14, v11
	v_fma_f32 v10, -v10, v13, v12
	v_div_fmas_f32 v10, v10, v11, v13
	v_div_fixup_f32 v7, v10, v7, 1.0
	v_div_scale_f32 v10, s[0:1], v6, v6, 1.0
	v_rcp_f32_e32 v11, v10
	s_nop 0
	v_fma_f32 v12, -v10, v11, 1.0
	v_fmac_f32_e32 v11, v12, v11
	v_div_scale_f32 v12, vcc, 1.0, v6, 1.0
	v_mul_f32_e32 v13, v12, v11
	v_fma_f32 v14, -v10, v13, v12
	v_fmac_f32_e32 v13, v14, v11
	v_fma_f32 v10, -v10, v13, v12
	v_div_fmas_f32 v10, v10, v11, v13
	v_div_fixup_f32 v6, v10, v6, 1.0
	v_div_scale_f32 v10, s[0:1], v5, v5, 1.0
	v_rcp_f32_e32 v11, v10
	s_nop 0
	v_fma_f32 v12, -v10, v11, 1.0
	v_fmac_f32_e32 v11, v12, v11
	v_div_scale_f32 v12, vcc, 1.0, v5, 1.0
	v_mul_f32_e32 v13, v12, v11
	v_fma_f32 v14, -v10, v13, v12
	v_fmac_f32_e32 v13, v14, v11
	v_fma_f32 v10, -v10, v13, v12
	v_div_fmas_f32 v10, v10, v11, v13
	v_div_fixup_f32 v5, v10, v5, 1.0
	v_div_scale_f32 v10, s[0:1], v4, v4, 1.0
	v_rcp_f32_e32 v11, v10
	s_nop 0
	v_fma_f32 v12, -v10, v11, 1.0
	v_fmac_f32_e32 v11, v12, v11
	v_div_scale_f32 v12, vcc, 1.0, v4, 1.0
	v_mul_f32_e32 v13, v12, v11
	v_fma_f32 v14, -v10, v13, v12
	v_fmac_f32_e32 v13, v14, v11
	v_fma_f32 v10, -v10, v13, v12
	v_div_fmas_f32 v10, v10, v11, v13
	v_div_fixup_f32 v4, v10, v4, 1.0
	global_store_dwordx4 v[8:9], v[4:7], off offset:64 sc1
	s_nop 1
	v_div_scale_f32 v4, s[0:1], v3, v3, 1.0
	v_rcp_f32_e32 v5, v4
	s_nop 0
	v_fma_f32 v6, -v4, v5, 1.0
	v_fmac_f32_e32 v5, v6, v5
	v_div_scale_f32 v6, vcc, 1.0, v3, 1.0
	v_mul_f32_e32 v7, v6, v5
	v_fma_f32 v10, -v4, v7, v6
	v_fmac_f32_e32 v7, v10, v5
	v_fma_f32 v4, -v4, v7, v6
	v_div_fmas_f32 v4, v4, v5, v7
	v_div_fixup_f32 v3, v4, v3, 1.0
	v_div_scale_f32 v4, s[0:1], v2, v2, 1.0
	v_rcp_f32_e32 v5, v4
	s_nop 0
	v_fma_f32 v6, -v4, v5, 1.0
	v_fmac_f32_e32 v5, v6, v5
	v_div_scale_f32 v6, vcc, 1.0, v2, 1.0
	v_mul_f32_e32 v7, v6, v5
	v_fma_f32 v10, -v4, v7, v6
	v_fmac_f32_e32 v7, v10, v5
	v_fma_f32 v4, -v4, v7, v6
	v_div_fmas_f32 v4, v4, v5, v7
	v_div_fixup_f32 v2, v4, v2, 1.0
	v_div_scale_f32 v4, s[0:1], v1, v1, 1.0
	v_rcp_f32_e32 v5, v4
	s_nop 0
	v_fma_f32 v6, -v4, v5, 1.0
	v_fmac_f32_e32 v5, v6, v5
	v_div_scale_f32 v6, vcc, 1.0, v1, 1.0
	v_mul_f32_e32 v7, v6, v5
	v_fma_f32 v10, -v4, v7, v6
	v_fmac_f32_e32 v7, v10, v5
	v_fma_f32 v4, -v4, v7, v6
	v_div_fmas_f32 v4, v4, v5, v7
	v_div_fixup_f32 v1, v4, v1, 1.0
	v_div_scale_f32 v4, s[0:1], v0, v0, 1.0
	v_rcp_f32_e32 v5, v4
	s_nop 0
	v_fma_f32 v6, -v4, v5, 1.0
	v_fmac_f32_e32 v5, v6, v5
	v_div_scale_f32 v6, vcc, 1.0, v0, 1.0
	v_mul_f32_e32 v7, v6, v5
	v_fma_f32 v10, -v4, v7, v6
	v_fmac_f32_e32 v7, v10, v5
	v_fma_f32 v4, -v4, v7, v6
	v_div_fmas_f32 v4, v4, v5, v7
	v_div_fixup_f32 v0, v4, v0, 1.0
	global_store_dwordx4 v[8:9], v[0:3], off offset:128 sc1

.LBB0_1051:
	s_ashr_i32 s19, s18, 31
	v_lshl_add_u32 v146, s42, 8, v140
	s_lshl_b64 s[0:1], s[18:19], 22
	v_ashrrev_i32_e32 v147, 31, v146
	v_lshl_add_u64 v[144:145], v[134:135], 0, s[0:1]
	v_lshlrev_b64 v[148:149], 9, v[146:147]
	v_lshl_add_u64 v[148:149], v[144:145], 0, v[148:149]
	global_store_dwordx4 v[148:149], v[124:127], off sc1
	global_store_dwordx4 v[148:149], v[120:123], off offset:64 sc1
	global_store_dwordx4 v[148:149], v[116:119], off offset:128 sc1
	global_store_dwordx4 v[148:149], v[112:115], off offset:192 sc1
	s_nop 1
	v_or_b32_e32 v112, 16, v146
	v_ashrrev_i32_e32 v113, 31, v112
	v_lshlrev_b64 v[112:113], 9, v[112:113]
	v_lshl_add_u64 v[112:113], v[144:145], 0, v[112:113]
	global_store_dwordx4 v[112:113], v[108:111], off sc1
	global_store_dwordx4 v[112:113], v[104:107], off offset:64 sc1
	global_store_dwordx4 v[112:113], v[100:103], off offset:128 sc1
	global_store_dwordx4 v[112:113], v[96:99], off offset:192 sc1
	s_nop 1
	v_or_b32_e32 v96, 32, v146
	v_ashrrev_i32_e32 v97, 31, v96
	v_lshlrev_b64 v[96:97], 9, v[96:97]
	v_lshl_add_u64 v[96:97], v[144:145], 0, v[96:97]
	global_store_dwordx4 v[96:97], v[92:95], off sc1
	global_store_dwordx4 v[96:97], v[88:91], off offset:64 sc1
	global_store_dwordx4 v[96:97], v[84:87], off offset:128 sc1
	global_store_dwordx4 v[96:97], v[80:83], off offset:192 sc1
	s_nop 1
	v_or_b32_e32 v80, 48, v146
	v_ashrrev_i32_e32 v81, 31, v80
	v_lshlrev_b64 v[80:81], 9, v[80:81]
	v_lshl_add_u64 v[80:81], v[144:145], 0, v[80:81]
	global_store_dwordx4 v[80:81], v[76:79], off sc1
	global_store_dwordx4 v[80:81], v[72:75], off offset:64 sc1
	global_store_dwordx4 v[80:81], v[68:71], off offset:128 sc1
	global_store_dwordx4 v[80:81], v[64:67], off offset:192 sc1
	s_nop 1
	v_add_u32_e32 v64, 0x80, v146
	v_ashrrev_i32_e32 v65, 31, v64
	v_lshlrev_b64 v[64:65], 9, v[64:65]
	v_lshl_add_u64 v[64:65], v[144:145], 0, v[64:65]
	global_store_dwordx4 v[64:65], v[60:63], off sc1
	global_store_dwordx4 v[64:65], v[56:59], off offset:64 sc1
	global_store_dwordx4 v[64:65], v[52:55], off offset:128 sc1
	global_store_dwordx4 v[64:65], v[48:51], off offset:192 sc1
	s_nop 1
	v_add_u32_e32 v48, 0x90, v146
	v_ashrrev_i32_e32 v49, 31, v48
	v_lshlrev_b64 v[48:49], 9, v[48:49]
	v_lshl_add_u64 v[48:49], v[144:145], 0, v[48:49]
	global_store_dwordx4 v[48:49], v[44:47], off sc1
	global_store_dwordx4 v[48:49], v[40:43], off offset:64 sc1
	global_store_dwordx4 v[48:49], v[36:39], off offset:128 sc1
	global_store_dwordx4 v[48:49], v[32:35], off offset:192 sc1
	s_nop 1
	v_add_u32_e32 v32, 0xa0, v146
	v_ashrrev_i32_e32 v33, 31, v32
	v_lshlrev_b64 v[32:33], 9, v[32:33]
	v_lshl_add_u64 v[32:33], v[144:145], 0, v[32:33]
	global_store_dwordx4 v[32:33], v[28:31], off sc1
	global_store_dwordx4 v[32:33], v[24:27], off offset:64 sc1
	global_store_dwordx4 v[32:33], v[20:23], off offset:128 sc1
	global_store_dwordx4 v[32:33], v[16:19], off offset:192 sc1
	s_nop 1
	v_add_u32_e32 v16, 0xb0, v146
	v_ashrrev_i32_e32 v17, 31, v16
	v_lshlrev_b64 v[16:17], 9, v[16:17]
	v_lshl_add_u64 v[16:17], v[144:145], 0, v[16:17]
	global_store_dwordx4 v[16:17], v[12:15], off sc1
	global_store_dwordx4 v[16:17], v[8:11], off offset:64 sc1
	global_store_dwordx4 v[16:17], v[4:7], off offset:128 sc1
	global_store_dwordx4 v[16:17], v[0:3], off offset:192 sc1
	s_andn2_b64 vcc, exec, s[2:3]
	s_mov_b64 s[0:1], -1
	s_cbranch_vccnz .LBB0_1037

.LBB0_1410:
	v_lshl_add_u32 v218, s58, 8, v178
	v_ashrrev_i32_e32 v219, 31, v218
	v_lshl_add_u64 v[216:217], s[8:9], 0, v[208:209]
	v_lshlrev_b64 v[220:221], 12, v[218:219]
	v_lshl_add_u64 v[144:145], v[216:217], 0, v[220:221]
	global_load_dwordx4 v[172:175], v[144:145], off
	global_load_dwordx4 v[168:171], v[144:145], off offset:64
	global_load_dwordx4 v[164:167], v[144:145], off offset:128
	global_load_dwordx4 v[160:163], v[144:145], off offset:192
	v_or_b32_e32 v144, 16, v218
	v_ashrrev_i32_e32 v145, 31, v144
	v_lshlrev_b64 v[222:223], 12, v[144:145]
	v_lshl_add_u64 v[144:145], v[216:217], 0, v[222:223]
	global_load_dwordx4 v[156:159], v[144:145], off
	global_load_dwordx4 v[152:155], v[144:145], off offset:64
	global_load_dwordx4 v[148:151], v[144:145], off offset:128
	s_nop 0
	global_load_dwordx4 v[144:147], v[144:145], off offset:192
	v_or_b32_e32 v238, 32, v218
	v_ashrrev_i32_e32 v239, 31, v238
	v_lshl_add_u64 v[240:241], s[38:39], 0, v[220:221]
	v_lshl_add_u64 v[222:223], s[38:39], 0, v[222:223]
	v_lshlrev_b64 v[220:221], 12, v[238:239]
	v_lshl_add_u64 v[238:239], v[240:241], 0, v[208:209]
	v_lshl_add_u64 v[222:223], v[222:223], 0, v[208:209]
	v_lshl_add_u64 v[240:241], v[216:217], 0, v[220:221]
	s_and_b64 vcc, exec, s[4:5]
	s_mov_b64 s[4:5], -1
	s_waitcnt vmcnt(0)
	v_pk_fma_f32 v[138:139], v[138:139], v[98:99], v[174:175]
	v_pk_fma_f32 v[136:137], v[136:137], v[96:97], v[172:173]
	v_pk_fma_f32 v[142:143], v[142:143], v[102:103], v[170:171]
	v_pk_fma_f32 v[140:141], v[140:141], v[100:101], v[168:169]
	v_pk_fma_f32 v[166:167], v[134:135], v[106:107], v[166:167]
	v_pk_fma_f32 v[126:127], v[126:127], v[98:99], v[158:159]
	v_pk_fma_f32 v[124:125], v[124:125], v[96:97], v[156:157]
	v_pk_fma_f32 v[164:165], v[132:133], v[104:105], v[164:165]
	v_pk_fma_f32 v[144:145], v[112:113], v[108:109], v[144:145]
	v_pk_fma_f32 v[162:163], v[130:131], v[110:111], v[162:163]
	v_pk_fma_f32 v[160:161], v[128:129], v[108:109], v[160:161]
	v_pk_add_f32 v[130:131], v[202:203], v[138:139]
	v_pk_add_f32 v[128:129], v[200:201], v[136:137]
	v_pk_fma_f32 v[122:123], v[122:123], v[102:103], v[154:155]
	v_pk_fma_f32 v[120:121], v[120:121], v[100:101], v[152:153]
	v_pk_fma_f32 v[150:151], v[118:119], v[106:107], v[150:151]
	v_pk_fma_f32 v[148:149], v[116:117], v[104:105], v[148:149]
	v_pk_fma_f32 v[146:147], v[114:115], v[110:111], v[146:147]
	v_pk_add_f32 v[114:115], v[202:203], v[126:127]
	v_pk_add_f32 v[112:113], v[200:201], v[124:125]
	v_pk_add_f32 v[124:125], v[206:207], v[144:145]
	v_pk_add_f32 v[134:135], v[204:205], v[142:143]
	v_pk_add_f32 v[132:133], v[198:199], v[140:141]
	v_pk_add_f32 v[138:139], v[212:213], v[166:167]
	v_pk_add_f32 v[136:137], v[210:211], v[164:165]
	v_pk_add_f32 v[142:143], v[214:215], v[162:163]
	v_pk_add_f32 v[140:141], v[206:207], v[160:161]
	global_store_dwordx4 v[238:239], v[128:131], off sc1
	global_store_dwordx4 v[238:239], v[132:135], off offset:64 sc1
	global_store_dwordx4 v[238:239], v[136:139], off offset:128 sc1
	global_store_dwordx4 v[238:239], v[140:143], off offset:192 sc1
	v_pk_add_f32 v[118:119], v[204:205], v[122:123]
	v_pk_add_f32 v[116:117], v[198:199], v[120:121]
	v_pk_add_f32 v[122:123], v[212:213], v[150:151]
	v_pk_add_f32 v[120:121], v[210:211], v[148:149]
	v_pk_add_f32 v[126:127], v[214:215], v[146:147]
	global_store_dwordx4 v[222:223], v[112:115], off sc1
	global_store_dwordx4 v[222:223], v[116:119], off offset:64 sc1
	global_store_dwordx4 v[222:223], v[120:123], off offset:128 sc1
	global_store_dwordx4 v[222:223], v[124:127], off offset:192 sc1
	global_load_dwordx4 v[112:115], v[240:241], off
	global_load_dwordx4 v[116:119], v[240:241], off offset:64
	v_or_b32_e32 v124, 48, v218
	v_ashrrev_i32_e32 v125, 31, v124
	v_lshlrev_b64 v[146:147], 12, v[124:125]
	global_load_dwordx4 v[120:123], v[240:241], off offset:128
	global_load_dwordx4 v[124:127], v[240:241], off offset:192
	v_lshl_add_u64 v[128:129], v[216:217], 0, v[146:147]
	global_load_dwordx4 v[140:143], v[128:129], off
	global_load_dwordx4 v[136:139], v[128:129], off offset:64
	global_load_dwordx4 v[132:135], v[128:129], off offset:128
	s_nop 0
	global_load_dwordx4 v[128:131], v[128:129], off offset:192
	v_lshl_add_u64 v[148:149], s[38:39], 0, v[220:221]
	v_add_u32_e32 v144, 0x80, v218
	v_lshl_add_u64 v[146:147], s[38:39], 0, v[146:147]
	v_lshl_add_u64 v[148:149], v[148:149], 0, v[208:209]
	v_ashrrev_i32_e32 v145, 31, v144
	v_lshl_add_u64 v[146:147], v[146:147], 0, v[208:209]
	v_lshlrev_b64 v[144:145], 12, v[144:145]
	v_lshl_add_u64 v[150:151], v[216:217], 0, v[144:145]
	s_waitcnt vmcnt(0)
	v_pk_fma_f32 v[94:95], v[94:95], v[98:99], v[114:115]
	v_pk_fma_f32 v[92:93], v[92:93], v[96:97], v[112:113]
	v_pk_fma_f32 v[90:91], v[90:91], v[102:103], v[118:119]
	v_pk_fma_f32 v[88:89], v[88:89], v[100:101], v[116:117]
	v_pk_fma_f32 v[86:87], v[86:87], v[106:107], v[122:123]
	v_pk_fma_f32 v[80:81], v[80:81], v[108:109], v[124:125]
	v_pk_fma_f32 v[84:85], v[84:85], v[104:105], v[120:121]
	v_pk_fma_f32 v[82:83], v[82:83], v[110:111], v[126:127]
	v_pk_fma_f32 v[112:113], v[78:79], v[98:99], v[142:143]
	v_pk_fma_f32 v[114:115], v[76:77], v[96:97], v[140:141]
	v_pk_fma_f32 v[116:117], v[74:75], v[102:103], v[138:139]
	v_pk_fma_f32 v[118:119], v[72:73], v[100:101], v[136:137]
	v_pk_fma_f32 v[120:121], v[70:71], v[106:107], v[134:135]
	v_pk_fma_f32 v[122:123], v[68:69], v[104:105], v[132:133]
	v_pk_fma_f32 v[124:125], v[66:67], v[110:111], v[130:131]
	v_pk_fma_f32 v[126:127], v[64:65], v[108:109], v[128:129]
	v_pk_add_f32 v[66:67], v[202:203], v[94:95]
	v_pk_add_f32 v[64:65], v[200:201], v[92:93]
	v_pk_add_f32 v[76:77], v[206:207], v[80:81]
	v_pk_add_f32 v[70:71], v[204:205], v[90:91]
	v_pk_add_f32 v[68:69], v[198:199], v[88:89]
	v_pk_add_f32 v[74:75], v[212:213], v[86:87]
	v_pk_add_f32 v[72:73], v[210:211], v[84:85]
	v_pk_add_f32 v[78:79], v[214:215], v[82:83]
	v_pk_add_f32 v[82:83], v[202:203], v[112:113]
	v_pk_add_f32 v[80:81], v[200:201], v[114:115]
	v_pk_add_f32 v[86:87], v[204:205], v[116:117]
	v_pk_add_f32 v[84:85], v[198:199], v[118:119]
	v_pk_add_f32 v[90:91], v[212:213], v[120:121]
	v_pk_add_f32 v[88:89], v[210:211], v[122:123]
	v_pk_add_f32 v[94:95], v[214:215], v[124:125]
	v_pk_add_f32 v[92:93], v[206:207], v[126:127]
	global_store_dwordx4 v[148:149], v[64:67], off sc1
	global_store_dwordx4 v[148:149], v[68:71], off offset:64 sc1
	global_store_dwordx4 v[148:149], v[72:75], off offset:128 sc1
	global_store_dwordx4 v[148:149], v[76:79], off offset:192 sc1
	global_store_dwordx4 v[146:147], v[80:83], off sc1
	global_store_dwordx4 v[146:147], v[84:87], off offset:64 sc1
	global_store_dwordx4 v[146:147], v[88:91], off offset:128 sc1
	global_store_dwordx4 v[146:147], v[92:95], off offset:192 sc1
	v_add_u32_e32 v76, 0x90, v218
	v_ashrrev_i32_e32 v77, 31, v76
	v_lshlrev_b64 v[112:113], 12, v[76:77]
	global_load_dwordx4 v[64:67], v[150:151], off
	global_load_dwordx4 v[68:71], v[150:151], off offset:64
	global_load_dwordx4 v[72:75], v[150:151], off offset:128
	global_load_dwordx4 v[76:79], v[150:151], off offset:192
	v_lshl_add_u64 v[80:81], v[216:217], 0, v[112:113]
	global_load_dwordx4 v[92:95], v[80:81], off
	global_load_dwordx4 v[88:91], v[80:81], off offset:64
	global_load_dwordx4 v[84:87], v[80:81], off offset:128
	s_nop 0
	global_load_dwordx4 v[80:83], v[80:81], off offset:192
	v_lshl_add_u64 v[116:117], s[38:39], 0, v[144:145]
	v_add_u32_e32 v114, 0xa0, v218
	v_lshl_add_u64 v[112:113], s[38:39], 0, v[112:113]
	v_lshl_add_u64 v[116:117], v[116:117], 0, v[208:209]
	v_ashrrev_i32_e32 v115, 31, v114
	v_lshl_add_u64 v[112:113], v[112:113], 0, v[208:209]
	v_lshlrev_b64 v[114:115], 12, v[114:115]
	v_lshl_add_u64 v[118:119], v[216:217], 0, v[114:115]
	s_waitcnt vmcnt(0)
	v_pk_fma_f32 v[62:63], v[62:63], v[98:99], v[66:67]
	v_pk_fma_f32 v[60:61], v[60:61], v[96:97], v[64:65]
	v_pk_fma_f32 v[58:59], v[58:59], v[102:103], v[70:71]
	v_pk_fma_f32 v[48:49], v[48:49], v[108:109], v[76:77]
	v_pk_fma_f32 v[56:57], v[56:57], v[100:101], v[68:69]
	v_pk_fma_f32 v[54:55], v[54:55], v[106:107], v[74:75]
	v_pk_fma_f32 v[52:53], v[52:53], v[104:105], v[72:73]
	v_pk_fma_f32 v[50:51], v[50:51], v[110:111], v[78:79]
	v_pk_fma_f32 v[64:65], v[46:47], v[98:99], v[94:95]
	v_pk_fma_f32 v[66:67], v[44:45], v[96:97], v[92:93]
	v_pk_fma_f32 v[68:69], v[42:43], v[102:103], v[90:91]
	v_pk_fma_f32 v[70:71], v[40:41], v[100:101], v[88:89]
	v_pk_fma_f32 v[72:73], v[38:39], v[106:107], v[86:87]
	v_pk_fma_f32 v[74:75], v[36:37], v[104:105], v[84:85]
	v_pk_fma_f32 v[76:77], v[34:35], v[110:111], v[82:83]
	v_pk_fma_f32 v[78:79], v[32:33], v[108:109], v[80:81]
	v_pk_add_f32 v[34:35], v[202:203], v[62:63]
	v_pk_add_f32 v[32:33], v[200:201], v[60:61]
	v_pk_add_f32 v[44:45], v[206:207], v[48:49]
	v_pk_add_f32 v[38:39], v[204:205], v[58:59]
	v_pk_add_f32 v[36:37], v[198:199], v[56:57]
	v_pk_add_f32 v[42:43], v[212:213], v[54:55]
	v_pk_add_f32 v[40:41], v[210:211], v[52:53]
	v_pk_add_f32 v[46:47], v[214:215], v[50:51]
	v_pk_add_f32 v[50:51], v[202:203], v[64:65]
	v_pk_add_f32 v[48:49], v[200:201], v[66:67]
	v_pk_add_f32 v[54:55], v[204:205], v[68:69]
	v_pk_add_f32 v[52:53], v[198:199], v[70:71]
	v_pk_add_f32 v[58:59], v[212:213], v[72:73]
	v_pk_add_f32 v[56:57], v[210:211], v[74:75]
	v_pk_add_f32 v[62:63], v[214:215], v[76:77]
	v_pk_add_f32 v[60:61], v[206:207], v[78:79]
	global_store_dwordx4 v[116:117], v[32:35], off sc1
	global_store_dwordx4 v[116:117], v[36:39], off offset:64 sc1
	global_store_dwordx4 v[116:117], v[40:43], off offset:128 sc1
	global_store_dwordx4 v[116:117], v[44:47], off offset:192 sc1
	global_store_dwordx4 v[112:113], v[48:51], off sc1
	global_store_dwordx4 v[112:113], v[52:55], off offset:64 sc1
	global_store_dwordx4 v[112:113], v[56:59], off offset:128 sc1
	global_store_dwordx4 v[112:113], v[60:63], off offset:192 sc1
	v_add_u32_e32 v44, 0xb0, v218
	v_ashrrev_i32_e32 v45, 31, v44
	v_lshlrev_b64 v[64:65], 12, v[44:45]
	global_load_dwordx4 v[32:35], v[118:119], off
	global_load_dwordx4 v[36:39], v[118:119], off offset:64
	v_lshl_add_u64 v[60:61], v[216:217], 0, v[64:65]
	global_load_dwordx4 v[40:43], v[118:119], off offset:128
	global_load_dwordx4 v[44:47], v[118:119], off offset:192
	global_load_dwordx4 v[48:51], v[60:61], off
	global_load_dwordx4 v[52:55], v[60:61], off offset:64
	global_load_dwordx4 v[56:59], v[60:61], off offset:128
	s_nop 0
	global_load_dwordx4 v[60:63], v[60:61], off offset:192
	v_lshl_add_u64 v[66:67], s[38:39], 0, v[114:115]
	v_lshl_add_u64 v[64:65], s[38:39], 0, v[64:65]
	v_lshl_add_u64 v[66:67], v[66:67], 0, v[208:209]
	v_lshl_add_u64 v[64:65], v[64:65], 0, v[208:209]
	s_waitcnt vmcnt(0)
	v_pk_fma_f32 v[30:31], v[30:31], v[98:99], v[34:35]
	v_pk_fma_f32 v[28:29], v[28:29], v[96:97], v[32:33]
	v_pk_fma_f32 v[26:27], v[26:27], v[102:103], v[38:39]
	v_pk_fma_f32 v[24:25], v[24:25], v[100:101], v[36:37]
	v_pk_fma_f32 v[22:23], v[22:23], v[106:107], v[42:43]
	v_pk_fma_f32 v[20:21], v[20:21], v[104:105], v[40:41]
	v_pk_fma_f32 v[18:19], v[18:19], v[110:111], v[46:47]
	v_pk_fma_f32 v[16:17], v[16:17], v[108:109], v[44:45]
	v_pk_fma_f32 v[32:33], v[14:15], v[98:99], v[50:51]
	v_pk_fma_f32 v[34:35], v[12:13], v[96:97], v[48:49]
	v_pk_fma_f32 v[36:37], v[10:11], v[102:103], v[54:55]
	v_pk_fma_f32 v[38:39], v[8:9], v[100:101], v[52:53]
	v_pk_fma_f32 v[40:41], v[6:7], v[106:107], v[58:59]
	v_pk_fma_f32 v[42:43], v[4:5], v[104:105], v[56:57]
	v_pk_fma_f32 v[44:45], v[2:3], v[110:111], v[62:63]
	v_pk_fma_f32 v[46:47], v[0:1], v[108:109], v[60:61]
	v_pk_add_f32 v[2:3], v[202:203], v[30:31]
	v_pk_add_f32 v[0:1], v[200:201], v[28:29]
	v_pk_add_f32 v[6:7], v[204:205], v[26:27]
	v_pk_add_f32 v[4:5], v[198:199], v[24:25]
	v_pk_add_f32 v[10:11], v[212:213], v[22:23]
	v_pk_add_f32 v[8:9], v[210:211], v[20:21]
	v_pk_add_f32 v[14:15], v[214:215], v[18:19]
	v_pk_add_f32 v[12:13], v[206:207], v[16:17]
	v_pk_add_f32 v[18:19], v[202:203], v[32:33]
	v_pk_add_f32 v[16:17], v[200:201], v[34:35]
	v_pk_add_f32 v[22:23], v[204:205], v[36:37]
	v_pk_add_f32 v[20:21], v[198:199], v[38:39]
	v_pk_add_f32 v[26:27], v[212:213], v[40:41]
	v_pk_add_f32 v[24:25], v[210:211], v[42:43]
	v_pk_add_f32 v[30:31], v[214:215], v[44:45]
	v_pk_add_f32 v[28:29], v[206:207], v[46:47]
	global_store_dwordx4 v[66:67], v[0:3], off sc1
	global_store_dwordx4 v[66:67], v[4:7], off offset:64 sc1
	global_store_dwordx4 v[66:67], v[8:11], off offset:128 sc1
	global_store_dwordx4 v[66:67], v[12:15], off offset:192 sc1
	global_store_dwordx4 v[64:65], v[16:19], off sc1
	global_store_dwordx4 v[64:65], v[20:23], off offset:64 sc1
	global_store_dwordx4 v[64:65], v[24:27], off offset:128 sc1
	global_store_dwordx4 v[64:65], v[28:31], off offset:192 sc1
	s_cbranch_vccnz .LBB0_1384
	s_andn2_b64 vcc, exec, s[26:27]
	s_cbranch_vccnz .LBB0_1383
	s_barrier
	s_branch .LBB0_1383

.LBB0_1619:
	s_lshr_b32 s0, s44, 5
	s_mulk_i32 s0, 0x1800
	s_ashr_i32 s1, s0, 31
	v_lshl_or_b32 v64, s45, 8, v162
	s_lshl_b64 s[0:1], s[0:1], 2
	v_ashrrev_i32_e32 v65, 31, v64
	v_lshl_add_u32 v158, s44, 8, v160
	s_add_u32 s0, s31, s0
	v_lshlrev_b64 v[154:155], 2, v[64:65]
	v_ashrrev_i32_e32 v159, 31, v158
	s_addc_u32 s1, s33, s1
	v_lshl_add_u64 v[156:157], s[38:39], 0, v[154:155]
	v_lshlrev_b64 v[208:209], 12, v[158:159]
	v_or_b32_e32 v192, 16, v158
	v_lshl_add_u64 v[64:65], s[0:1], 0, v[154:155]
	v_lshl_add_u64 v[188:189], v[156:157], 0, v[208:209]
	v_ashrrev_i32_e32 v193, 31, v192
	global_load_dwordx4 v[76:79], v[64:65], off
	global_load_dwordx4 v[72:75], v[64:65], off offset:64
	global_load_dwordx4 v[68:71], v[64:65], off offset:128
	s_nop 0
	global_load_dwordx4 v[64:67], v[64:65], off offset:192
	s_nop 0
	global_load_dwordx4 v[164:167], v[188:189], off
	global_load_dwordx4 v[168:171], v[188:189], off offset:64
	global_load_dwordx4 v[172:175], v[188:189], off offset:128
	s_nop 0
	global_load_dwordx4 v[188:191], v[188:189], off offset:192
	v_lshlrev_b64 v[210:211], 12, v[192:193]
	v_lshl_add_u64 v[204:205], v[156:157], 0, v[210:211]
	global_load_dwordx4 v[192:195], v[204:205], off
	global_load_dwordx4 v[196:199], v[204:205], off offset:64
	global_load_dwordx4 v[200:203], v[204:205], off offset:128
	s_nop 0
	global_load_dwordx4 v[204:207], v[204:205], off offset:192
	v_lshl_add_u64 v[208:209], s[38:39], 0, v[208:209]
	v_lshl_add_u64 v[208:209], v[208:209], 0, v[154:155]
	s_mov_b64 s[0:1], -1
	s_and_b64 vcc, exec, s[2:3]
	s_waitcnt vmcnt(0)
	v_pk_fma_f32 v[142:143], v[142:143], v[78:79], v[166:167]
	v_pk_fma_f32 v[140:141], v[140:141], v[76:77], v[164:165]
	v_pk_fma_f32 v[138:139], v[138:139], v[74:75], v[170:171]
	v_pk_fma_f32 v[130:131], v[130:131], v[66:67], v[190:191]
	v_pk_fma_f32 v[128:129], v[128:129], v[64:65], v[188:189]
	v_pk_add_f32 v[130:131], v[130:131], 0 op_sel_hi:[1,0]
	v_pk_add_f32 v[128:129], v[128:129], 0 op_sel_hi:[1,0]
	global_store_dwordx4 v[208:209], v[128:131], off offset:192 sc1
	v_pk_fma_f32 v[114:115], v[114:115], v[66:67], v[206:207]
	v_pk_fma_f32 v[112:113], v[112:113], v[64:65], v[204:205]
	v_lshl_add_u64 v[128:129], s[38:39], 0, v[210:211]
	v_lshl_add_u64 v[128:129], v[128:129], 0, v[154:155]
	v_pk_add_f32 v[114:115], v[114:115], 0 op_sel_hi:[1,0]
	v_pk_add_f32 v[112:113], v[112:113], 0 op_sel_hi:[1,0]
	v_pk_fma_f32 v[136:137], v[136:137], v[72:73], v[168:169]
	v_pk_fma_f32 v[134:135], v[134:135], v[70:71], v[174:175]
	v_pk_fma_f32 v[132:133], v[132:133], v[68:69], v[172:173]
	v_pk_fma_f32 v[126:127], v[126:127], v[78:79], v[194:195]
	v_pk_fma_f32 v[124:125], v[124:125], v[76:77], v[192:193]
	v_pk_fma_f32 v[122:123], v[122:123], v[74:75], v[198:199]
	v_pk_fma_f32 v[120:121], v[120:121], v[72:73], v[196:197]
	v_pk_fma_f32 v[118:119], v[118:119], v[70:71], v[202:203]
	v_pk_fma_f32 v[116:117], v[116:117], v[68:69], v[200:201]
	global_store_dwordx4 v[128:129], v[112:115], off offset:192 sc1
	v_pk_add_f32 v[142:143], v[142:143], 0 op_sel_hi:[1,0]
	v_pk_add_f32 v[140:141], v[140:141], 0 op_sel_hi:[1,0]
	v_or_b32_e32 v112, 32, v158
	v_pk_add_f32 v[138:139], v[138:139], 0 op_sel_hi:[1,0]
	v_pk_add_f32 v[136:137], v[136:137], 0 op_sel_hi:[1,0]
	v_pk_add_f32 v[134:135], v[134:135], 0 op_sel_hi:[1,0]
	v_pk_add_f32 v[132:133], v[132:133], 0 op_sel_hi:[1,0]
	v_pk_add_f32 v[126:127], v[126:127], 0 op_sel_hi:[1,0]
	v_pk_add_f32 v[124:125], v[124:125], 0 op_sel_hi:[1,0]
	v_pk_add_f32 v[122:123], v[122:123], 0 op_sel_hi:[1,0]
	v_pk_add_f32 v[120:121], v[120:121], 0 op_sel_hi:[1,0]
	v_pk_add_f32 v[118:119], v[118:119], 0 op_sel_hi:[1,0]
	v_pk_add_f32 v[116:117], v[116:117], 0 op_sel_hi:[1,0]
	v_ashrrev_i32_e32 v113, 31, v112
	global_store_dwordx4 v[208:209], v[140:143], off sc1
	global_store_dwordx4 v[208:209], v[136:139], off offset:64 sc1
	global_store_dwordx4 v[208:209], v[132:135], off offset:128 sc1
	global_store_dwordx4 v[128:129], v[124:127], off sc1
	global_store_dwordx4 v[128:129], v[120:123], off offset:64 sc1
	global_store_dwordx4 v[128:129], v[116:119], off offset:128 sc1
	v_lshlrev_b64 v[164:165], 12, v[112:113]
	v_or_b32_e32 v128, 48, v158
	v_lshl_add_u64 v[124:125], v[156:157], 0, v[164:165]
	v_ashrrev_i32_e32 v129, 31, v128
	global_load_dwordx4 v[112:115], v[124:125], off
	global_load_dwordx4 v[116:119], v[124:125], off offset:64
	global_load_dwordx4 v[120:123], v[124:125], off offset:128
	s_nop 0
	global_load_dwordx4 v[124:127], v[124:125], off offset:192
	v_lshlrev_b64 v[166:167], 12, v[128:129]
	v_lshl_add_u64 v[140:141], v[156:157], 0, v[166:167]
	global_load_dwordx4 v[128:131], v[140:141], off
	global_load_dwordx4 v[132:135], v[140:141], off offset:64
	global_load_dwordx4 v[136:139], v[140:141], off offset:128
	s_nop 0
	global_load_dwordx4 v[140:143], v[140:141], off offset:192
	v_lshl_add_u64 v[164:165], s[38:39], 0, v[164:165]
	v_lshl_add_u64 v[164:165], v[164:165], 0, v[154:155]
	s_waitcnt vmcnt(0)
	v_pk_fma_f32 v[110:111], v[110:111], v[78:79], v[114:115]
	v_pk_fma_f32 v[108:109], v[108:109], v[76:77], v[112:113]
	v_pk_fma_f32 v[106:107], v[106:107], v[74:75], v[118:119]
	v_pk_fma_f32 v[98:99], v[98:99], v[66:67], v[126:127]
	v_pk_fma_f32 v[96:97], v[96:97], v[64:65], v[124:125]
	v_pk_add_f32 v[98:99], v[98:99], 0 op_sel_hi:[1,0]
	v_pk_add_f32 v[96:97], v[96:97], 0 op_sel_hi:[1,0]
	global_store_dwordx4 v[164:165], v[96:99], off offset:192 sc1
	v_pk_fma_f32 v[82:83], v[82:83], v[66:67], v[142:143]
	v_pk_fma_f32 v[80:81], v[80:81], v[64:65], v[140:141]
	v_lshl_add_u64 v[96:97], s[38:39], 0, v[166:167]
	v_lshl_add_u64 v[96:97], v[96:97], 0, v[154:155]
	v_pk_add_f32 v[82:83], v[82:83], 0 op_sel_hi:[1,0]
	v_pk_add_f32 v[80:81], v[80:81], 0 op_sel_hi:[1,0]
	v_pk_fma_f32 v[104:105], v[104:105], v[72:73], v[116:117]
	v_pk_fma_f32 v[102:103], v[102:103], v[70:71], v[122:123]
	v_pk_fma_f32 v[100:101], v[100:101], v[68:69], v[120:121]
	v_pk_fma_f32 v[94:95], v[94:95], v[78:79], v[130:131]
	v_pk_fma_f32 v[92:93], v[92:93], v[76:77], v[128:129]
	v_pk_fma_f32 v[90:91], v[90:91], v[74:75], v[134:135]
	v_pk_fma_f32 v[88:89], v[88:89], v[72:73], v[132:133]
	v_pk_fma_f32 v[86:87], v[86:87], v[70:71], v[138:139]
	v_pk_fma_f32 v[84:85], v[84:85], v[68:69], v[136:137]
	global_store_dwordx4 v[96:97], v[80:83], off offset:192 sc1
	v_pk_add_f32 v[110:111], v[110:111], 0 op_sel_hi:[1,0]
	v_pk_add_f32 v[108:109], v[108:109], 0 op_sel_hi:[1,0]
	v_add_u32_e32 v80, 0x80, v158
	v_pk_add_f32 v[106:107], v[106:107], 0 op_sel_hi:[1,0]
	v_pk_add_f32 v[104:105], v[104:105], 0 op_sel_hi:[1,0]
	v_pk_add_f32 v[102:103], v[102:103], 0 op_sel_hi:[1,0]
	v_pk_add_f32 v[100:101], v[100:101], 0 op_sel_hi:[1,0]
	v_pk_add_f32 v[94:95], v[94:95], 0 op_sel_hi:[1,0]
	v_pk_add_f32 v[92:93], v[92:93], 0 op_sel_hi:[1,0]
	v_pk_add_f32 v[90:91], v[90:91], 0 op_sel_hi:[1,0]
	v_pk_add_f32 v[88:89], v[88:89], 0 op_sel_hi:[1,0]
	v_pk_add_f32 v[86:87], v[86:87], 0 op_sel_hi:[1,0]
	v_pk_add_f32 v[84:85], v[84:85], 0 op_sel_hi:[1,0]
	v_ashrrev_i32_e32 v81, 31, v80
	global_store_dwordx4 v[164:165], v[108:111], off sc1
	global_store_dwordx4 v[164:165], v[104:107], off offset:64 sc1
	global_store_dwordx4 v[164:165], v[100:103], off offset:128 sc1
	global_store_dwordx4 v[96:97], v[92:95], off sc1
	global_store_dwordx4 v[96:97], v[88:91], off offset:64 sc1
	global_store_dwordx4 v[96:97], v[84:87], off offset:128 sc1
	v_lshlrev_b64 v[112:113], 12, v[80:81]
	v_add_u32_e32 v96, 0x90, v158
	v_lshl_add_u64 v[92:93], v[156:157], 0, v[112:113]
	v_ashrrev_i32_e32 v97, 31, v96
	global_load_dwordx4 v[80:83], v[92:93], off
	global_load_dwordx4 v[84:87], v[92:93], off offset:64
	global_load_dwordx4 v[88:91], v[92:93], off offset:128
	s_nop 0
	global_load_dwordx4 v[92:95], v[92:93], off offset:192
	v_lshlrev_b64 v[114:115], 12, v[96:97]
	v_lshl_add_u64 v[108:109], v[156:157], 0, v[114:115]
	global_load_dwordx4 v[96:99], v[108:109], off
	global_load_dwordx4 v[100:103], v[108:109], off offset:64
	global_load_dwordx4 v[104:107], v[108:109], off offset:128
	s_nop 0
	global_load_dwordx4 v[108:111], v[108:109], off offset:192
	v_lshl_add_u64 v[112:113], s[38:39], 0, v[112:113]
	v_lshl_add_u64 v[112:113], v[112:113], 0, v[154:155]
	s_waitcnt vmcnt(0)
	v_pk_fma_f32 v[62:63], v[62:63], v[78:79], v[82:83]
	v_pk_fma_f32 v[60:61], v[60:61], v[76:77], v[80:81]
	v_pk_fma_f32 v[58:59], v[58:59], v[74:75], v[86:87]
	v_pk_fma_f32 v[50:51], v[50:51], v[66:67], v[94:95]
	v_pk_fma_f32 v[48:49], v[48:49], v[64:65], v[92:93]
	v_pk_add_f32 v[50:51], v[50:51], 0 op_sel_hi:[1,0]
	v_pk_add_f32 v[48:49], v[48:49], 0 op_sel_hi:[1,0]
	global_store_dwordx4 v[112:113], v[48:51], off offset:192 sc1
	v_pk_fma_f32 v[34:35], v[34:35], v[66:67], v[110:111]
	v_pk_fma_f32 v[32:33], v[32:33], v[64:65], v[108:109]
	v_lshl_add_u64 v[48:49], s[38:39], 0, v[114:115]
	v_lshl_add_u64 v[48:49], v[48:49], 0, v[154:155]
	v_pk_add_f32 v[34:35], v[34:35], 0 op_sel_hi:[1,0]
	v_pk_add_f32 v[32:33], v[32:33], 0 op_sel_hi:[1,0]
	v_pk_fma_f32 v[56:57], v[56:57], v[72:73], v[84:85]
	v_pk_fma_f32 v[54:55], v[54:55], v[70:71], v[90:91]
	v_pk_fma_f32 v[52:53], v[52:53], v[68:69], v[88:89]
	v_pk_fma_f32 v[46:47], v[46:47], v[78:79], v[98:99]
	v_pk_fma_f32 v[44:45], v[44:45], v[76:77], v[96:97]
	v_pk_fma_f32 v[42:43], v[42:43], v[74:75], v[102:103]
	v_pk_fma_f32 v[40:41], v[40:41], v[72:73], v[100:101]
	v_pk_fma_f32 v[38:39], v[38:39], v[70:71], v[106:107]
	v_pk_fma_f32 v[36:37], v[36:37], v[68:69], v[104:105]
	global_store_dwordx4 v[48:49], v[32:35], off offset:192 sc1
	v_pk_add_f32 v[62:63], v[62:63], 0 op_sel_hi:[1,0]
	v_pk_add_f32 v[60:61], v[60:61], 0 op_sel_hi:[1,0]
	v_add_u32_e32 v32, 0xa0, v158
	v_pk_add_f32 v[58:59], v[58:59], 0 op_sel_hi:[1,0]
	v_pk_add_f32 v[56:57], v[56:57], 0 op_sel_hi:[1,0]
	v_pk_add_f32 v[54:55], v[54:55], 0 op_sel_hi:[1,0]
	v_pk_add_f32 v[52:53], v[52:53], 0 op_sel_hi:[1,0]
	v_pk_add_f32 v[46:47], v[46:47], 0 op_sel_hi:[1,0]
	v_pk_add_f32 v[44:45], v[44:45], 0 op_sel_hi:[1,0]
	v_pk_add_f32 v[42:43], v[42:43], 0 op_sel_hi:[1,0]
	v_pk_add_f32 v[40:41], v[40:41], 0 op_sel_hi:[1,0]
	v_pk_add_f32 v[38:39], v[38:39], 0 op_sel_hi:[1,0]
	v_pk_add_f32 v[36:37], v[36:37], 0 op_sel_hi:[1,0]
	v_ashrrev_i32_e32 v33, 31, v32
	global_store_dwordx4 v[112:113], v[60:63], off sc1
	global_store_dwordx4 v[112:113], v[56:59], off offset:64 sc1
	global_store_dwordx4 v[112:113], v[52:55], off offset:128 sc1
	global_store_dwordx4 v[48:49], v[44:47], off sc1
	global_store_dwordx4 v[48:49], v[40:43], off offset:64 sc1
	global_store_dwordx4 v[48:49], v[36:39], off offset:128 sc1
	v_lshlrev_b64 v[80:81], 12, v[32:33]
	v_lshl_add_u64 v[32:33], v[156:157], 0, v[80:81]
	global_load_dwordx4 v[36:39], v[32:33], off
	global_load_dwordx4 v[40:43], v[32:33], off offset:64
	global_load_dwordx4 v[44:47], v[32:33], off offset:128
	global_load_dwordx4 v[48:51], v[32:33], off offset:192
	v_add_u32_e32 v32, 0xb0, v158
	v_ashrrev_i32_e32 v33, 31, v32
	v_lshlrev_b64 v[82:83], 12, v[32:33]
	v_lshl_add_u64 v[32:33], v[156:157], 0, v[82:83]
	global_load_dwordx4 v[52:55], v[32:33], off
	global_load_dwordx4 v[56:59], v[32:33], off offset:64
	global_load_dwordx4 v[60:63], v[32:33], off offset:128
	s_nop 0
	global_load_dwordx4 v[32:35], v[32:33], off offset:192
	v_lshl_add_u64 v[80:81], s[38:39], 0, v[80:81]
	v_lshl_add_u64 v[80:81], v[80:81], 0, v[154:155]
	s_waitcnt vmcnt(0)
	v_pk_fma_f32 v[30:31], v[30:31], v[78:79], v[38:39]
	v_pk_fma_f32 v[28:29], v[28:29], v[76:77], v[36:37]
	v_pk_fma_f32 v[26:27], v[26:27], v[74:75], v[42:43]
	v_pk_fma_f32 v[18:19], v[18:19], v[66:67], v[50:51]
	v_pk_fma_f32 v[16:17], v[16:17], v[64:65], v[48:49]
	v_pk_add_f32 v[18:19], v[18:19], 0 op_sel_hi:[1,0]
	v_pk_add_f32 v[16:17], v[16:17], 0 op_sel_hi:[1,0]
	v_pk_fma_f32 v[24:25], v[24:25], v[72:73], v[40:41]
	v_pk_fma_f32 v[22:23], v[22:23], v[70:71], v[46:47]
	v_pk_fma_f32 v[20:21], v[20:21], v[68:69], v[44:45]
	global_store_dwordx4 v[80:81], v[16:19], off offset:192 sc1
	v_pk_fma_f32 v[14:15], v[14:15], v[78:79], v[54:55]
	v_pk_fma_f32 v[12:13], v[12:13], v[76:77], v[52:53]
	v_lshl_add_u64 v[16:17], s[38:39], 0, v[82:83]
	v_pk_fma_f32 v[10:11], v[10:11], v[74:75], v[58:59]
	v_pk_fma_f32 v[8:9], v[8:9], v[72:73], v[56:57]
	v_pk_fma_f32 v[6:7], v[6:7], v[70:71], v[62:63]
	v_pk_fma_f32 v[4:5], v[4:5], v[68:69], v[60:61]
	v_pk_fma_f32 v[2:3], v[2:3], v[66:67], v[34:35]
	v_pk_fma_f32 v[0:1], v[0:1], v[64:65], v[32:33]
	v_pk_add_f32 v[30:31], v[30:31], 0 op_sel_hi:[1,0]
	v_pk_add_f32 v[28:29], v[28:29], 0 op_sel_hi:[1,0]
	v_pk_add_f32 v[26:27], v[26:27], 0 op_sel_hi:[1,0]
	v_pk_add_f32 v[24:25], v[24:25], 0 op_sel_hi:[1,0]
	v_pk_add_f32 v[22:23], v[22:23], 0 op_sel_hi:[1,0]
	v_pk_add_f32 v[20:21], v[20:21], 0 op_sel_hi:[1,0]
	v_lshl_add_u64 v[16:17], v[16:17], 0, v[154:155]
	v_pk_add_f32 v[14:15], v[14:15], 0 op_sel_hi:[1,0]
	v_pk_add_f32 v[12:13], v[12:13], 0 op_sel_hi:[1,0]
	v_pk_add_f32 v[10:11], v[10:11], 0 op_sel_hi:[1,0]
	v_pk_add_f32 v[8:9], v[8:9], 0 op_sel_hi:[1,0]
	v_pk_add_f32 v[6:7], v[6:7], 0 op_sel_hi:[1,0]
	v_pk_add_f32 v[4:5], v[4:5], 0 op_sel_hi:[1,0]
	v_pk_add_f32 v[2:3], v[2:3], 0 op_sel_hi:[1,0]
	v_pk_add_f32 v[0:1], v[0:1], 0 op_sel_hi:[1,0]
	global_store_dwordx4 v[80:81], v[28:31], off sc1
	global_store_dwordx4 v[80:81], v[24:27], off offset:64 sc1
	global_store_dwordx4 v[80:81], v[20:23], off offset:128 sc1
	global_store_dwordx4 v[16:17], v[12:15], off sc1
	global_store_dwordx4 v[16:17], v[8:11], off offset:64 sc1
	global_store_dwordx4 v[16:17], v[4:7], off offset:128 sc1
	global_store_dwordx4 v[16:17], v[0:3], off offset:192 sc1
	s_cbranch_vccnz .LBB0_1603
	s_andn2_b64 vcc, exec, s[10:11]
	s_cbranch_vccnz .LBB0_1602
	s_barrier
	s_branch .LBB0_1602
